# weight-conversion loops: both 16-load halves of an item in flight before the first wait (prologue de-serialisation of cvt_job, 17 loops) - on top of v63
# speedup vs baseline: 1.0102x; 1.0072x over previous
.LBB0_62:
	s_lshl_b32 s23, s10, 1
	s_lshl_b32 s26, s7, 1
	s_mov_b32 s98, s23
	s_mov_b32 s99, s26
	v_add_u32_e32 v52, s23, v30
	v_add_u32_e32 v50, s26, v1
	v_add_u32_e32 v54, s26, v19
	v_add_u32_e32 v56, s23, v32
	v_add_u32_e32 v58, s26, v21
	v_add_u32_e32 v60, s23, v34
	v_add_u32_e32 v62, s26, v23
	v_add_u32_e32 v64, s23, v36
	v_add_u32_e32 v66, s26, v31
	v_add_u32_e32 v68, s23, v38
	v_add_u32_e32 v70, s26, v33
	v_add_u32_e32 v72, s23, v40
	v_add_u32_e32 v74, s26, v35
	v_add_u32_e32 v76, s23, v42
	v_add_u32_e32 v78, s26, v37
	v_add_u32_e32 v80, s23, v44
	v_ashrrev_i32_e32 v53, 31, v52
	v_ashrrev_i32_e32 v51, 31, v50
	v_ashrrev_i32_e32 v57, 31, v56
	v_ashrrev_i32_e32 v55, 31, v54
	v_ashrrev_i32_e32 v61, 31, v60
	v_ashrrev_i32_e32 v59, 31, v58
	v_ashrrev_i32_e32 v65, 31, v64
	v_ashrrev_i32_e32 v63, 31, v62
	v_ashrrev_i32_e32 v69, 31, v68
	v_ashrrev_i32_e32 v67, 31, v66
	v_ashrrev_i32_e32 v73, 31, v72
	v_ashrrev_i32_e32 v71, 31, v70
	v_ashrrev_i32_e32 v77, 31, v76
	v_ashrrev_i32_e32 v75, 31, v74
	v_ashrrev_i32_e32 v81, 31, v80
	v_ashrrev_i32_e32 v79, 31, v78
	v_lshlrev_b64 v[52:53], 13, v[52:53]
	v_lshlrev_b64 v[50:51], 13, v[50:51]
	v_lshlrev_b64 v[54:55], 13, v[54:55]
	v_lshlrev_b64 v[56:57], 13, v[56:57]
	v_lshlrev_b64 v[58:59], 13, v[58:59]
	v_lshlrev_b64 v[60:61], 13, v[60:61]
	v_lshlrev_b64 v[62:63], 13, v[62:63]
	v_lshlrev_b64 v[64:65], 13, v[64:65]
	v_lshlrev_b64 v[66:67], 13, v[66:67]
	v_lshlrev_b64 v[68:69], 13, v[68:69]
	v_lshlrev_b64 v[70:71], 13, v[70:71]
	v_lshlrev_b64 v[72:73], 13, v[72:73]
	v_lshlrev_b64 v[74:75], 13, v[74:75]
	v_lshlrev_b64 v[76:77], 13, v[76:77]
	v_lshlrev_b64 v[78:79], 13, v[78:79]
	v_lshlrev_b64 v[80:81], 13, v[80:81]
	v_lshl_add_u64 v[52:53], v[28:29], 0, v[52:53]
	v_lshl_add_u64 v[50:51], v[28:29], 0, v[50:51]
	v_lshl_add_u64 v[56:57], v[28:29], 0, v[56:57]
	v_lshl_add_u64 v[54:55], v[28:29], 0, v[54:55]
	v_lshl_add_u64 v[60:61], v[28:29], 0, v[60:61]
	v_lshl_add_u64 v[58:59], v[28:29], 0, v[58:59]
	v_lshl_add_u64 v[64:65], v[28:29], 0, v[64:65]
	v_lshl_add_u64 v[62:63], v[28:29], 0, v[62:63]
	v_lshl_add_u64 v[68:69], v[28:29], 0, v[68:69]
	v_lshl_add_u64 v[66:67], v[28:29], 0, v[66:67]
	v_lshl_add_u64 v[72:73], v[28:29], 0, v[72:73]
	v_lshl_add_u64 v[70:71], v[28:29], 0, v[70:71]
	v_lshl_add_u64 v[76:77], v[28:29], 0, v[76:77]
	v_lshl_add_u64 v[74:75], v[28:29], 0, v[74:75]
	v_lshl_add_u64 v[80:81], v[28:29], 0, v[80:81]
	v_lshl_add_u64 v[78:79], v[28:29], 0, v[78:79]
	global_load_dword v188, v[52:53], off
	global_load_dword v189, v[50:51], off
	global_load_dword v190, v[56:57], off
	global_load_dword v191, v[54:55], off
	global_load_dword v192, v[60:61], off
	global_load_dword v193, v[58:59], off
	global_load_dword v194, v[64:65], off
	global_load_dword v195, v[62:63], off
	global_load_dword v196, v[68:69], off
	global_load_dword v197, v[66:67], off
	global_load_dword v198, v[72:73], off
	global_load_dword v199, v[70:71], off
	global_load_dword v200, v[76:77], off
	global_load_dword v201, v[74:75], off
	global_load_dword v202, v[80:81], off
	global_load_dword v203, v[78:79], off
	s_add_i32 s10, s10, 16
	s_add_i32 s7, s7, 16
	s_lshl_b32 s23, s10, 1
	s_lshl_b32 s26, s7, 1
	v_add_u32_e32 v52, s23, v30
	v_add_u32_e32 v50, s26, v1
	v_add_u32_e32 v54, s26, v19
	v_add_u32_e32 v56, s23, v32
	v_add_u32_e32 v58, s26, v21
	v_add_u32_e32 v60, s23, v34
	v_add_u32_e32 v62, s26, v23
	v_add_u32_e32 v64, s23, v36
	v_add_u32_e32 v66, s26, v31
	v_add_u32_e32 v68, s23, v38
	v_add_u32_e32 v70, s26, v33
	v_add_u32_e32 v72, s23, v40
	v_add_u32_e32 v74, s26, v35
	v_add_u32_e32 v76, s23, v42
	v_add_u32_e32 v78, s26, v37
	v_add_u32_e32 v80, s23, v44
	v_ashrrev_i32_e32 v53, 31, v52
	v_ashrrev_i32_e32 v51, 31, v50
	v_ashrrev_i32_e32 v57, 31, v56
	v_ashrrev_i32_e32 v55, 31, v54
	v_ashrrev_i32_e32 v61, 31, v60
	v_ashrrev_i32_e32 v59, 31, v58
	v_ashrrev_i32_e32 v65, 31, v64
	v_ashrrev_i32_e32 v63, 31, v62
	v_ashrrev_i32_e32 v69, 31, v68
	v_ashrrev_i32_e32 v67, 31, v66
	v_ashrrev_i32_e32 v73, 31, v72
	v_ashrrev_i32_e32 v71, 31, v70
	v_ashrrev_i32_e32 v77, 31, v76
	v_ashrrev_i32_e32 v75, 31, v74
	v_ashrrev_i32_e32 v81, 31, v80
	v_ashrrev_i32_e32 v79, 31, v78
	v_lshlrev_b64 v[52:53], 13, v[52:53]
	v_lshlrev_b64 v[50:51], 13, v[50:51]
	v_lshlrev_b64 v[54:55], 13, v[54:55]
	v_lshlrev_b64 v[56:57], 13, v[56:57]
	v_lshlrev_b64 v[58:59], 13, v[58:59]
	v_lshlrev_b64 v[60:61], 13, v[60:61]
	v_lshlrev_b64 v[62:63], 13, v[62:63]
	v_lshlrev_b64 v[64:65], 13, v[64:65]
	v_lshlrev_b64 v[66:67], 13, v[66:67]
	v_lshlrev_b64 v[68:69], 13, v[68:69]
	v_lshlrev_b64 v[70:71], 13, v[70:71]
	v_lshlrev_b64 v[72:73], 13, v[72:73]
	v_lshlrev_b64 v[74:75], 13, v[74:75]
	v_lshlrev_b64 v[76:77], 13, v[76:77]
	v_lshlrev_b64 v[78:79], 13, v[78:79]
	v_lshlrev_b64 v[80:81], 13, v[80:81]
	v_lshl_add_u64 v[52:53], v[28:29], 0, v[52:53]
	v_lshl_add_u64 v[50:51], v[28:29], 0, v[50:51]
	v_lshl_add_u64 v[56:57], v[28:29], 0, v[56:57]
	v_lshl_add_u64 v[54:55], v[28:29], 0, v[54:55]
	v_lshl_add_u64 v[60:61], v[28:29], 0, v[60:61]
	v_lshl_add_u64 v[58:59], v[28:29], 0, v[58:59]
	v_lshl_add_u64 v[64:65], v[28:29], 0, v[64:65]
	v_lshl_add_u64 v[62:63], v[28:29], 0, v[62:63]
	v_lshl_add_u64 v[68:69], v[28:29], 0, v[68:69]
	v_lshl_add_u64 v[66:67], v[28:29], 0, v[66:67]
	v_lshl_add_u64 v[72:73], v[28:29], 0, v[72:73]
	v_lshl_add_u64 v[70:71], v[28:29], 0, v[70:71]
	v_lshl_add_u64 v[76:77], v[28:29], 0, v[76:77]
	v_lshl_add_u64 v[74:75], v[28:29], 0, v[74:75]
	v_lshl_add_u64 v[80:81], v[28:29], 0, v[80:81]
	v_lshl_add_u64 v[78:79], v[28:29], 0, v[78:79]
	global_load_dword v204, v[52:53], off
	global_load_dword v205, v[50:51], off
	global_load_dword v206, v[56:57], off
	global_load_dword v207, v[54:55], off
	global_load_dword v208, v[60:61], off
	global_load_dword v209, v[58:59], off
	global_load_dword v210, v[64:65], off
	global_load_dword v211, v[62:63], off
	global_load_dword v212, v[68:69], off
	global_load_dword v213, v[66:67], off
	global_load_dword v214, v[72:73], off
	global_load_dword v215, v[70:71], off
	global_load_dword v216, v[76:77], off
	global_load_dword v217, v[74:75], off
	global_load_dword v218, v[80:81], off
	global_load_dword v219, v[78:79], off
	s_mov_b32 s23, s98
	s_mov_b32 s26, s99
	v_add_u32_e32 v50, s23, v2
	v_add_u32_e32 v52, s26, v3
	v_add_u32_e32 v56, s26, v5
	v_add_u32_e32 v54, s23, v6
	v_add_u32_e32 v60, s26, v7
	v_add_u32_e32 v58, s23, v8
	v_add_u32_e32 v64, s26, v9
	v_add_u32_e32 v62, s23, v10
	v_add_u32_e32 v68, s26, v11
	v_add_u32_e32 v66, s23, v12
	v_add_u32_e32 v72, s26, v13
	v_add_u32_e32 v70, s23, v14
	v_add_u32_e32 v76, s26, v15
	v_add_u32_e32 v74, s23, v16
	v_add_u32_e32 v80, s26, v17
	v_add_u32_e32 v78, s23, v18
	v_mad_u64_u32 v[50:51], s[26:27], v50, s95, v[4:5]
	v_mad_u64_u32 v[52:53], s[26:27], v52, s95, v[4:5]
	v_mad_u64_u32 v[54:55], s[26:27], v54, s95, v[4:5]
	v_mad_u64_u32 v[56:57], s[26:27], v56, s95, v[4:5]
	v_mad_u64_u32 v[58:59], s[26:27], v58, s95, v[4:5]
	v_mad_u64_u32 v[60:61], s[26:27], v60, s95, v[4:5]
	v_mad_u64_u32 v[62:63], s[26:27], v62, s95, v[4:5]
	v_mad_u64_u32 v[64:65], s[26:27], v64, s95, v[4:5]
	v_mad_u64_u32 v[66:67], s[26:27], v66, s95, v[4:5]
	v_mad_u64_u32 v[68:69], s[26:27], v68, s95, v[4:5]
	v_mad_u64_u32 v[70:71], s[26:27], v70, s95, v[4:5]
	v_mad_u64_u32 v[72:73], s[26:27], v72, s95, v[4:5]
	v_mad_u64_u32 v[74:75], s[26:27], v74, s95, v[4:5]
	v_mad_u64_u32 v[76:77], s[26:27], v76, s95, v[4:5]
	v_mad_u64_u32 v[78:79], s[26:27], v78, s95, v[4:5]
	v_mad_u64_u32 v[80:81], s[26:27], v80, s95, v[4:5]
	s_waitcnt vmcnt(31)
	ds_write_b32 v50, v188
	s_waitcnt vmcnt(30)
	ds_write_b32 v52, v189
	s_waitcnt vmcnt(29)
	ds_write_b32 v54, v190
	s_waitcnt vmcnt(28)
	ds_write_b32 v56, v191
	s_waitcnt vmcnt(27)
	ds_write_b32 v58, v192
	s_waitcnt vmcnt(26)
	ds_write_b32 v60, v193
	s_waitcnt vmcnt(25)
	ds_write_b32 v62, v194
	s_waitcnt vmcnt(24)
	ds_write_b32 v64, v195
	s_waitcnt vmcnt(23)
	ds_write_b32 v66, v196
	s_waitcnt vmcnt(22)
	ds_write_b32 v68, v197
	s_waitcnt vmcnt(21)
	ds_write_b32 v70, v198
	s_waitcnt vmcnt(20)
	ds_write_b32 v72, v199
	s_waitcnt vmcnt(19)
	ds_write_b32 v74, v200
	s_waitcnt vmcnt(18)
	ds_write_b32 v76, v201
	s_waitcnt vmcnt(17)
	ds_write_b32 v78, v202
	s_waitcnt vmcnt(16)
	ds_write_b32 v80, v203
	s_lshl_b32 s23, s10, 1
	s_lshl_b32 s26, s7, 1
	v_add_u32_e32 v50, s23, v2
	v_add_u32_e32 v52, s26, v3
	v_add_u32_e32 v56, s26, v5
	v_add_u32_e32 v54, s23, v6
	v_add_u32_e32 v60, s26, v7
	v_add_u32_e32 v58, s23, v8
	v_add_u32_e32 v64, s26, v9
	v_add_u32_e32 v62, s23, v10
	v_add_u32_e32 v68, s26, v11
	v_add_u32_e32 v66, s23, v12
	v_add_u32_e32 v72, s26, v13
	v_add_u32_e32 v70, s23, v14
	v_add_u32_e32 v76, s26, v15
	v_add_u32_e32 v74, s23, v16
	v_add_u32_e32 v80, s26, v17
	v_add_u32_e32 v78, s23, v18
	v_mad_u64_u32 v[50:51], s[26:27], v50, s95, v[4:5]
	v_mad_u64_u32 v[52:53], s[26:27], v52, s95, v[4:5]
	v_mad_u64_u32 v[54:55], s[26:27], v54, s95, v[4:5]
	v_mad_u64_u32 v[56:57], s[26:27], v56, s95, v[4:5]
	v_mad_u64_u32 v[58:59], s[26:27], v58, s95, v[4:5]
	v_mad_u64_u32 v[60:61], s[26:27], v60, s95, v[4:5]
	v_mad_u64_u32 v[62:63], s[26:27], v62, s95, v[4:5]
	v_mad_u64_u32 v[64:65], s[26:27], v64, s95, v[4:5]
	v_mad_u64_u32 v[66:67], s[26:27], v66, s95, v[4:5]
	v_mad_u64_u32 v[68:69], s[26:27], v68, s95, v[4:5]
	v_mad_u64_u32 v[70:71], s[26:27], v70, s95, v[4:5]
	v_mad_u64_u32 v[72:73], s[26:27], v72, s95, v[4:5]
	v_mad_u64_u32 v[74:75], s[26:27], v74, s95, v[4:5]
	v_mad_u64_u32 v[76:77], s[26:27], v76, s95, v[4:5]
	v_mad_u64_u32 v[78:79], s[26:27], v78, s95, v[4:5]
	v_mad_u64_u32 v[80:81], s[26:27], v80, s95, v[4:5]
	s_waitcnt vmcnt(15)
	ds_write_b32 v50, v204
	s_waitcnt vmcnt(14)
	ds_write_b32 v52, v205
	s_waitcnt vmcnt(13)
	ds_write_b32 v54, v206
	s_waitcnt vmcnt(12)
	ds_write_b32 v56, v207
	s_waitcnt vmcnt(11)
	ds_write_b32 v58, v208
	s_waitcnt vmcnt(10)
	ds_write_b32 v60, v209
	s_waitcnt vmcnt(9)
	ds_write_b32 v62, v210
	s_waitcnt vmcnt(8)
	ds_write_b32 v64, v211
	s_waitcnt vmcnt(7)
	ds_write_b32 v66, v212
	s_waitcnt vmcnt(6)
	ds_write_b32 v68, v213
	s_waitcnt vmcnt(5)
	ds_write_b32 v70, v214
	s_waitcnt vmcnt(4)
	ds_write_b32 v72, v215
	s_waitcnt vmcnt(3)
	ds_write_b32 v74, v216
	s_waitcnt vmcnt(2)
	ds_write_b32 v76, v217
	s_waitcnt vmcnt(1)
	ds_write_b32 v78, v218
	s_waitcnt vmcnt(0)
	ds_write_b32 v80, v219
	s_add_i32 s10, s10, 16
	s_add_i32 s7, s7, 16
	s_add_i32 s13, s13, -16
	s_add_i32 s13, s13, -16
	s_cmp_lg_u32 s13, 0
	s_waitcnt lgkmcnt(0)
	ds_read2_b32 v[32:33], v43 offset0:33 offset1:41
	ds_read2_b32 v[34:35], v43 offset1:8
	ds_read2_b32 v[36:37], v43 offset0:66 offset1:74
	ds_read2_b32 v[50:51], v43 offset0:99 offset1:107
	ds_read2_b32 v[52:53], v43 offset0:132 offset1:140
	ds_read2_b32 v[54:55], v43 offset0:165 offset1:173
	ds_read2_b32 v[56:57], v43 offset0:198 offset1:206
	ds_read2_b32 v[58:59], v43 offset0:231 offset1:239
	s_add_i32 s7, s22, s2
	v_add_u32_e32 v62, s7, v41
	s_ashr_i32 s13, s12, 31
	v_ashrrev_i32_e32 v63, 31, v62
	v_lshl_add_u64 v[60:61], s[12:13], 1, v[24:25]
	v_lshlrev_b64 v[62:63], 12, v[62:63]
	s_waitcnt lgkmcnt(6)
	v_cvt_pk_bf16_f32 v28, v34, v32
	s_waitcnt lgkmcnt(4)
	v_cvt_pk_bf16_f32 v29, v36, v50
	s_waitcnt lgkmcnt(2)
	v_cvt_pk_bf16_f32 v30, v52, v54
	s_waitcnt lgkmcnt(0)
	v_cvt_pk_bf16_f32 v31, v56, v58
	v_lshl_add_u64 v[62:63], v[60:61], 0, v[62:63]
	v_add_u32_e32 v32, s7, v45
	global_store_dwordx4 v[62:63], v[28:31], off
	s_add_i32 s3, s3, s81
	s_cmpk_lt_i32 s3, 0x800
	v_cvt_pk_bf16_f32 v28, v35, v33
	v_ashrrev_i32_e32 v33, 31, v32
	v_cvt_pk_bf16_f32 v29, v37, v51
	v_cvt_pk_bf16_f32 v30, v53, v55
	v_cvt_pk_bf16_f32 v31, v57, v59
	v_lshlrev_b64 v[32:33], 12, v[32:33]
	ds_read2_b32 v[34:35], v43 offset0:49 offset1:57
	ds_read2_b32 v[36:37], v43 offset0:16 offset1:24
	ds_read2_b32 v[50:51], v43 offset0:82 offset1:90
	ds_read2_b32 v[52:53], v43 offset0:115 offset1:123
	ds_read2_b32 v[54:55], v43 offset0:148 offset1:156
	ds_read2_b32 v[56:57], v43 offset0:181 offset1:189
	ds_read2_b32 v[58:59], v43 offset0:214 offset1:222
	ds_read2_b32 v[62:63], v43 offset0:247 offset1:255
	v_lshl_add_u64 v[32:33], v[60:61], 0, v[32:33]
	global_store_dwordx4 v[32:33], v[28:31], off
	v_add_u32_e32 v32, s7, v46
	v_ashrrev_i32_e32 v33, 31, v32
	v_lshlrev_b64 v[32:33], 12, v[32:33]
	s_waitcnt lgkmcnt(6)
	v_cvt_pk_bf16_f32 v28, v36, v34
	s_waitcnt lgkmcnt(4)
	v_cvt_pk_bf16_f32 v29, v50, v52
	s_waitcnt lgkmcnt(2)
	v_cvt_pk_bf16_f32 v30, v54, v56
	s_waitcnt lgkmcnt(0)
	v_cvt_pk_bf16_f32 v31, v58, v62
	v_lshl_add_u64 v[32:33], v[60:61], 0, v[32:33]
	global_store_dwordx4 v[32:33], v[28:31], off
	v_add_u32_e32 v32, s7, v47
	v_ashrrev_i32_e32 v33, 31, v32
	v_lshlrev_b64 v[32:33], 12, v[32:33]
	v_cvt_pk_bf16_f32 v28, v37, v35
	v_cvt_pk_bf16_f32 v29, v51, v53
	v_cvt_pk_bf16_f32 v30, v55, v57
	v_cvt_pk_bf16_f32 v31, v59, v63
	v_lshl_add_u64 v[32:33], v[60:61], 0, v[32:33]
	global_store_dwordx4 v[32:33], v[28:31], off
	s_waitcnt lgkmcnt(0)
	s_cbranch_scc1 .LBB0_61
	s_branch .LBB0_58

.LBB0_67:
	s_lshl_b32 s10, s3, 1
	s_lshl_b32 s13, s2, 1
	s_mov_b32 s98, s10
	s_mov_b32 s99, s13
	v_add_u32_e32 v48, s10, v30
	v_add_u32_e32 v50, s13, v1
	v_add_u32_e32 v54, s13, v19
	v_add_u32_e32 v52, s10, v32
	v_add_u32_e32 v58, s13, v21
	v_add_u32_e32 v56, s10, v34
	v_add_u32_e32 v62, s13, v23
	v_add_u32_e32 v60, s10, v36
	v_add_u32_e32 v66, s13, v31
	v_add_u32_e32 v64, s10, v38
	v_add_u32_e32 v70, s13, v33
	v_add_u32_e32 v68, s10, v40
	v_add_u32_e32 v74, s13, v35
	v_add_u32_e32 v72, s10, v42
	v_add_u32_e32 v78, s13, v37
	v_add_u32_e32 v76, s10, v44
	v_mad_i64_i32 v[48:49], s[26:27], v48, s4, v[28:29]
	v_mad_i64_i32 v[50:51], s[26:27], v50, s4, v[28:29]
	v_mad_i64_i32 v[52:53], s[26:27], v52, s4, v[28:29]
	v_mad_i64_i32 v[54:55], s[26:27], v54, s4, v[28:29]
	v_mad_i64_i32 v[56:57], s[26:27], v56, s4, v[28:29]
	v_mad_i64_i32 v[58:59], s[26:27], v58, s4, v[28:29]
	v_mad_i64_i32 v[60:61], s[26:27], v60, s4, v[28:29]
	v_mad_i64_i32 v[62:63], s[26:27], v62, s4, v[28:29]
	v_mad_i64_i32 v[64:65], s[26:27], v64, s4, v[28:29]
	v_mad_i64_i32 v[66:67], s[26:27], v66, s4, v[28:29]
	v_mad_i64_i32 v[68:69], s[26:27], v68, s4, v[28:29]
	v_mad_i64_i32 v[70:71], s[26:27], v70, s4, v[28:29]
	v_mad_i64_i32 v[72:73], s[26:27], v72, s4, v[28:29]
	v_mad_i64_i32 v[74:75], s[26:27], v74, s4, v[28:29]
	v_mad_i64_i32 v[76:77], s[26:27], v76, s4, v[28:29]
	v_mad_i64_i32 v[78:79], s[26:27], v78, s4, v[28:29]
	global_load_dword v188, v[48:49], off
	global_load_dword v189, v[50:51], off
	global_load_dword v190, v[52:53], off
	global_load_dword v191, v[54:55], off
	global_load_dword v192, v[56:57], off
	global_load_dword v193, v[58:59], off
	global_load_dword v194, v[60:61], off
	global_load_dword v195, v[62:63], off
	global_load_dword v196, v[64:65], off
	global_load_dword v197, v[66:67], off
	global_load_dword v198, v[68:69], off
	global_load_dword v199, v[70:71], off
	global_load_dword v200, v[72:73], off
	global_load_dword v201, v[74:75], off
	global_load_dword v202, v[76:77], off
	global_load_dword v203, v[78:79], off
	s_add_i32 s3, s3, 16
	s_add_i32 s2, s2, 16
	s_lshl_b32 s10, s3, 1
	s_lshl_b32 s13, s2, 1
	v_add_u32_e32 v48, s10, v30
	v_add_u32_e32 v50, s13, v1
	v_add_u32_e32 v54, s13, v19
	v_add_u32_e32 v52, s10, v32
	v_add_u32_e32 v58, s13, v21
	v_add_u32_e32 v56, s10, v34
	v_add_u32_e32 v62, s13, v23
	v_add_u32_e32 v60, s10, v36
	v_add_u32_e32 v66, s13, v31
	v_add_u32_e32 v64, s10, v38
	v_add_u32_e32 v70, s13, v33
	v_add_u32_e32 v68, s10, v40
	v_add_u32_e32 v74, s13, v35
	v_add_u32_e32 v72, s10, v42
	v_add_u32_e32 v78, s13, v37
	v_add_u32_e32 v76, s10, v44
	v_mad_i64_i32 v[48:49], s[26:27], v48, s4, v[28:29]
	v_mad_i64_i32 v[50:51], s[26:27], v50, s4, v[28:29]
	v_mad_i64_i32 v[52:53], s[26:27], v52, s4, v[28:29]
	v_mad_i64_i32 v[54:55], s[26:27], v54, s4, v[28:29]
	v_mad_i64_i32 v[56:57], s[26:27], v56, s4, v[28:29]
	v_mad_i64_i32 v[58:59], s[26:27], v58, s4, v[28:29]
	v_mad_i64_i32 v[60:61], s[26:27], v60, s4, v[28:29]
	v_mad_i64_i32 v[62:63], s[26:27], v62, s4, v[28:29]
	v_mad_i64_i32 v[64:65], s[26:27], v64, s4, v[28:29]
	v_mad_i64_i32 v[66:67], s[26:27], v66, s4, v[28:29]
	v_mad_i64_i32 v[68:69], s[26:27], v68, s4, v[28:29]
	v_mad_i64_i32 v[70:71], s[26:27], v70, s4, v[28:29]
	v_mad_i64_i32 v[72:73], s[26:27], v72, s4, v[28:29]
	v_mad_i64_i32 v[74:75], s[26:27], v74, s4, v[28:29]
	v_mad_i64_i32 v[76:77], s[26:27], v76, s4, v[28:29]
	v_mad_i64_i32 v[78:79], s[26:27], v78, s4, v[28:29]
	global_load_dword v204, v[48:49], off
	global_load_dword v205, v[50:51], off
	global_load_dword v206, v[52:53], off
	global_load_dword v207, v[54:55], off
	global_load_dword v208, v[56:57], off
	global_load_dword v209, v[58:59], off
	global_load_dword v210, v[60:61], off
	global_load_dword v211, v[62:63], off
	global_load_dword v212, v[64:65], off
	global_load_dword v213, v[66:67], off
	global_load_dword v214, v[68:69], off
	global_load_dword v215, v[70:71], off
	global_load_dword v216, v[72:73], off
	global_load_dword v217, v[74:75], off
	global_load_dword v218, v[76:77], off
	global_load_dword v219, v[78:79], off
	s_mov_b32 s10, s98
	s_mov_b32 s13, s99
	v_add_u32_e32 v48, s10, v2
	v_add_u32_e32 v50, s13, v3
	v_add_u32_e32 v54, s13, v5
	v_add_u32_e32 v52, s10, v6
	v_add_u32_e32 v58, s13, v7
	v_add_u32_e32 v56, s10, v8
	v_add_u32_e32 v62, s13, v9
	v_add_u32_e32 v60, s10, v10
	v_add_u32_e32 v66, s13, v11
	v_add_u32_e32 v64, s10, v12
	v_add_u32_e32 v70, s13, v13
	v_add_u32_e32 v68, s10, v14
	v_add_u32_e32 v74, s13, v15
	v_add_u32_e32 v72, s10, v16
	v_add_u32_e32 v78, s13, v17
	v_add_u32_e32 v76, s10, v18
	v_mad_u64_u32 v[48:49], s[26:27], v48, s95, v[4:5]
	v_mad_u64_u32 v[50:51], s[26:27], v50, s95, v[4:5]
	v_mad_u64_u32 v[52:53], s[26:27], v52, s95, v[4:5]
	v_mad_u64_u32 v[54:55], s[26:27], v54, s95, v[4:5]
	v_mad_u64_u32 v[56:57], s[26:27], v56, s95, v[4:5]
	v_mad_u64_u32 v[58:59], s[26:27], v58, s95, v[4:5]
	v_mad_u64_u32 v[60:61], s[26:27], v60, s95, v[4:5]
	v_mad_u64_u32 v[62:63], s[26:27], v62, s95, v[4:5]
	v_mad_u64_u32 v[64:65], s[26:27], v64, s95, v[4:5]
	v_mad_u64_u32 v[66:67], s[26:27], v66, s95, v[4:5]
	v_mad_u64_u32 v[68:69], s[26:27], v68, s95, v[4:5]
	v_mad_u64_u32 v[70:71], s[26:27], v70, s95, v[4:5]
	v_mad_u64_u32 v[72:73], s[26:27], v72, s95, v[4:5]
	v_mad_u64_u32 v[74:75], s[26:27], v74, s95, v[4:5]
	v_mad_u64_u32 v[76:77], s[26:27], v76, s95, v[4:5]
	v_mad_u64_u32 v[78:79], s[26:27], v78, s95, v[4:5]
	s_waitcnt vmcnt(31)
	ds_write_b32 v48, v188
	s_waitcnt vmcnt(30)
	ds_write_b32 v50, v189
	s_waitcnt vmcnt(29)
	ds_write_b32 v52, v190
	s_waitcnt vmcnt(28)
	ds_write_b32 v54, v191
	s_waitcnt vmcnt(27)
	ds_write_b32 v56, v192
	s_waitcnt vmcnt(26)
	ds_write_b32 v58, v193
	s_waitcnt vmcnt(25)
	ds_write_b32 v60, v194
	s_waitcnt vmcnt(24)
	ds_write_b32 v62, v195
	s_waitcnt vmcnt(23)
	ds_write_b32 v64, v196
	s_waitcnt vmcnt(22)
	ds_write_b32 v66, v197
	s_waitcnt vmcnt(21)
	ds_write_b32 v68, v198
	s_waitcnt vmcnt(20)
	ds_write_b32 v70, v199
	s_waitcnt vmcnt(19)
	ds_write_b32 v72, v200
	s_waitcnt vmcnt(18)
	ds_write_b32 v74, v201
	s_waitcnt vmcnt(17)
	ds_write_b32 v76, v202
	s_waitcnt vmcnt(16)
	ds_write_b32 v78, v203
	s_lshl_b32 s10, s3, 1
	s_lshl_b32 s13, s2, 1
	v_add_u32_e32 v48, s10, v2
	v_add_u32_e32 v50, s13, v3
	v_add_u32_e32 v54, s13, v5
	v_add_u32_e32 v52, s10, v6
	v_add_u32_e32 v58, s13, v7
	v_add_u32_e32 v56, s10, v8
	v_add_u32_e32 v62, s13, v9
	v_add_u32_e32 v60, s10, v10
	v_add_u32_e32 v66, s13, v11
	v_add_u32_e32 v64, s10, v12
	v_add_u32_e32 v70, s13, v13
	v_add_u32_e32 v68, s10, v14
	v_add_u32_e32 v74, s13, v15
	v_add_u32_e32 v72, s10, v16
	v_add_u32_e32 v78, s13, v17
	v_add_u32_e32 v76, s10, v18
	v_mad_u64_u32 v[48:49], s[26:27], v48, s95, v[4:5]
	v_mad_u64_u32 v[50:51], s[26:27], v50, s95, v[4:5]
	v_mad_u64_u32 v[52:53], s[26:27], v52, s95, v[4:5]
	v_mad_u64_u32 v[54:55], s[26:27], v54, s95, v[4:5]
	v_mad_u64_u32 v[56:57], s[26:27], v56, s95, v[4:5]
	v_mad_u64_u32 v[58:59], s[26:27], v58, s95, v[4:5]
	v_mad_u64_u32 v[60:61], s[26:27], v60, s95, v[4:5]
	v_mad_u64_u32 v[62:63], s[26:27], v62, s95, v[4:5]
	v_mad_u64_u32 v[64:65], s[26:27], v64, s95, v[4:5]
	v_mad_u64_u32 v[66:67], s[26:27], v66, s95, v[4:5]
	v_mad_u64_u32 v[68:69], s[26:27], v68, s95, v[4:5]
	v_mad_u64_u32 v[70:71], s[26:27], v70, s95, v[4:5]
	v_mad_u64_u32 v[72:73], s[26:27], v72, s95, v[4:5]
	v_mad_u64_u32 v[74:75], s[26:27], v74, s95, v[4:5]
	v_mad_u64_u32 v[76:77], s[26:27], v76, s95, v[4:5]
	v_mad_u64_u32 v[78:79], s[26:27], v78, s95, v[4:5]
	s_waitcnt vmcnt(15)
	ds_write_b32 v48, v204
	s_waitcnt vmcnt(14)
	ds_write_b32 v50, v205
	s_waitcnt vmcnt(13)
	ds_write_b32 v52, v206
	s_waitcnt vmcnt(12)
	ds_write_b32 v54, v207
	s_waitcnt vmcnt(11)
	ds_write_b32 v56, v208
	s_waitcnt vmcnt(10)
	ds_write_b32 v58, v209
	s_waitcnt vmcnt(9)
	ds_write_b32 v60, v210
	s_waitcnt vmcnt(8)
	ds_write_b32 v62, v211
	s_waitcnt vmcnt(7)
	ds_write_b32 v64, v212
	s_waitcnt vmcnt(6)
	ds_write_b32 v66, v213
	s_waitcnt vmcnt(5)
	ds_write_b32 v68, v214
	s_waitcnt vmcnt(4)
	ds_write_b32 v70, v215
	s_waitcnt vmcnt(3)
	ds_write_b32 v72, v216
	s_waitcnt vmcnt(2)
	ds_write_b32 v74, v217
	s_waitcnt vmcnt(1)
	ds_write_b32 v76, v218
	s_waitcnt vmcnt(0)
	ds_write_b32 v78, v219
	s_add_i32 s3, s3, 16
	s_add_i32 s2, s2, 16
	s_add_i32 s7, s7, -16
	s_add_i32 s7, s7, -16
	s_cmp_lg_u32 s7, 0
	s_waitcnt lgkmcnt(0)
	ds_read2_b32 v[32:33], v43 offset0:33 offset1:41
	ds_read2_b32 v[34:35], v43 offset1:8
	ds_read2_b32 v[36:37], v43 offset0:66 offset1:74
	ds_read2_b32 v[48:49], v43 offset0:99 offset1:107
	ds_read2_b32 v[50:51], v43 offset0:132 offset1:140
	ds_read2_b32 v[52:53], v43 offset0:165 offset1:173
	ds_read2_b32 v[54:55], v43 offset0:198 offset1:206
	ds_read2_b32 v[56:57], v43 offset0:231 offset1:239
	s_add_i32 s2, s22, 0x1800
	v_add_u32_e32 v60, s2, v41
	s_ashr_i32 s13, s12, 31
	v_ashrrev_i32_e32 v61, 31, v60
	v_lshl_add_u64 v[58:59], s[12:13], 1, v[24:25]
	v_lshlrev_b64 v[60:61], 12, v[60:61]
	s_waitcnt lgkmcnt(6)
	v_cvt_pk_bf16_f32 v28, v34, v32
	s_waitcnt lgkmcnt(4)
	v_cvt_pk_bf16_f32 v29, v36, v48
	s_waitcnt lgkmcnt(2)
	v_cvt_pk_bf16_f32 v30, v50, v52
	s_waitcnt lgkmcnt(0)
	v_cvt_pk_bf16_f32 v31, v54, v56
	v_lshl_add_u64 v[60:61], v[58:59], 0, v[60:61]
	v_add_u32_e32 v32, s2, v45
	global_store_dwordx4 v[60:61], v[28:31], off
	s_add_i32 s0, s0, s81
	s_cmpk_lt_i32 s0, 0x60
	v_cvt_pk_bf16_f32 v28, v35, v33
	v_ashrrev_i32_e32 v33, 31, v32
	v_cvt_pk_bf16_f32 v29, v37, v49
	v_cvt_pk_bf16_f32 v30, v51, v53
	v_cvt_pk_bf16_f32 v31, v55, v57
	v_lshlrev_b64 v[32:33], 12, v[32:33]
	ds_read2_b32 v[34:35], v43 offset0:49 offset1:57
	ds_read2_b32 v[36:37], v43 offset0:16 offset1:24
	ds_read2_b32 v[48:49], v43 offset0:82 offset1:90
	ds_read2_b32 v[50:51], v43 offset0:115 offset1:123
	ds_read2_b32 v[52:53], v43 offset0:148 offset1:156
	ds_read2_b32 v[54:55], v43 offset0:181 offset1:189
	ds_read2_b32 v[56:57], v43 offset0:214 offset1:222
	ds_read2_b32 v[60:61], v43 offset0:247 offset1:255
	v_lshl_add_u64 v[32:33], v[58:59], 0, v[32:33]
	global_store_dwordx4 v[32:33], v[28:31], off
	v_add_u32_e32 v32, s2, v46
	v_ashrrev_i32_e32 v33, 31, v32
	v_lshlrev_b64 v[32:33], 12, v[32:33]
	s_waitcnt lgkmcnt(6)
	v_cvt_pk_bf16_f32 v28, v36, v34
	s_waitcnt lgkmcnt(4)
	v_cvt_pk_bf16_f32 v29, v48, v50
	s_waitcnt lgkmcnt(2)
	v_cvt_pk_bf16_f32 v30, v52, v54
	s_waitcnt lgkmcnt(0)
	v_cvt_pk_bf16_f32 v31, v56, v60
	v_lshl_add_u64 v[32:33], v[58:59], 0, v[32:33]
	global_store_dwordx4 v[32:33], v[28:31], off
	v_add_u32_e32 v32, s2, v47
	v_ashrrev_i32_e32 v33, 31, v32
	v_lshlrev_b64 v[32:33], 12, v[32:33]
	v_cvt_pk_bf16_f32 v28, v37, v35
	v_cvt_pk_bf16_f32 v29, v49, v51
	v_cvt_pk_bf16_f32 v30, v53, v55
	v_cvt_pk_bf16_f32 v31, v57, v61
	v_lshl_add_u64 v[32:33], v[58:59], 0, v[32:33]
	global_store_dwordx4 v[32:33], v[28:31], off
	s_waitcnt lgkmcnt(0)
	s_cbranch_scc1 .LBB0_66

.LBB0_75:
	s_lshl_b32 s9, s3, 1
	s_lshl_b32 s10, s2, 1
	s_mov_b32 s98, s9
	s_mov_b32 s99, s10
	v_add_u32_e32 v48, s9, v30
	v_add_u32_e32 v50, s10, v1
	v_add_u32_e32 v54, s10, v19
	v_add_u32_e32 v52, s9, v32
	v_add_u32_e32 v58, s10, v21
	v_add_u32_e32 v56, s9, v34
	v_add_u32_e32 v62, s10, v23
	v_add_u32_e32 v60, s9, v36
	v_add_u32_e32 v66, s10, v31
	v_add_u32_e32 v64, s9, v38
	v_add_u32_e32 v70, s10, v33
	v_add_u32_e32 v68, s9, v40
	v_add_u32_e32 v74, s10, v35
	v_add_u32_e32 v72, s9, v42
	v_add_u32_e32 v78, s10, v37
	v_add_u32_e32 v76, s9, v44
	v_mad_i64_i32 v[48:49], s[22:23], v48, s4, v[28:29]
	v_mad_i64_i32 v[50:51], s[22:23], v50, s4, v[28:29]
	v_mad_i64_i32 v[52:53], s[22:23], v52, s4, v[28:29]
	v_mad_i64_i32 v[54:55], s[22:23], v54, s4, v[28:29]
	v_mad_i64_i32 v[56:57], s[22:23], v56, s4, v[28:29]
	v_mad_i64_i32 v[58:59], s[22:23], v58, s4, v[28:29]
	v_mad_i64_i32 v[60:61], s[22:23], v60, s4, v[28:29]
	v_mad_i64_i32 v[62:63], s[22:23], v62, s4, v[28:29]
	v_mad_i64_i32 v[64:65], s[22:23], v64, s4, v[28:29]
	v_mad_i64_i32 v[66:67], s[22:23], v66, s4, v[28:29]
	v_mad_i64_i32 v[68:69], s[22:23], v68, s4, v[28:29]
	v_mad_i64_i32 v[70:71], s[22:23], v70, s4, v[28:29]
	v_mad_i64_i32 v[72:73], s[22:23], v72, s4, v[28:29]
	v_mad_i64_i32 v[74:75], s[22:23], v74, s4, v[28:29]
	v_mad_i64_i32 v[76:77], s[22:23], v76, s4, v[28:29]
	v_mad_i64_i32 v[78:79], s[22:23], v78, s4, v[28:29]
	global_load_dword v188, v[48:49], off
	global_load_dword v189, v[50:51], off
	global_load_dword v190, v[52:53], off
	global_load_dword v191, v[54:55], off
	global_load_dword v192, v[56:57], off
	global_load_dword v193, v[58:59], off
	global_load_dword v194, v[60:61], off
	global_load_dword v195, v[62:63], off
	global_load_dword v196, v[64:65], off
	global_load_dword v197, v[66:67], off
	global_load_dword v198, v[68:69], off
	global_load_dword v199, v[70:71], off
	global_load_dword v200, v[72:73], off
	global_load_dword v201, v[74:75], off
	global_load_dword v202, v[76:77], off
	global_load_dword v203, v[78:79], off
	s_add_i32 s3, s3, 16
	s_add_i32 s2, s2, 16
	s_lshl_b32 s9, s3, 1
	s_lshl_b32 s10, s2, 1
	v_add_u32_e32 v48, s9, v30
	v_add_u32_e32 v50, s10, v1
	v_add_u32_e32 v54, s10, v19
	v_add_u32_e32 v52, s9, v32
	v_add_u32_e32 v58, s10, v21
	v_add_u32_e32 v56, s9, v34
	v_add_u32_e32 v62, s10, v23
	v_add_u32_e32 v60, s9, v36
	v_add_u32_e32 v66, s10, v31
	v_add_u32_e32 v64, s9, v38
	v_add_u32_e32 v70, s10, v33
	v_add_u32_e32 v68, s9, v40
	v_add_u32_e32 v74, s10, v35
	v_add_u32_e32 v72, s9, v42
	v_add_u32_e32 v78, s10, v37
	v_add_u32_e32 v76, s9, v44
	v_mad_i64_i32 v[48:49], s[22:23], v48, s4, v[28:29]
	v_mad_i64_i32 v[50:51], s[22:23], v50, s4, v[28:29]
	v_mad_i64_i32 v[52:53], s[22:23], v52, s4, v[28:29]
	v_mad_i64_i32 v[54:55], s[22:23], v54, s4, v[28:29]
	v_mad_i64_i32 v[56:57], s[22:23], v56, s4, v[28:29]
	v_mad_i64_i32 v[58:59], s[22:23], v58, s4, v[28:29]
	v_mad_i64_i32 v[60:61], s[22:23], v60, s4, v[28:29]
	v_mad_i64_i32 v[62:63], s[22:23], v62, s4, v[28:29]
	v_mad_i64_i32 v[64:65], s[22:23], v64, s4, v[28:29]
	v_mad_i64_i32 v[66:67], s[22:23], v66, s4, v[28:29]
	v_mad_i64_i32 v[68:69], s[22:23], v68, s4, v[28:29]
	v_mad_i64_i32 v[70:71], s[22:23], v70, s4, v[28:29]
	v_mad_i64_i32 v[72:73], s[22:23], v72, s4, v[28:29]
	v_mad_i64_i32 v[74:75], s[22:23], v74, s4, v[28:29]
	v_mad_i64_i32 v[76:77], s[22:23], v76, s4, v[28:29]
	v_mad_i64_i32 v[78:79], s[22:23], v78, s4, v[28:29]
	global_load_dword v204, v[48:49], off
	global_load_dword v205, v[50:51], off
	global_load_dword v206, v[52:53], off
	global_load_dword v207, v[54:55], off
	global_load_dword v208, v[56:57], off
	global_load_dword v209, v[58:59], off
	global_load_dword v210, v[60:61], off
	global_load_dword v211, v[62:63], off
	global_load_dword v212, v[64:65], off
	global_load_dword v213, v[66:67], off
	global_load_dword v214, v[68:69], off
	global_load_dword v215, v[70:71], off
	global_load_dword v216, v[72:73], off
	global_load_dword v217, v[74:75], off
	global_load_dword v218, v[76:77], off
	global_load_dword v219, v[78:79], off
	s_mov_b32 s9, s98
	s_mov_b32 s10, s99
	v_add_u32_e32 v48, s9, v2
	v_add_u32_e32 v50, s10, v3
	v_add_u32_e32 v54, s10, v5
	v_add_u32_e32 v52, s9, v6
	v_add_u32_e32 v58, s10, v7
	v_add_u32_e32 v56, s9, v8
	v_add_u32_e32 v62, s10, v9
	v_add_u32_e32 v60, s9, v10
	v_add_u32_e32 v66, s10, v11
	v_add_u32_e32 v64, s9, v12
	v_add_u32_e32 v70, s10, v13
	v_add_u32_e32 v68, s9, v14
	v_add_u32_e32 v74, s10, v15
	v_add_u32_e32 v72, s9, v16
	v_add_u32_e32 v78, s10, v17
	v_add_u32_e32 v76, s9, v18
	v_mad_u64_u32 v[48:49], s[22:23], v48, s95, v[4:5]
	v_mad_u64_u32 v[50:51], s[22:23], v50, s95, v[4:5]
	v_mad_u64_u32 v[52:53], s[22:23], v52, s95, v[4:5]
	v_mad_u64_u32 v[54:55], s[22:23], v54, s95, v[4:5]
	v_mad_u64_u32 v[56:57], s[22:23], v56, s95, v[4:5]
	v_mad_u64_u32 v[58:59], s[22:23], v58, s95, v[4:5]
	v_mad_u64_u32 v[60:61], s[22:23], v60, s95, v[4:5]
	v_mad_u64_u32 v[62:63], s[22:23], v62, s95, v[4:5]
	v_mad_u64_u32 v[64:65], s[22:23], v64, s95, v[4:5]
	v_mad_u64_u32 v[66:67], s[22:23], v66, s95, v[4:5]
	v_mad_u64_u32 v[68:69], s[22:23], v68, s95, v[4:5]
	v_mad_u64_u32 v[70:71], s[22:23], v70, s95, v[4:5]
	v_mad_u64_u32 v[72:73], s[22:23], v72, s95, v[4:5]
	v_mad_u64_u32 v[74:75], s[22:23], v74, s95, v[4:5]
	v_mad_u64_u32 v[76:77], s[22:23], v76, s95, v[4:5]
	v_mad_u64_u32 v[78:79], s[22:23], v78, s95, v[4:5]
	s_waitcnt vmcnt(31)
	ds_write_b32 v48, v188
	s_waitcnt vmcnt(30)
	ds_write_b32 v50, v189
	s_waitcnt vmcnt(29)
	ds_write_b32 v52, v190
	s_waitcnt vmcnt(28)
	ds_write_b32 v54, v191
	s_waitcnt vmcnt(27)
	ds_write_b32 v56, v192
	s_waitcnt vmcnt(26)
	ds_write_b32 v58, v193
	s_waitcnt vmcnt(25)
	ds_write_b32 v60, v194
	s_waitcnt vmcnt(24)
	ds_write_b32 v62, v195
	s_waitcnt vmcnt(23)
	ds_write_b32 v64, v196
	s_waitcnt vmcnt(22)
	ds_write_b32 v66, v197
	s_waitcnt vmcnt(21)
	ds_write_b32 v68, v198
	s_waitcnt vmcnt(20)
	ds_write_b32 v70, v199
	s_waitcnt vmcnt(19)
	ds_write_b32 v72, v200
	s_waitcnt vmcnt(18)
	ds_write_b32 v74, v201
	s_waitcnt vmcnt(17)
	ds_write_b32 v76, v202
	s_waitcnt vmcnt(16)
	ds_write_b32 v78, v203
	s_lshl_b32 s9, s3, 1
	s_lshl_b32 s10, s2, 1
	v_add_u32_e32 v48, s9, v2
	v_add_u32_e32 v50, s10, v3
	v_add_u32_e32 v54, s10, v5
	v_add_u32_e32 v52, s9, v6
	v_add_u32_e32 v58, s10, v7
	v_add_u32_e32 v56, s9, v8
	v_add_u32_e32 v62, s10, v9
	v_add_u32_e32 v60, s9, v10
	v_add_u32_e32 v66, s10, v11
	v_add_u32_e32 v64, s9, v12
	v_add_u32_e32 v70, s10, v13
	v_add_u32_e32 v68, s9, v14
	v_add_u32_e32 v74, s10, v15
	v_add_u32_e32 v72, s9, v16
	v_add_u32_e32 v78, s10, v17
	v_add_u32_e32 v76, s9, v18
	v_mad_u64_u32 v[48:49], s[22:23], v48, s95, v[4:5]
	v_mad_u64_u32 v[50:51], s[22:23], v50, s95, v[4:5]
	v_mad_u64_u32 v[52:53], s[22:23], v52, s95, v[4:5]
	v_mad_u64_u32 v[54:55], s[22:23], v54, s95, v[4:5]
	v_mad_u64_u32 v[56:57], s[22:23], v56, s95, v[4:5]
	v_mad_u64_u32 v[58:59], s[22:23], v58, s95, v[4:5]
	v_mad_u64_u32 v[60:61], s[22:23], v60, s95, v[4:5]
	v_mad_u64_u32 v[62:63], s[22:23], v62, s95, v[4:5]
	v_mad_u64_u32 v[64:65], s[22:23], v64, s95, v[4:5]
	v_mad_u64_u32 v[66:67], s[22:23], v66, s95, v[4:5]
	v_mad_u64_u32 v[68:69], s[22:23], v68, s95, v[4:5]
	v_mad_u64_u32 v[70:71], s[22:23], v70, s95, v[4:5]
	v_mad_u64_u32 v[72:73], s[22:23], v72, s95, v[4:5]
	v_mad_u64_u32 v[74:75], s[22:23], v74, s95, v[4:5]
	v_mad_u64_u32 v[76:77], s[22:23], v76, s95, v[4:5]
	v_mad_u64_u32 v[78:79], s[22:23], v78, s95, v[4:5]
	s_waitcnt vmcnt(15)
	ds_write_b32 v48, v204
	s_waitcnt vmcnt(14)
	ds_write_b32 v50, v205
	s_waitcnt vmcnt(13)
	ds_write_b32 v52, v206
	s_waitcnt vmcnt(12)
	ds_write_b32 v54, v207
	s_waitcnt vmcnt(11)
	ds_write_b32 v56, v208
	s_waitcnt vmcnt(10)
	ds_write_b32 v58, v209
	s_waitcnt vmcnt(9)
	ds_write_b32 v60, v210
	s_waitcnt vmcnt(8)
	ds_write_b32 v62, v211
	s_waitcnt vmcnt(7)
	ds_write_b32 v64, v212
	s_waitcnt vmcnt(6)
	ds_write_b32 v66, v213
	s_waitcnt vmcnt(5)
	ds_write_b32 v68, v214
	s_waitcnt vmcnt(4)
	ds_write_b32 v70, v215
	s_waitcnt vmcnt(3)
	ds_write_b32 v72, v216
	s_waitcnt vmcnt(2)
	ds_write_b32 v74, v217
	s_waitcnt vmcnt(1)
	ds_write_b32 v76, v218
	s_waitcnt vmcnt(0)
	ds_write_b32 v78, v219
	s_add_i32 s3, s3, 16
	s_add_i32 s2, s2, 16
	s_add_i32 s7, s7, -16
	s_add_i32 s7, s7, -16
	s_cmp_lg_u32 s7, 0
	s_waitcnt lgkmcnt(0)
	ds_read2_b32 v[32:33], v43 offset0:33 offset1:41
	ds_read2_b32 v[34:35], v43 offset1:8
	ds_read2_b32 v[36:37], v43 offset0:66 offset1:74
	ds_read2_b32 v[48:49], v43 offset0:99 offset1:107
	ds_read2_b32 v[50:51], v43 offset0:132 offset1:140
	ds_read2_b32 v[52:53], v43 offset0:165 offset1:173
	ds_read2_b32 v[54:55], v43 offset0:198 offset1:206
	ds_read2_b32 v[56:57], v43 offset0:231 offset1:239
	s_add_i32 s2, s12, 0x1900
	v_add_u32_e32 v60, s2, v41
	s_ashr_i32 s9, s8, 31
	v_ashrrev_i32_e32 v61, 31, v60
	v_lshl_add_u64 v[58:59], s[8:9], 1, v[24:25]
	v_lshlrev_b64 v[60:61], 12, v[60:61]
	s_waitcnt lgkmcnt(6)
	v_cvt_pk_bf16_f32 v28, v34, v32
	s_waitcnt lgkmcnt(4)
	v_cvt_pk_bf16_f32 v29, v36, v48
	s_waitcnt lgkmcnt(2)
	v_cvt_pk_bf16_f32 v30, v50, v52
	s_waitcnt lgkmcnt(0)
	v_cvt_pk_bf16_f32 v31, v54, v56
	v_lshl_add_u64 v[60:61], v[58:59], 0, v[60:61]
	v_add_u32_e32 v32, s2, v45
	global_store_dwordx4 v[60:61], v[28:31], off
	s_add_i32 s0, s0, s81
	s_cmpk_lt_i32 s0, 0x60
	v_cvt_pk_bf16_f32 v28, v35, v33
	v_ashrrev_i32_e32 v33, 31, v32
	v_cvt_pk_bf16_f32 v29, v37, v49
	v_cvt_pk_bf16_f32 v30, v51, v53
	v_cvt_pk_bf16_f32 v31, v55, v57
	v_lshlrev_b64 v[32:33], 12, v[32:33]
	ds_read2_b32 v[34:35], v43 offset0:49 offset1:57
	ds_read2_b32 v[36:37], v43 offset0:16 offset1:24
	ds_read2_b32 v[48:49], v43 offset0:82 offset1:90
	ds_read2_b32 v[50:51], v43 offset0:115 offset1:123
	ds_read2_b32 v[52:53], v43 offset0:148 offset1:156
	ds_read2_b32 v[54:55], v43 offset0:181 offset1:189
	ds_read2_b32 v[56:57], v43 offset0:214 offset1:222
	ds_read2_b32 v[60:61], v43 offset0:247 offset1:255
	v_lshl_add_u64 v[32:33], v[58:59], 0, v[32:33]
	global_store_dwordx4 v[32:33], v[28:31], off
	v_add_u32_e32 v32, s2, v46
	v_ashrrev_i32_e32 v33, 31, v32
	v_lshlrev_b64 v[32:33], 12, v[32:33]
	s_waitcnt lgkmcnt(6)
	v_cvt_pk_bf16_f32 v28, v36, v34
	s_waitcnt lgkmcnt(4)
	v_cvt_pk_bf16_f32 v29, v48, v50
	s_waitcnt lgkmcnt(2)
	v_cvt_pk_bf16_f32 v30, v52, v54
	s_waitcnt lgkmcnt(0)
	v_cvt_pk_bf16_f32 v31, v56, v60
	v_lshl_add_u64 v[32:33], v[58:59], 0, v[32:33]
	global_store_dwordx4 v[32:33], v[28:31], off
	v_add_u32_e32 v32, s2, v47
	v_ashrrev_i32_e32 v33, 31, v32
	v_lshlrev_b64 v[32:33], 12, v[32:33]
	v_cvt_pk_bf16_f32 v28, v37, v35
	v_cvt_pk_bf16_f32 v29, v49, v51
	v_cvt_pk_bf16_f32 v30, v53, v55
	v_cvt_pk_bf16_f32 v31, v57, v61
	v_lshl_add_u64 v[32:33], v[58:59], 0, v[32:33]
	global_store_dwordx4 v[32:33], v[28:31], off
	s_waitcnt lgkmcnt(0)
	s_cbranch_scc1 .LBB0_74
	s_movk_i32 s0, 0x5f

.LBB0_84:
	s_lshl_b32 s9, s3, 1
	s_lshl_b32 s10, s2, 1
	s_mov_b32 s98, s9
	s_mov_b32 s99, s10
	v_add_u32_e32 v50, s9, v30
	v_add_u32_e32 v48, s10, v1
	v_add_u32_e32 v52, s10, v19
	v_add_u32_e32 v54, s9, v32
	v_add_u32_e32 v56, s10, v21
	v_add_u32_e32 v58, s9, v34
	v_add_u32_e32 v60, s10, v23
	v_add_u32_e32 v62, s9, v36
	v_add_u32_e32 v64, s10, v31
	v_add_u32_e32 v66, s9, v38
	v_add_u32_e32 v68, s10, v33
	v_add_u32_e32 v70, s9, v40
	v_add_u32_e32 v72, s10, v35
	v_add_u32_e32 v74, s9, v42
	v_add_u32_e32 v76, s10, v37
	v_add_u32_e32 v78, s9, v44
	v_ashrrev_i32_e32 v51, 31, v50
	v_ashrrev_i32_e32 v49, 31, v48
	v_ashrrev_i32_e32 v55, 31, v54
	v_ashrrev_i32_e32 v53, 31, v52
	v_ashrrev_i32_e32 v59, 31, v58
	v_ashrrev_i32_e32 v57, 31, v56
	v_ashrrev_i32_e32 v63, 31, v62
	v_ashrrev_i32_e32 v61, 31, v60
	v_ashrrev_i32_e32 v67, 31, v66
	v_ashrrev_i32_e32 v65, 31, v64
	v_ashrrev_i32_e32 v71, 31, v70
	v_ashrrev_i32_e32 v69, 31, v68
	v_ashrrev_i32_e32 v75, 31, v74
	v_ashrrev_i32_e32 v73, 31, v72
	v_ashrrev_i32_e32 v79, 31, v78
	v_ashrrev_i32_e32 v77, 31, v76
	v_lshlrev_b64 v[50:51], 10, v[50:51]
	v_lshlrev_b64 v[48:49], 10, v[48:49]
	v_lshlrev_b64 v[52:53], 10, v[52:53]
	v_lshlrev_b64 v[54:55], 10, v[54:55]
	v_lshlrev_b64 v[56:57], 10, v[56:57]
	v_lshlrev_b64 v[58:59], 10, v[58:59]
	v_lshlrev_b64 v[60:61], 10, v[60:61]
	v_lshlrev_b64 v[62:63], 10, v[62:63]
	v_lshlrev_b64 v[64:65], 10, v[64:65]
	v_lshlrev_b64 v[66:67], 10, v[66:67]
	v_lshlrev_b64 v[68:69], 10, v[68:69]
	v_lshlrev_b64 v[70:71], 10, v[70:71]
	v_lshlrev_b64 v[72:73], 10, v[72:73]
	v_lshlrev_b64 v[74:75], 10, v[74:75]
	v_lshlrev_b64 v[76:77], 10, v[76:77]
	v_lshlrev_b64 v[78:79], 10, v[78:79]
	v_lshl_add_u64 v[50:51], v[28:29], 0, v[50:51]
	v_lshl_add_u64 v[48:49], v[28:29], 0, v[48:49]
	v_lshl_add_u64 v[54:55], v[28:29], 0, v[54:55]
	v_lshl_add_u64 v[52:53], v[28:29], 0, v[52:53]
	v_lshl_add_u64 v[58:59], v[28:29], 0, v[58:59]
	v_lshl_add_u64 v[56:57], v[28:29], 0, v[56:57]
	v_lshl_add_u64 v[62:63], v[28:29], 0, v[62:63]
	v_lshl_add_u64 v[60:61], v[28:29], 0, v[60:61]
	v_lshl_add_u64 v[66:67], v[28:29], 0, v[66:67]
	v_lshl_add_u64 v[64:65], v[28:29], 0, v[64:65]
	v_lshl_add_u64 v[70:71], v[28:29], 0, v[70:71]
	v_lshl_add_u64 v[68:69], v[28:29], 0, v[68:69]
	v_lshl_add_u64 v[74:75], v[28:29], 0, v[74:75]
	v_lshl_add_u64 v[72:73], v[28:29], 0, v[72:73]
	v_lshl_add_u64 v[78:79], v[28:29], 0, v[78:79]
	v_lshl_add_u64 v[76:77], v[28:29], 0, v[76:77]
	global_load_dword v188, v[50:51], off
	global_load_dword v189, v[48:49], off
	global_load_dword v190, v[54:55], off
	global_load_dword v191, v[52:53], off
	global_load_dword v192, v[58:59], off
	global_load_dword v193, v[56:57], off
	global_load_dword v194, v[62:63], off
	global_load_dword v195, v[60:61], off
	global_load_dword v196, v[66:67], off
	global_load_dword v197, v[64:65], off
	global_load_dword v198, v[70:71], off
	global_load_dword v199, v[68:69], off
	global_load_dword v200, v[74:75], off
	global_load_dword v201, v[72:73], off
	global_load_dword v202, v[78:79], off
	global_load_dword v203, v[76:77], off
	s_add_i32 s3, s3, 16
	s_add_i32 s2, s2, 16
	s_lshl_b32 s9, s3, 1
	s_lshl_b32 s10, s2, 1
	v_add_u32_e32 v50, s9, v30
	v_add_u32_e32 v48, s10, v1
	v_add_u32_e32 v52, s10, v19
	v_add_u32_e32 v54, s9, v32
	v_add_u32_e32 v56, s10, v21
	v_add_u32_e32 v58, s9, v34
	v_add_u32_e32 v60, s10, v23
	v_add_u32_e32 v62, s9, v36
	v_add_u32_e32 v64, s10, v31
	v_add_u32_e32 v66, s9, v38
	v_add_u32_e32 v68, s10, v33
	v_add_u32_e32 v70, s9, v40
	v_add_u32_e32 v72, s10, v35
	v_add_u32_e32 v74, s9, v42
	v_add_u32_e32 v76, s10, v37
	v_add_u32_e32 v78, s9, v44
	v_ashrrev_i32_e32 v51, 31, v50
	v_ashrrev_i32_e32 v49, 31, v48
	v_ashrrev_i32_e32 v55, 31, v54
	v_ashrrev_i32_e32 v53, 31, v52
	v_ashrrev_i32_e32 v59, 31, v58
	v_ashrrev_i32_e32 v57, 31, v56
	v_ashrrev_i32_e32 v63, 31, v62
	v_ashrrev_i32_e32 v61, 31, v60
	v_ashrrev_i32_e32 v67, 31, v66
	v_ashrrev_i32_e32 v65, 31, v64
	v_ashrrev_i32_e32 v71, 31, v70
	v_ashrrev_i32_e32 v69, 31, v68
	v_ashrrev_i32_e32 v75, 31, v74
	v_ashrrev_i32_e32 v73, 31, v72
	v_ashrrev_i32_e32 v79, 31, v78
	v_ashrrev_i32_e32 v77, 31, v76
	v_lshlrev_b64 v[50:51], 10, v[50:51]
	v_lshlrev_b64 v[48:49], 10, v[48:49]
	v_lshlrev_b64 v[52:53], 10, v[52:53]
	v_lshlrev_b64 v[54:55], 10, v[54:55]
	v_lshlrev_b64 v[56:57], 10, v[56:57]
	v_lshlrev_b64 v[58:59], 10, v[58:59]
	v_lshlrev_b64 v[60:61], 10, v[60:61]
	v_lshlrev_b64 v[62:63], 10, v[62:63]
	v_lshlrev_b64 v[64:65], 10, v[64:65]
	v_lshlrev_b64 v[66:67], 10, v[66:67]
	v_lshlrev_b64 v[68:69], 10, v[68:69]
	v_lshlrev_b64 v[70:71], 10, v[70:71]
	v_lshlrev_b64 v[72:73], 10, v[72:73]
	v_lshlrev_b64 v[74:75], 10, v[74:75]
	v_lshlrev_b64 v[76:77], 10, v[76:77]
	v_lshlrev_b64 v[78:79], 10, v[78:79]
	v_lshl_add_u64 v[50:51], v[28:29], 0, v[50:51]
	v_lshl_add_u64 v[48:49], v[28:29], 0, v[48:49]
	v_lshl_add_u64 v[54:55], v[28:29], 0, v[54:55]
	v_lshl_add_u64 v[52:53], v[28:29], 0, v[52:53]
	v_lshl_add_u64 v[58:59], v[28:29], 0, v[58:59]
	v_lshl_add_u64 v[56:57], v[28:29], 0, v[56:57]
	v_lshl_add_u64 v[62:63], v[28:29], 0, v[62:63]
	v_lshl_add_u64 v[60:61], v[28:29], 0, v[60:61]
	v_lshl_add_u64 v[66:67], v[28:29], 0, v[66:67]
	v_lshl_add_u64 v[64:65], v[28:29], 0, v[64:65]
	v_lshl_add_u64 v[70:71], v[28:29], 0, v[70:71]
	v_lshl_add_u64 v[68:69], v[28:29], 0, v[68:69]
	v_lshl_add_u64 v[74:75], v[28:29], 0, v[74:75]
	v_lshl_add_u64 v[72:73], v[28:29], 0, v[72:73]
	v_lshl_add_u64 v[78:79], v[28:29], 0, v[78:79]
	v_lshl_add_u64 v[76:77], v[28:29], 0, v[76:77]
	global_load_dword v204, v[50:51], off
	global_load_dword v205, v[48:49], off
	global_load_dword v206, v[54:55], off
	global_load_dword v207, v[52:53], off
	global_load_dword v208, v[58:59], off
	global_load_dword v209, v[56:57], off
	global_load_dword v210, v[62:63], off
	global_load_dword v211, v[60:61], off
	global_load_dword v212, v[66:67], off
	global_load_dword v213, v[64:65], off
	global_load_dword v214, v[70:71], off
	global_load_dword v215, v[68:69], off
	global_load_dword v216, v[74:75], off
	global_load_dword v217, v[72:73], off
	global_load_dword v218, v[78:79], off
	global_load_dword v219, v[76:77], off
	s_mov_b32 s9, s98
	s_mov_b32 s10, s99
	v_add_u32_e32 v48, s9, v2
	v_add_u32_e32 v50, s10, v3
	v_add_u32_e32 v54, s10, v5
	v_add_u32_e32 v52, s9, v6
	v_add_u32_e32 v58, s10, v7
	v_add_u32_e32 v56, s9, v8
	v_add_u32_e32 v62, s10, v9
	v_add_u32_e32 v60, s9, v10
	v_add_u32_e32 v66, s10, v11
	v_add_u32_e32 v64, s9, v12
	v_add_u32_e32 v70, s10, v13
	v_add_u32_e32 v68, s9, v14
	v_add_u32_e32 v74, s10, v15
	v_add_u32_e32 v72, s9, v16
	v_add_u32_e32 v78, s10, v17
	v_add_u32_e32 v76, s9, v18
	v_mad_u64_u32 v[48:49], s[26:27], v48, s95, v[4:5]
	v_mad_u64_u32 v[50:51], s[26:27], v50, s95, v[4:5]
	v_mad_u64_u32 v[52:53], s[26:27], v52, s95, v[4:5]
	v_mad_u64_u32 v[54:55], s[26:27], v54, s95, v[4:5]
	v_mad_u64_u32 v[56:57], s[26:27], v56, s95, v[4:5]
	v_mad_u64_u32 v[58:59], s[26:27], v58, s95, v[4:5]
	v_mad_u64_u32 v[60:61], s[26:27], v60, s95, v[4:5]
	v_mad_u64_u32 v[62:63], s[26:27], v62, s95, v[4:5]
	v_mad_u64_u32 v[64:65], s[26:27], v64, s95, v[4:5]
	v_mad_u64_u32 v[66:67], s[26:27], v66, s95, v[4:5]
	v_mad_u64_u32 v[68:69], s[26:27], v68, s95, v[4:5]
	v_mad_u64_u32 v[70:71], s[26:27], v70, s95, v[4:5]
	v_mad_u64_u32 v[72:73], s[26:27], v72, s95, v[4:5]
	v_mad_u64_u32 v[74:75], s[26:27], v74, s95, v[4:5]
	v_mad_u64_u32 v[76:77], s[26:27], v76, s95, v[4:5]
	v_mad_u64_u32 v[78:79], s[26:27], v78, s95, v[4:5]
	s_waitcnt vmcnt(31)
	ds_write_b32 v48, v188
	s_waitcnt vmcnt(30)
	ds_write_b32 v50, v189
	s_waitcnt vmcnt(29)
	ds_write_b32 v52, v190
	s_waitcnt vmcnt(28)
	ds_write_b32 v54, v191
	s_waitcnt vmcnt(27)
	ds_write_b32 v56, v192
	s_waitcnt vmcnt(26)
	ds_write_b32 v58, v193
	s_waitcnt vmcnt(25)
	ds_write_b32 v60, v194
	s_waitcnt vmcnt(24)
	ds_write_b32 v62, v195
	s_waitcnt vmcnt(23)
	ds_write_b32 v64, v196
	s_waitcnt vmcnt(22)
	ds_write_b32 v66, v197
	s_waitcnt vmcnt(21)
	ds_write_b32 v68, v198
	s_waitcnt vmcnt(20)
	ds_write_b32 v70, v199
	s_waitcnt vmcnt(19)
	ds_write_b32 v72, v200
	s_waitcnt vmcnt(18)
	ds_write_b32 v74, v201
	s_waitcnt vmcnt(17)
	ds_write_b32 v76, v202
	s_waitcnt vmcnt(16)
	ds_write_b32 v78, v203
	s_lshl_b32 s9, s3, 1
	s_lshl_b32 s10, s2, 1
	v_add_u32_e32 v48, s9, v2
	v_add_u32_e32 v50, s10, v3
	v_add_u32_e32 v54, s10, v5
	v_add_u32_e32 v52, s9, v6
	v_add_u32_e32 v58, s10, v7
	v_add_u32_e32 v56, s9, v8
	v_add_u32_e32 v62, s10, v9
	v_add_u32_e32 v60, s9, v10
	v_add_u32_e32 v66, s10, v11
	v_add_u32_e32 v64, s9, v12
	v_add_u32_e32 v70, s10, v13
	v_add_u32_e32 v68, s9, v14
	v_add_u32_e32 v74, s10, v15
	v_add_u32_e32 v72, s9, v16
	v_add_u32_e32 v78, s10, v17
	v_add_u32_e32 v76, s9, v18
	v_mad_u64_u32 v[48:49], s[26:27], v48, s95, v[4:5]
	v_mad_u64_u32 v[50:51], s[26:27], v50, s95, v[4:5]
	v_mad_u64_u32 v[52:53], s[26:27], v52, s95, v[4:5]
	v_mad_u64_u32 v[54:55], s[26:27], v54, s95, v[4:5]
	v_mad_u64_u32 v[56:57], s[26:27], v56, s95, v[4:5]
	v_mad_u64_u32 v[58:59], s[26:27], v58, s95, v[4:5]
	v_mad_u64_u32 v[60:61], s[26:27], v60, s95, v[4:5]
	v_mad_u64_u32 v[62:63], s[26:27], v62, s95, v[4:5]
	v_mad_u64_u32 v[64:65], s[26:27], v64, s95, v[4:5]
	v_mad_u64_u32 v[66:67], s[26:27], v66, s95, v[4:5]
	v_mad_u64_u32 v[68:69], s[26:27], v68, s95, v[4:5]
	v_mad_u64_u32 v[70:71], s[26:27], v70, s95, v[4:5]
	v_mad_u64_u32 v[72:73], s[26:27], v72, s95, v[4:5]
	v_mad_u64_u32 v[74:75], s[26:27], v74, s95, v[4:5]
	v_mad_u64_u32 v[76:77], s[26:27], v76, s95, v[4:5]
	v_mad_u64_u32 v[78:79], s[26:27], v78, s95, v[4:5]
	s_waitcnt vmcnt(15)
	ds_write_b32 v48, v204
	s_waitcnt vmcnt(14)
	ds_write_b32 v50, v205
	s_waitcnt vmcnt(13)
	ds_write_b32 v52, v206
	s_waitcnt vmcnt(12)
	ds_write_b32 v54, v207
	s_waitcnt vmcnt(11)
	ds_write_b32 v56, v208
	s_waitcnt vmcnt(10)
	ds_write_b32 v58, v209
	s_waitcnt vmcnt(9)
	ds_write_b32 v60, v210
	s_waitcnt vmcnt(8)
	ds_write_b32 v62, v211
	s_waitcnt vmcnt(7)
	ds_write_b32 v64, v212
	s_waitcnt vmcnt(6)
	ds_write_b32 v66, v213
	s_waitcnt vmcnt(5)
	ds_write_b32 v68, v214
	s_waitcnt vmcnt(4)
	ds_write_b32 v70, v215
	s_waitcnt vmcnt(3)
	ds_write_b32 v72, v216
	s_waitcnt vmcnt(2)
	ds_write_b32 v74, v217
	s_waitcnt vmcnt(1)
	ds_write_b32 v76, v218
	s_waitcnt vmcnt(0)
	ds_write_b32 v78, v219
	s_add_i32 s3, s3, 16
	s_add_i32 s2, s2, 16
	s_add_i32 s7, s7, -16
	s_add_i32 s7, s7, -16
	s_cmp_lg_u32 s7, 0
	s_waitcnt lgkmcnt(0)
	ds_read2_b32 v[32:33], v43 offset0:33 offset1:41
	ds_read2_b32 v[34:35], v43 offset1:8
	ds_read2_b32 v[36:37], v43 offset0:66 offset1:74
	ds_read2_b32 v[48:49], v43 offset0:99 offset1:107
	ds_read2_b32 v[50:51], v43 offset0:132 offset1:140
	ds_read2_b32 v[52:53], v43 offset0:165 offset1:173
	ds_read2_b32 v[54:55], v43 offset0:198 offset1:206
	ds_read2_b32 v[56:57], v43 offset0:231 offset1:239
	s_add_i32 s2, s22, 0x1a00
	v_add_u32_e32 v60, s2, v41
	s_ashr_i32 s9, s8, 31
	v_ashrrev_i32_e32 v61, 31, v60
	v_lshl_add_u64 v[58:59], s[8:9], 1, v[24:25]
	v_lshlrev_b64 v[60:61], 12, v[60:61]
	s_waitcnt lgkmcnt(6)
	v_cvt_pk_bf16_f32 v28, v34, v32
	s_waitcnt lgkmcnt(4)
	v_cvt_pk_bf16_f32 v29, v36, v48
	s_waitcnt lgkmcnt(2)
	v_cvt_pk_bf16_f32 v30, v50, v52
	s_waitcnt lgkmcnt(0)
	v_cvt_pk_bf16_f32 v31, v54, v56
	v_lshl_add_u64 v[60:61], v[58:59], 0, v[60:61]
	v_add_u32_e32 v32, s2, v45
	global_store_dwordx4 v[60:61], v[28:31], off
	s_add_i32 s0, s0, s81
	s_cmpk_lt_i32 s0, 0x100
	v_cvt_pk_bf16_f32 v28, v35, v33
	v_ashrrev_i32_e32 v33, 31, v32
	v_cvt_pk_bf16_f32 v29, v37, v49
	v_cvt_pk_bf16_f32 v30, v51, v53
	v_cvt_pk_bf16_f32 v31, v55, v57
	v_lshlrev_b64 v[32:33], 12, v[32:33]
	ds_read2_b32 v[34:35], v43 offset0:49 offset1:57
	ds_read2_b32 v[36:37], v43 offset0:16 offset1:24
	ds_read2_b32 v[48:49], v43 offset0:82 offset1:90
	ds_read2_b32 v[50:51], v43 offset0:115 offset1:123
	ds_read2_b32 v[52:53], v43 offset0:148 offset1:156
	ds_read2_b32 v[54:55], v43 offset0:181 offset1:189
	ds_read2_b32 v[56:57], v43 offset0:214 offset1:222
	ds_read2_b32 v[60:61], v43 offset0:247 offset1:255
	v_lshl_add_u64 v[32:33], v[58:59], 0, v[32:33]
	global_store_dwordx4 v[32:33], v[28:31], off
	v_add_u32_e32 v32, s2, v46
	v_ashrrev_i32_e32 v33, 31, v32
	v_lshlrev_b64 v[32:33], 12, v[32:33]
	s_waitcnt lgkmcnt(6)
	v_cvt_pk_bf16_f32 v28, v36, v34
	s_waitcnt lgkmcnt(4)
	v_cvt_pk_bf16_f32 v29, v48, v50
	s_waitcnt lgkmcnt(2)
	v_cvt_pk_bf16_f32 v30, v52, v54
	s_waitcnt lgkmcnt(0)
	v_cvt_pk_bf16_f32 v31, v56, v60
	v_lshl_add_u64 v[32:33], v[58:59], 0, v[32:33]
	global_store_dwordx4 v[32:33], v[28:31], off
	v_add_u32_e32 v32, s2, v47
	v_ashrrev_i32_e32 v33, 31, v32
	v_lshlrev_b64 v[32:33], 12, v[32:33]
	v_cvt_pk_bf16_f32 v28, v37, v35
	v_cvt_pk_bf16_f32 v29, v49, v51
	v_cvt_pk_bf16_f32 v30, v53, v55
	v_cvt_pk_bf16_f32 v31, v57, v61
	v_lshl_add_u64 v[32:33], v[58:59], 0, v[32:33]
	global_store_dwordx4 v[32:33], v[28:31], off
	s_waitcnt lgkmcnt(0)
	s_cbranch_scc1 .LBB0_83
	s_movk_i32 s0, 0x5f

.LBB0_104:
	s_lshl_b32 s9, s3, 1
	s_lshl_b32 s10, s2, 1
	s_mov_b32 s98, s9
	s_mov_b32 s99, s10
	v_add_u32_e32 v50, s9, v28
	v_add_u32_e32 v48, s10, v1
	v_add_u32_e32 v52, s10, v19
	v_add_u32_e32 v54, s9, v30
	v_add_u32_e32 v56, s10, v21
	v_add_u32_e32 v58, s9, v32
	v_add_u32_e32 v60, s10, v29
	v_add_u32_e32 v62, s9, v34
	v_add_u32_e32 v64, s10, v31
	v_add_u32_e32 v66, s9, v36
	v_add_u32_e32 v68, s10, v33
	v_add_u32_e32 v70, s9, v38
	v_add_u32_e32 v72, s10, v35
	v_add_u32_e32 v74, s9, v40
	v_add_u32_e32 v76, s10, v37
	v_add_u32_e32 v78, s9, v42
	v_ashrrev_i32_e32 v51, 31, v50
	v_ashrrev_i32_e32 v49, 31, v48
	v_ashrrev_i32_e32 v55, 31, v54
	v_ashrrev_i32_e32 v53, 31, v52
	v_ashrrev_i32_e32 v59, 31, v58
	v_ashrrev_i32_e32 v57, 31, v56
	v_ashrrev_i32_e32 v63, 31, v62
	v_ashrrev_i32_e32 v61, 31, v60
	v_ashrrev_i32_e32 v67, 31, v66
	v_ashrrev_i32_e32 v65, 31, v64
	v_ashrrev_i32_e32 v71, 31, v70
	v_ashrrev_i32_e32 v69, 31, v68
	v_ashrrev_i32_e32 v75, 31, v74
	v_ashrrev_i32_e32 v73, 31, v72
	v_ashrrev_i32_e32 v79, 31, v78
	v_ashrrev_i32_e32 v77, 31, v76
	v_lshlrev_b64 v[50:51], 13, v[50:51]
	v_lshlrev_b64 v[48:49], 13, v[48:49]
	v_lshlrev_b64 v[52:53], 13, v[52:53]
	v_lshlrev_b64 v[54:55], 13, v[54:55]
	v_lshlrev_b64 v[56:57], 13, v[56:57]
	v_lshlrev_b64 v[58:59], 13, v[58:59]
	v_lshlrev_b64 v[60:61], 13, v[60:61]
	v_lshlrev_b64 v[62:63], 13, v[62:63]
	v_lshlrev_b64 v[64:65], 13, v[64:65]
	v_lshlrev_b64 v[66:67], 13, v[66:67]
	v_lshlrev_b64 v[68:69], 13, v[68:69]
	v_lshlrev_b64 v[70:71], 13, v[70:71]
	v_lshlrev_b64 v[72:73], 13, v[72:73]
	v_lshlrev_b64 v[74:75], 13, v[74:75]
	v_lshlrev_b64 v[76:77], 13, v[76:77]
	v_lshlrev_b64 v[78:79], 13, v[78:79]
	v_lshl_add_u64 v[50:51], v[26:27], 0, v[50:51]
	v_lshl_add_u64 v[48:49], v[26:27], 0, v[48:49]
	v_lshl_add_u64 v[54:55], v[26:27], 0, v[54:55]
	v_lshl_add_u64 v[52:53], v[26:27], 0, v[52:53]
	v_lshl_add_u64 v[58:59], v[26:27], 0, v[58:59]
	v_lshl_add_u64 v[56:57], v[26:27], 0, v[56:57]
	v_lshl_add_u64 v[62:63], v[26:27], 0, v[62:63]
	v_lshl_add_u64 v[60:61], v[26:27], 0, v[60:61]
	v_lshl_add_u64 v[66:67], v[26:27], 0, v[66:67]
	v_lshl_add_u64 v[64:65], v[26:27], 0, v[64:65]
	v_lshl_add_u64 v[70:71], v[26:27], 0, v[70:71]
	v_lshl_add_u64 v[68:69], v[26:27], 0, v[68:69]
	v_lshl_add_u64 v[74:75], v[26:27], 0, v[74:75]
	v_lshl_add_u64 v[72:73], v[26:27], 0, v[72:73]
	v_lshl_add_u64 v[78:79], v[26:27], 0, v[78:79]
	v_lshl_add_u64 v[76:77], v[26:27], 0, v[76:77]
	global_load_dword v188, v[50:51], off
	global_load_dword v189, v[48:49], off
	global_load_dword v190, v[54:55], off
	global_load_dword v191, v[52:53], off
	global_load_dword v192, v[58:59], off
	global_load_dword v193, v[56:57], off
	global_load_dword v194, v[62:63], off
	global_load_dword v195, v[60:61], off
	global_load_dword v196, v[66:67], off
	global_load_dword v197, v[64:65], off
	global_load_dword v198, v[70:71], off
	global_load_dword v199, v[68:69], off
	global_load_dword v200, v[74:75], off
	global_load_dword v201, v[72:73], off
	global_load_dword v202, v[78:79], off
	global_load_dword v203, v[76:77], off
	s_add_i32 s3, s3, 16
	s_add_i32 s2, s2, 16
	s_lshl_b32 s9, s3, 1
	s_lshl_b32 s10, s2, 1
	v_add_u32_e32 v50, s9, v28
	v_add_u32_e32 v48, s10, v1
	v_add_u32_e32 v52, s10, v19
	v_add_u32_e32 v54, s9, v30
	v_add_u32_e32 v56, s10, v21
	v_add_u32_e32 v58, s9, v32
	v_add_u32_e32 v60, s10, v29
	v_add_u32_e32 v62, s9, v34
	v_add_u32_e32 v64, s10, v31
	v_add_u32_e32 v66, s9, v36
	v_add_u32_e32 v68, s10, v33
	v_add_u32_e32 v70, s9, v38
	v_add_u32_e32 v72, s10, v35
	v_add_u32_e32 v74, s9, v40
	v_add_u32_e32 v76, s10, v37
	v_add_u32_e32 v78, s9, v42
	v_ashrrev_i32_e32 v51, 31, v50
	v_ashrrev_i32_e32 v49, 31, v48
	v_ashrrev_i32_e32 v55, 31, v54
	v_ashrrev_i32_e32 v53, 31, v52
	v_ashrrev_i32_e32 v59, 31, v58
	v_ashrrev_i32_e32 v57, 31, v56
	v_ashrrev_i32_e32 v63, 31, v62
	v_ashrrev_i32_e32 v61, 31, v60
	v_ashrrev_i32_e32 v67, 31, v66
	v_ashrrev_i32_e32 v65, 31, v64
	v_ashrrev_i32_e32 v71, 31, v70
	v_ashrrev_i32_e32 v69, 31, v68
	v_ashrrev_i32_e32 v75, 31, v74
	v_ashrrev_i32_e32 v73, 31, v72
	v_ashrrev_i32_e32 v79, 31, v78
	v_ashrrev_i32_e32 v77, 31, v76
	v_lshlrev_b64 v[50:51], 13, v[50:51]
	v_lshlrev_b64 v[48:49], 13, v[48:49]
	v_lshlrev_b64 v[52:53], 13, v[52:53]
	v_lshlrev_b64 v[54:55], 13, v[54:55]
	v_lshlrev_b64 v[56:57], 13, v[56:57]
	v_lshlrev_b64 v[58:59], 13, v[58:59]
	v_lshlrev_b64 v[60:61], 13, v[60:61]
	v_lshlrev_b64 v[62:63], 13, v[62:63]
	v_lshlrev_b64 v[64:65], 13, v[64:65]
	v_lshlrev_b64 v[66:67], 13, v[66:67]
	v_lshlrev_b64 v[68:69], 13, v[68:69]
	v_lshlrev_b64 v[70:71], 13, v[70:71]
	v_lshlrev_b64 v[72:73], 13, v[72:73]
	v_lshlrev_b64 v[74:75], 13, v[74:75]
	v_lshlrev_b64 v[76:77], 13, v[76:77]
	v_lshlrev_b64 v[78:79], 13, v[78:79]
	v_lshl_add_u64 v[50:51], v[26:27], 0, v[50:51]
	v_lshl_add_u64 v[48:49], v[26:27], 0, v[48:49]
	v_lshl_add_u64 v[54:55], v[26:27], 0, v[54:55]
	v_lshl_add_u64 v[52:53], v[26:27], 0, v[52:53]
	v_lshl_add_u64 v[58:59], v[26:27], 0, v[58:59]
	v_lshl_add_u64 v[56:57], v[26:27], 0, v[56:57]
	v_lshl_add_u64 v[62:63], v[26:27], 0, v[62:63]
	v_lshl_add_u64 v[60:61], v[26:27], 0, v[60:61]
	v_lshl_add_u64 v[66:67], v[26:27], 0, v[66:67]
	v_lshl_add_u64 v[64:65], v[26:27], 0, v[64:65]
	v_lshl_add_u64 v[70:71], v[26:27], 0, v[70:71]
	v_lshl_add_u64 v[68:69], v[26:27], 0, v[68:69]
	v_lshl_add_u64 v[74:75], v[26:27], 0, v[74:75]
	v_lshl_add_u64 v[72:73], v[26:27], 0, v[72:73]
	v_lshl_add_u64 v[78:79], v[26:27], 0, v[78:79]
	v_lshl_add_u64 v[76:77], v[26:27], 0, v[76:77]
	global_load_dword v204, v[50:51], off
	global_load_dword v205, v[48:49], off
	global_load_dword v206, v[54:55], off
	global_load_dword v207, v[52:53], off
	global_load_dword v208, v[58:59], off
	global_load_dword v209, v[56:57], off
	global_load_dword v210, v[62:63], off
	global_load_dword v211, v[60:61], off
	global_load_dword v212, v[66:67], off
	global_load_dword v213, v[64:65], off
	global_load_dword v214, v[70:71], off
	global_load_dword v215, v[68:69], off
	global_load_dword v216, v[74:75], off
	global_load_dword v217, v[72:73], off
	global_load_dword v218, v[78:79], off
	global_load_dword v219, v[76:77], off
	s_mov_b32 s9, s98
	s_mov_b32 s10, s99
	v_add_u32_e32 v48, s9, v2
	v_add_u32_e32 v50, s10, v3
	v_add_u32_e32 v54, s10, v5
	v_add_u32_e32 v52, s9, v6
	v_add_u32_e32 v58, s10, v7
	v_add_u32_e32 v56, s9, v8
	v_add_u32_e32 v62, s10, v9
	v_add_u32_e32 v60, s9, v10
	v_add_u32_e32 v66, s10, v11
	v_add_u32_e32 v64, s9, v12
	v_add_u32_e32 v70, s10, v13
	v_add_u32_e32 v68, s9, v14
	v_add_u32_e32 v74, s10, v15
	v_add_u32_e32 v72, s9, v16
	v_add_u32_e32 v78, s10, v17
	v_add_u32_e32 v76, s9, v18
	v_mad_u64_u32 v[48:49], s[22:23], v48, s95, v[4:5]
	v_mad_u64_u32 v[50:51], s[22:23], v50, s95, v[4:5]
	v_mad_u64_u32 v[52:53], s[22:23], v52, s95, v[4:5]
	v_mad_u64_u32 v[54:55], s[22:23], v54, s95, v[4:5]
	v_mad_u64_u32 v[56:57], s[22:23], v56, s95, v[4:5]
	v_mad_u64_u32 v[58:59], s[22:23], v58, s95, v[4:5]
	v_mad_u64_u32 v[60:61], s[22:23], v60, s95, v[4:5]
	v_mad_u64_u32 v[62:63], s[22:23], v62, s95, v[4:5]
	v_mad_u64_u32 v[64:65], s[22:23], v64, s95, v[4:5]
	v_mad_u64_u32 v[66:67], s[22:23], v66, s95, v[4:5]
	v_mad_u64_u32 v[68:69], s[22:23], v68, s95, v[4:5]
	v_mad_u64_u32 v[70:71], s[22:23], v70, s95, v[4:5]
	v_mad_u64_u32 v[72:73], s[22:23], v72, s95, v[4:5]
	v_mad_u64_u32 v[74:75], s[22:23], v74, s95, v[4:5]
	v_mad_u64_u32 v[76:77], s[22:23], v76, s95, v[4:5]
	v_mad_u64_u32 v[78:79], s[22:23], v78, s95, v[4:5]
	s_waitcnt vmcnt(31)
	ds_write_b32 v48, v188
	s_waitcnt vmcnt(30)
	ds_write_b32 v50, v189
	s_waitcnt vmcnt(29)
	ds_write_b32 v52, v190
	s_waitcnt vmcnt(28)
	ds_write_b32 v54, v191
	s_waitcnt vmcnt(27)
	ds_write_b32 v56, v192
	s_waitcnt vmcnt(26)
	ds_write_b32 v58, v193
	s_waitcnt vmcnt(25)
	ds_write_b32 v60, v194
	s_waitcnt vmcnt(24)
	ds_write_b32 v62, v195
	s_waitcnt vmcnt(23)
	ds_write_b32 v64, v196
	s_waitcnt vmcnt(22)
	ds_write_b32 v66, v197
	s_waitcnt vmcnt(21)
	ds_write_b32 v68, v198
	s_waitcnt vmcnt(20)
	ds_write_b32 v70, v199
	s_waitcnt vmcnt(19)
	ds_write_b32 v72, v200
	s_waitcnt vmcnt(18)
	ds_write_b32 v74, v201
	s_waitcnt vmcnt(17)
	ds_write_b32 v76, v202
	s_waitcnt vmcnt(16)
	ds_write_b32 v78, v203
	s_lshl_b32 s9, s3, 1
	s_lshl_b32 s10, s2, 1
	v_add_u32_e32 v48, s9, v2
	v_add_u32_e32 v50, s10, v3
	v_add_u32_e32 v54, s10, v5
	v_add_u32_e32 v52, s9, v6
	v_add_u32_e32 v58, s10, v7
	v_add_u32_e32 v56, s9, v8
	v_add_u32_e32 v62, s10, v9
	v_add_u32_e32 v60, s9, v10
	v_add_u32_e32 v66, s10, v11
	v_add_u32_e32 v64, s9, v12
	v_add_u32_e32 v70, s10, v13
	v_add_u32_e32 v68, s9, v14
	v_add_u32_e32 v74, s10, v15
	v_add_u32_e32 v72, s9, v16
	v_add_u32_e32 v78, s10, v17
	v_add_u32_e32 v76, s9, v18
	v_mad_u64_u32 v[48:49], s[22:23], v48, s95, v[4:5]
	v_mad_u64_u32 v[50:51], s[22:23], v50, s95, v[4:5]
	v_mad_u64_u32 v[52:53], s[22:23], v52, s95, v[4:5]
	v_mad_u64_u32 v[54:55], s[22:23], v54, s95, v[4:5]
	v_mad_u64_u32 v[56:57], s[22:23], v56, s95, v[4:5]
	v_mad_u64_u32 v[58:59], s[22:23], v58, s95, v[4:5]
	v_mad_u64_u32 v[60:61], s[22:23], v60, s95, v[4:5]
	v_mad_u64_u32 v[62:63], s[22:23], v62, s95, v[4:5]
	v_mad_u64_u32 v[64:65], s[22:23], v64, s95, v[4:5]
	v_mad_u64_u32 v[66:67], s[22:23], v66, s95, v[4:5]
	v_mad_u64_u32 v[68:69], s[22:23], v68, s95, v[4:5]
	v_mad_u64_u32 v[70:71], s[22:23], v70, s95, v[4:5]
	v_mad_u64_u32 v[72:73], s[22:23], v72, s95, v[4:5]
	v_mad_u64_u32 v[74:75], s[22:23], v74, s95, v[4:5]
	v_mad_u64_u32 v[76:77], s[22:23], v76, s95, v[4:5]
	v_mad_u64_u32 v[78:79], s[22:23], v78, s95, v[4:5]
	s_waitcnt vmcnt(15)
	ds_write_b32 v48, v204
	s_waitcnt vmcnt(14)
	ds_write_b32 v50, v205
	s_waitcnt vmcnt(13)
	ds_write_b32 v52, v206
	s_waitcnt vmcnt(12)
	ds_write_b32 v54, v207
	s_waitcnt vmcnt(11)
	ds_write_b32 v56, v208
	s_waitcnt vmcnt(10)
	ds_write_b32 v58, v209
	s_waitcnt vmcnt(9)
	ds_write_b32 v60, v210
	s_waitcnt vmcnt(8)
	ds_write_b32 v62, v211
	s_waitcnt vmcnt(7)
	ds_write_b32 v64, v212
	s_waitcnt vmcnt(6)
	ds_write_b32 v66, v213
	s_waitcnt vmcnt(5)
	ds_write_b32 v68, v214
	s_waitcnt vmcnt(4)
	ds_write_b32 v70, v215
	s_waitcnt vmcnt(3)
	ds_write_b32 v72, v216
	s_waitcnt vmcnt(2)
	ds_write_b32 v74, v217
	s_waitcnt vmcnt(1)
	ds_write_b32 v76, v218
	s_waitcnt vmcnt(0)
	ds_write_b32 v78, v219
	s_add_i32 s3, s3, 16
	s_add_i32 s2, s2, 16
	s_add_i32 s7, s7, -16
	s_add_i32 s7, s7, -16
	s_cmp_lg_u32 s7, 0
	s_waitcnt lgkmcnt(0)
	ds_read2_b32 v[30:31], v43 offset0:33 offset1:41
	ds_read2_b32 v[32:33], v43 offset1:8
	ds_read2_b32 v[34:35], v43 offset0:66 offset1:74
	ds_read2_b32 v[36:37], v43 offset0:99 offset1:107
	ds_read2_b32 v[48:49], v43 offset0:132 offset1:140
	ds_read2_b32 v[50:51], v43 offset0:165 offset1:173
	ds_read2_b32 v[52:53], v43 offset0:198 offset1:206
	ds_read2_b32 v[54:55], v43 offset0:231 offset1:239
	s_add_i32 s2, s12, 0x1000
	v_add_u32_e32 v58, s2, v41
	s_ashr_i32 s9, s8, 31
	v_ashrrev_i32_e32 v59, 31, v58
	v_lshl_add_u64 v[56:57], s[8:9], 1, v[22:23]
	v_lshlrev_b64 v[58:59], 9, v[58:59]
	s_waitcnt lgkmcnt(6)
	v_cvt_pk_bf16_f32 v26, v32, v30
	s_waitcnt lgkmcnt(4)
	v_cvt_pk_bf16_f32 v27, v34, v36
	s_waitcnt lgkmcnt(2)
	v_cvt_pk_bf16_f32 v28, v48, v50
	s_waitcnt lgkmcnt(0)
	v_cvt_pk_bf16_f32 v29, v52, v54
	v_lshl_add_u64 v[58:59], v[56:57], 0, v[58:59]
	v_add_u32_e32 v30, s2, v45
	global_store_dwordx4 v[58:59], v[26:29], off
	s_add_i32 s0, s0, s81
	s_cmpk_lt_i32 s0, 0x100
	v_cvt_pk_bf16_f32 v26, v33, v31
	v_ashrrev_i32_e32 v31, 31, v30
	v_cvt_pk_bf16_f32 v27, v35, v37
	v_cvt_pk_bf16_f32 v28, v49, v51
	v_cvt_pk_bf16_f32 v29, v53, v55
	v_lshlrev_b64 v[30:31], 9, v[30:31]
	ds_read2_b32 v[32:33], v43 offset0:49 offset1:57
	ds_read2_b32 v[34:35], v43 offset0:16 offset1:24
	ds_read2_b32 v[36:37], v43 offset0:82 offset1:90
	ds_read2_b32 v[48:49], v43 offset0:115 offset1:123
	ds_read2_b32 v[50:51], v43 offset0:148 offset1:156
	ds_read2_b32 v[52:53], v43 offset0:181 offset1:189
	ds_read2_b32 v[54:55], v43 offset0:214 offset1:222
	ds_read2_b32 v[58:59], v43 offset0:247 offset1:255
	v_lshl_add_u64 v[30:31], v[56:57], 0, v[30:31]
	global_store_dwordx4 v[30:31], v[26:29], off
	v_add_u32_e32 v30, s2, v46
	v_ashrrev_i32_e32 v31, 31, v30
	v_lshlrev_b64 v[30:31], 9, v[30:31]
	s_waitcnt lgkmcnt(6)
	v_cvt_pk_bf16_f32 v26, v34, v32
	s_waitcnt lgkmcnt(4)
	v_cvt_pk_bf16_f32 v27, v36, v48
	s_waitcnt lgkmcnt(2)
	v_cvt_pk_bf16_f32 v28, v50, v52
	s_waitcnt lgkmcnt(0)
	v_cvt_pk_bf16_f32 v29, v54, v58
	v_lshl_add_u64 v[30:31], v[56:57], 0, v[30:31]
	global_store_dwordx4 v[30:31], v[26:29], off
	v_add_u32_e32 v30, s2, v47
	v_ashrrev_i32_e32 v31, 31, v30
	v_lshlrev_b64 v[30:31], 9, v[30:31]
	v_cvt_pk_bf16_f32 v26, v35, v33
	v_cvt_pk_bf16_f32 v27, v37, v49
	v_cvt_pk_bf16_f32 v28, v51, v53
	v_cvt_pk_bf16_f32 v29, v55, v59
	v_lshl_add_u64 v[30:31], v[56:57], 0, v[30:31]
	global_store_dwordx4 v[30:31], v[26:29], off
	s_waitcnt lgkmcnt(0)
	s_cbranch_scc1 .LBB0_103

.LBB0_109:
	s_lshl_b32 s9, s3, 1
	s_lshl_b32 s10, s2, 1
	s_mov_b32 s98, s9
	s_mov_b32 s99, s10
	v_add_u32_e32 v50, s9, v26
	v_add_u32_e32 v48, s10, v1
	v_add_u32_e32 v52, s10, v19
	v_add_u32_e32 v54, s9, v28
	v_add_u32_e32 v56, s10, v27
	v_add_u32_e32 v58, s9, v30
	v_add_u32_e32 v60, s10, v29
	v_add_u32_e32 v62, s9, v32
	v_add_u32_e32 v64, s10, v31
	v_add_u32_e32 v66, s9, v34
	v_add_u32_e32 v68, s10, v33
	v_add_u32_e32 v70, s9, v36
	v_add_u32_e32 v72, s10, v35
	v_add_u32_e32 v74, s9, v38
	v_add_u32_e32 v76, s10, v37
	v_add_u32_e32 v78, s9, v40
	v_ashrrev_i32_e32 v51, 31, v50
	v_ashrrev_i32_e32 v49, 31, v48
	v_ashrrev_i32_e32 v55, 31, v54
	v_ashrrev_i32_e32 v53, 31, v52
	v_ashrrev_i32_e32 v59, 31, v58
	v_ashrrev_i32_e32 v57, 31, v56
	v_ashrrev_i32_e32 v63, 31, v62
	v_ashrrev_i32_e32 v61, 31, v60
	v_ashrrev_i32_e32 v67, 31, v66
	v_ashrrev_i32_e32 v65, 31, v64
	v_ashrrev_i32_e32 v71, 31, v70
	v_ashrrev_i32_e32 v69, 31, v68
	v_ashrrev_i32_e32 v75, 31, v74
	v_ashrrev_i32_e32 v73, 31, v72
	v_ashrrev_i32_e32 v79, 31, v78
	v_ashrrev_i32_e32 v77, 31, v76
	v_lshlrev_b64 v[50:51], 13, v[50:51]
	v_lshlrev_b64 v[48:49], 13, v[48:49]
	v_lshlrev_b64 v[52:53], 13, v[52:53]
	v_lshlrev_b64 v[54:55], 13, v[54:55]
	v_lshlrev_b64 v[56:57], 13, v[56:57]
	v_lshlrev_b64 v[58:59], 13, v[58:59]
	v_lshlrev_b64 v[60:61], 13, v[60:61]
	v_lshlrev_b64 v[62:63], 13, v[62:63]
	v_lshlrev_b64 v[64:65], 13, v[64:65]
	v_lshlrev_b64 v[66:67], 13, v[66:67]
	v_lshlrev_b64 v[68:69], 13, v[68:69]
	v_lshlrev_b64 v[70:71], 13, v[70:71]
	v_lshlrev_b64 v[72:73], 13, v[72:73]
	v_lshlrev_b64 v[74:75], 13, v[74:75]
	v_lshlrev_b64 v[76:77], 13, v[76:77]
	v_lshlrev_b64 v[78:79], 13, v[78:79]
	v_lshl_add_u64 v[50:51], v[24:25], 0, v[50:51]
	v_lshl_add_u64 v[48:49], v[24:25], 0, v[48:49]
	v_lshl_add_u64 v[54:55], v[24:25], 0, v[54:55]
	v_lshl_add_u64 v[52:53], v[24:25], 0, v[52:53]
	v_lshl_add_u64 v[58:59], v[24:25], 0, v[58:59]
	v_lshl_add_u64 v[56:57], v[24:25], 0, v[56:57]
	v_lshl_add_u64 v[62:63], v[24:25], 0, v[62:63]
	v_lshl_add_u64 v[60:61], v[24:25], 0, v[60:61]
	v_lshl_add_u64 v[66:67], v[24:25], 0, v[66:67]
	v_lshl_add_u64 v[64:65], v[24:25], 0, v[64:65]
	v_lshl_add_u64 v[70:71], v[24:25], 0, v[70:71]
	v_lshl_add_u64 v[68:69], v[24:25], 0, v[68:69]
	v_lshl_add_u64 v[74:75], v[24:25], 0, v[74:75]
	v_lshl_add_u64 v[72:73], v[24:25], 0, v[72:73]
	v_lshl_add_u64 v[78:79], v[24:25], 0, v[78:79]
	v_lshl_add_u64 v[76:77], v[24:25], 0, v[76:77]
	global_load_dword v188, v[50:51], off
	global_load_dword v189, v[48:49], off
	global_load_dword v190, v[54:55], off
	global_load_dword v191, v[52:53], off
	global_load_dword v192, v[58:59], off
	global_load_dword v193, v[56:57], off
	global_load_dword v194, v[62:63], off
	global_load_dword v195, v[60:61], off
	global_load_dword v196, v[66:67], off
	global_load_dword v197, v[64:65], off
	global_load_dword v198, v[70:71], off
	global_load_dword v199, v[68:69], off
	global_load_dword v200, v[74:75], off
	global_load_dword v201, v[72:73], off
	global_load_dword v202, v[78:79], off
	global_load_dword v203, v[76:77], off
	s_add_i32 s3, s3, 16
	s_add_i32 s2, s2, 16
	s_lshl_b32 s9, s3, 1
	s_lshl_b32 s10, s2, 1
	v_add_u32_e32 v50, s9, v26
	v_add_u32_e32 v48, s10, v1
	v_add_u32_e32 v52, s10, v19
	v_add_u32_e32 v54, s9, v28
	v_add_u32_e32 v56, s10, v27
	v_add_u32_e32 v58, s9, v30
	v_add_u32_e32 v60, s10, v29
	v_add_u32_e32 v62, s9, v32
	v_add_u32_e32 v64, s10, v31
	v_add_u32_e32 v66, s9, v34
	v_add_u32_e32 v68, s10, v33
	v_add_u32_e32 v70, s9, v36
	v_add_u32_e32 v72, s10, v35
	v_add_u32_e32 v74, s9, v38
	v_add_u32_e32 v76, s10, v37
	v_add_u32_e32 v78, s9, v40
	v_ashrrev_i32_e32 v51, 31, v50
	v_ashrrev_i32_e32 v49, 31, v48
	v_ashrrev_i32_e32 v55, 31, v54
	v_ashrrev_i32_e32 v53, 31, v52
	v_ashrrev_i32_e32 v59, 31, v58
	v_ashrrev_i32_e32 v57, 31, v56
	v_ashrrev_i32_e32 v63, 31, v62
	v_ashrrev_i32_e32 v61, 31, v60
	v_ashrrev_i32_e32 v67, 31, v66
	v_ashrrev_i32_e32 v65, 31, v64
	v_ashrrev_i32_e32 v71, 31, v70
	v_ashrrev_i32_e32 v69, 31, v68
	v_ashrrev_i32_e32 v75, 31, v74
	v_ashrrev_i32_e32 v73, 31, v72
	v_ashrrev_i32_e32 v79, 31, v78
	v_ashrrev_i32_e32 v77, 31, v76
	v_lshlrev_b64 v[50:51], 13, v[50:51]
	v_lshlrev_b64 v[48:49], 13, v[48:49]
	v_lshlrev_b64 v[52:53], 13, v[52:53]
	v_lshlrev_b64 v[54:55], 13, v[54:55]
	v_lshlrev_b64 v[56:57], 13, v[56:57]
	v_lshlrev_b64 v[58:59], 13, v[58:59]
	v_lshlrev_b64 v[60:61], 13, v[60:61]
	v_lshlrev_b64 v[62:63], 13, v[62:63]
	v_lshlrev_b64 v[64:65], 13, v[64:65]
	v_lshlrev_b64 v[66:67], 13, v[66:67]
	v_lshlrev_b64 v[68:69], 13, v[68:69]
	v_lshlrev_b64 v[70:71], 13, v[70:71]
	v_lshlrev_b64 v[72:73], 13, v[72:73]
	v_lshlrev_b64 v[74:75], 13, v[74:75]
	v_lshlrev_b64 v[76:77], 13, v[76:77]
	v_lshlrev_b64 v[78:79], 13, v[78:79]
	v_lshl_add_u64 v[50:51], v[24:25], 0, v[50:51]
	v_lshl_add_u64 v[48:49], v[24:25], 0, v[48:49]
	v_lshl_add_u64 v[54:55], v[24:25], 0, v[54:55]
	v_lshl_add_u64 v[52:53], v[24:25], 0, v[52:53]
	v_lshl_add_u64 v[58:59], v[24:25], 0, v[58:59]
	v_lshl_add_u64 v[56:57], v[24:25], 0, v[56:57]
	v_lshl_add_u64 v[62:63], v[24:25], 0, v[62:63]
	v_lshl_add_u64 v[60:61], v[24:25], 0, v[60:61]
	v_lshl_add_u64 v[66:67], v[24:25], 0, v[66:67]
	v_lshl_add_u64 v[64:65], v[24:25], 0, v[64:65]
	v_lshl_add_u64 v[70:71], v[24:25], 0, v[70:71]
	v_lshl_add_u64 v[68:69], v[24:25], 0, v[68:69]
	v_lshl_add_u64 v[74:75], v[24:25], 0, v[74:75]
	v_lshl_add_u64 v[72:73], v[24:25], 0, v[72:73]
	v_lshl_add_u64 v[78:79], v[24:25], 0, v[78:79]
	v_lshl_add_u64 v[76:77], v[24:25], 0, v[76:77]
	global_load_dword v204, v[50:51], off
	global_load_dword v205, v[48:49], off
	global_load_dword v206, v[54:55], off
	global_load_dword v207, v[52:53], off
	global_load_dword v208, v[58:59], off
	global_load_dword v209, v[56:57], off
	global_load_dword v210, v[62:63], off
	global_load_dword v211, v[60:61], off
	global_load_dword v212, v[66:67], off
	global_load_dword v213, v[64:65], off
	global_load_dword v214, v[70:71], off
	global_load_dword v215, v[68:69], off
	global_load_dword v216, v[74:75], off
	global_load_dword v217, v[72:73], off
	global_load_dword v218, v[78:79], off
	global_load_dword v219, v[76:77], off
	s_mov_b32 s9, s98
	s_mov_b32 s10, s99
	v_add_u32_e32 v48, s9, v2
	v_add_u32_e32 v50, s10, v3
	v_add_u32_e32 v54, s10, v5
	v_add_u32_e32 v52, s9, v6
	v_add_u32_e32 v58, s10, v7
	v_add_u32_e32 v56, s9, v8
	v_add_u32_e32 v62, s10, v9
	v_add_u32_e32 v60, s9, v10
	v_add_u32_e32 v66, s10, v11
	v_add_u32_e32 v64, s9, v12
	v_add_u32_e32 v70, s10, v13
	v_add_u32_e32 v68, s9, v14
	v_add_u32_e32 v74, s10, v15
	v_add_u32_e32 v72, s9, v16
	v_add_u32_e32 v78, s10, v17
	v_add_u32_e32 v76, s9, v18
	v_mad_u64_u32 v[48:49], s[22:23], v48, s95, v[4:5]
	v_mad_u64_u32 v[50:51], s[22:23], v50, s95, v[4:5]
	v_mad_u64_u32 v[52:53], s[22:23], v52, s95, v[4:5]
	v_mad_u64_u32 v[54:55], s[22:23], v54, s95, v[4:5]
	v_mad_u64_u32 v[56:57], s[22:23], v56, s95, v[4:5]
	v_mad_u64_u32 v[58:59], s[22:23], v58, s95, v[4:5]
	v_mad_u64_u32 v[60:61], s[22:23], v60, s95, v[4:5]
	v_mad_u64_u32 v[62:63], s[22:23], v62, s95, v[4:5]
	v_mad_u64_u32 v[64:65], s[22:23], v64, s95, v[4:5]
	v_mad_u64_u32 v[66:67], s[22:23], v66, s95, v[4:5]
	v_mad_u64_u32 v[68:69], s[22:23], v68, s95, v[4:5]
	v_mad_u64_u32 v[70:71], s[22:23], v70, s95, v[4:5]
	v_mad_u64_u32 v[72:73], s[22:23], v72, s95, v[4:5]
	v_mad_u64_u32 v[74:75], s[22:23], v74, s95, v[4:5]
	v_mad_u64_u32 v[76:77], s[22:23], v76, s95, v[4:5]
	v_mad_u64_u32 v[78:79], s[22:23], v78, s95, v[4:5]
	s_waitcnt vmcnt(31)
	ds_write_b32 v48, v188
	s_waitcnt vmcnt(30)
	ds_write_b32 v50, v189
	s_waitcnt vmcnt(29)
	ds_write_b32 v52, v190
	s_waitcnt vmcnt(28)
	ds_write_b32 v54, v191
	s_waitcnt vmcnt(27)
	ds_write_b32 v56, v192
	s_waitcnt vmcnt(26)
	ds_write_b32 v58, v193
	s_waitcnt vmcnt(25)
	ds_write_b32 v60, v194
	s_waitcnt vmcnt(24)
	ds_write_b32 v62, v195
	s_waitcnt vmcnt(23)
	ds_write_b32 v64, v196
	s_waitcnt vmcnt(22)
	ds_write_b32 v66, v197
	s_waitcnt vmcnt(21)
	ds_write_b32 v68, v198
	s_waitcnt vmcnt(20)
	ds_write_b32 v70, v199
	s_waitcnt vmcnt(19)
	ds_write_b32 v72, v200
	s_waitcnt vmcnt(18)
	ds_write_b32 v74, v201
	s_waitcnt vmcnt(17)
	ds_write_b32 v76, v202
	s_waitcnt vmcnt(16)
	ds_write_b32 v78, v203
	s_lshl_b32 s9, s3, 1
	s_lshl_b32 s10, s2, 1
	v_add_u32_e32 v48, s9, v2
	v_add_u32_e32 v50, s10, v3
	v_add_u32_e32 v54, s10, v5
	v_add_u32_e32 v52, s9, v6
	v_add_u32_e32 v58, s10, v7
	v_add_u32_e32 v56, s9, v8
	v_add_u32_e32 v62, s10, v9
	v_add_u32_e32 v60, s9, v10
	v_add_u32_e32 v66, s10, v11
	v_add_u32_e32 v64, s9, v12
	v_add_u32_e32 v70, s10, v13
	v_add_u32_e32 v68, s9, v14
	v_add_u32_e32 v74, s10, v15
	v_add_u32_e32 v72, s9, v16
	v_add_u32_e32 v78, s10, v17
	v_add_u32_e32 v76, s9, v18
	v_mad_u64_u32 v[48:49], s[22:23], v48, s95, v[4:5]
	v_mad_u64_u32 v[50:51], s[22:23], v50, s95, v[4:5]
	v_mad_u64_u32 v[52:53], s[22:23], v52, s95, v[4:5]
	v_mad_u64_u32 v[54:55], s[22:23], v54, s95, v[4:5]
	v_mad_u64_u32 v[56:57], s[22:23], v56, s95, v[4:5]
	v_mad_u64_u32 v[58:59], s[22:23], v58, s95, v[4:5]
	v_mad_u64_u32 v[60:61], s[22:23], v60, s95, v[4:5]
	v_mad_u64_u32 v[62:63], s[22:23], v62, s95, v[4:5]
	v_mad_u64_u32 v[64:65], s[22:23], v64, s95, v[4:5]
	v_mad_u64_u32 v[66:67], s[22:23], v66, s95, v[4:5]
	v_mad_u64_u32 v[68:69], s[22:23], v68, s95, v[4:5]
	v_mad_u64_u32 v[70:71], s[22:23], v70, s95, v[4:5]
	v_mad_u64_u32 v[72:73], s[22:23], v72, s95, v[4:5]
	v_mad_u64_u32 v[74:75], s[22:23], v74, s95, v[4:5]
	v_mad_u64_u32 v[76:77], s[22:23], v76, s95, v[4:5]
	v_mad_u64_u32 v[78:79], s[22:23], v78, s95, v[4:5]
	s_waitcnt vmcnt(15)
	ds_write_b32 v48, v204
	s_waitcnt vmcnt(14)
	ds_write_b32 v50, v205
	s_waitcnt vmcnt(13)
	ds_write_b32 v52, v206
	s_waitcnt vmcnt(12)
	ds_write_b32 v54, v207
	s_waitcnt vmcnt(11)
	ds_write_b32 v56, v208
	s_waitcnt vmcnt(10)
	ds_write_b32 v58, v209
	s_waitcnt vmcnt(9)
	ds_write_b32 v60, v210
	s_waitcnt vmcnt(8)
	ds_write_b32 v62, v211
	s_waitcnt vmcnt(7)
	ds_write_b32 v64, v212
	s_waitcnt vmcnt(6)
	ds_write_b32 v66, v213
	s_waitcnt vmcnt(5)
	ds_write_b32 v68, v214
	s_waitcnt vmcnt(4)
	ds_write_b32 v70, v215
	s_waitcnt vmcnt(3)
	ds_write_b32 v72, v216
	s_waitcnt vmcnt(2)
	ds_write_b32 v74, v217
	s_waitcnt vmcnt(1)
	ds_write_b32 v76, v218
	s_waitcnt vmcnt(0)
	ds_write_b32 v78, v219
	s_add_i32 s3, s3, 16
	s_add_i32 s2, s2, 16
	s_add_i32 s7, s7, -16
	s_add_i32 s7, s7, -16
	s_cmp_lg_u32 s7, 0
	s_waitcnt lgkmcnt(0)
	ds_read2_b32 v[28:29], v43 offset0:33 offset1:41
	ds_read2_b32 v[30:31], v43 offset1:8
	ds_read2_b32 v[32:33], v43 offset0:66 offset1:74
	ds_read2_b32 v[34:35], v43 offset0:99 offset1:107
	ds_read2_b32 v[36:37], v43 offset0:132 offset1:140
	ds_read2_b32 v[48:49], v43 offset0:165 offset1:173
	ds_read2_b32 v[50:51], v43 offset0:198 offset1:206
	ds_read2_b32 v[52:53], v43 offset0:231 offset1:239
	v_add_u32_e32 v56, s8, v41
	s_ashr_i32 s13, s12, 31
	v_ashrrev_i32_e32 v57, 31, v56
	v_lshl_add_u64 v[54:55], s[12:13], 1, v[22:23]
	v_lshlrev_b64 v[56:57], 12, v[56:57]
	s_waitcnt lgkmcnt(6)
	v_cvt_pk_bf16_f32 v24, v30, v28
	s_waitcnt lgkmcnt(4)
	v_cvt_pk_bf16_f32 v25, v32, v34
	s_waitcnt lgkmcnt(2)
	v_cvt_pk_bf16_f32 v26, v36, v48
	s_waitcnt lgkmcnt(0)
	v_cvt_pk_bf16_f32 v27, v50, v52
	v_lshl_add_u64 v[56:57], v[54:55], 0, v[56:57]
	v_add_u32_e32 v28, s8, v45
	global_store_dwordx4 v[56:57], v[24:27], off
	s_add_i32 s0, s0, s81
	s_cmpk_gt_i32 s0, 0x7ff
	v_cvt_pk_bf16_f32 v24, v31, v29
	v_ashrrev_i32_e32 v29, 31, v28
	v_cvt_pk_bf16_f32 v25, v33, v35
	v_cvt_pk_bf16_f32 v26, v37, v49
	v_cvt_pk_bf16_f32 v27, v51, v53
	v_lshlrev_b64 v[28:29], 12, v[28:29]
	ds_read2_b32 v[30:31], v43 offset0:49 offset1:57
	ds_read2_b32 v[32:33], v43 offset0:16 offset1:24
	ds_read2_b32 v[34:35], v43 offset0:82 offset1:90
	ds_read2_b32 v[36:37], v43 offset0:115 offset1:123
	ds_read2_b32 v[48:49], v43 offset0:148 offset1:156
	ds_read2_b32 v[50:51], v43 offset0:181 offset1:189
	ds_read2_b32 v[52:53], v43 offset0:214 offset1:222
	ds_read2_b32 v[56:57], v43 offset0:247 offset1:255
	v_lshl_add_u64 v[28:29], v[54:55], 0, v[28:29]
	global_store_dwordx4 v[28:29], v[24:27], off
	v_add_u32_e32 v28, s8, v46
	v_ashrrev_i32_e32 v29, 31, v28
	v_lshlrev_b64 v[28:29], 12, v[28:29]
	s_waitcnt lgkmcnt(6)
	v_cvt_pk_bf16_f32 v24, v32, v30
	s_waitcnt lgkmcnt(4)
	v_cvt_pk_bf16_f32 v25, v34, v36
	s_waitcnt lgkmcnt(2)
	v_cvt_pk_bf16_f32 v26, v48, v50
	s_waitcnt lgkmcnt(0)
	v_cvt_pk_bf16_f32 v27, v52, v56
	v_lshl_add_u64 v[28:29], v[54:55], 0, v[28:29]
	global_store_dwordx4 v[28:29], v[24:27], off
	v_add_u32_e32 v28, s8, v47
	v_ashrrev_i32_e32 v29, 31, v28
	v_lshlrev_b64 v[28:29], 12, v[28:29]
	v_cvt_pk_bf16_f32 v24, v33, v31
	v_cvt_pk_bf16_f32 v25, v35, v37
	v_cvt_pk_bf16_f32 v26, v49, v51
	v_cvt_pk_bf16_f32 v27, v53, v57
	v_lshl_add_u64 v[28:29], v[54:55], 0, v[28:29]
	global_store_dwordx4 v[28:29], v[24:27], off
	s_waitcnt lgkmcnt(0)
	s_cbranch_scc0 .LBB0_108

.LBB0_116:
	s_lshl_b32 s9, s3, 1
	s_lshl_b32 s10, s2, 1
	s_mov_b32 s98, s9
	s_mov_b32 s99, s10
	v_add_u32_e32 v44, s9, v26
	v_add_u32_e32 v43, s10, v21
	v_add_u32_e32 v50, s10, v23
	v_add_u32_e32 v48, s9, v28
	v_add_u32_e32 v54, s10, v27
	v_add_u32_e32 v52, s9, v30
	v_add_u32_e32 v58, s10, v29
	v_add_u32_e32 v56, s9, v32
	v_add_u32_e32 v62, s10, v31
	v_add_u32_e32 v60, s9, v34
	v_add_u32_e32 v66, s10, v33
	v_add_u32_e32 v64, s9, v36
	v_add_u32_e32 v70, s10, v35
	v_add_u32_e32 v68, s9, v38
	v_add_u32_e32 v74, s10, v37
	v_add_u32_e32 v72, s9, v40
	v_mad_i64_i32 v[44:45], s[22:23], v44, s5, v[24:25]
	v_mad_i64_i32 v[46:47], s[22:23], v43, s5, v[24:25]
	v_mad_i64_i32 v[48:49], s[22:23], v48, s5, v[24:25]
	v_mad_i64_i32 v[50:51], s[22:23], v50, s5, v[24:25]
	v_mad_i64_i32 v[52:53], s[22:23], v52, s5, v[24:25]
	v_mad_i64_i32 v[54:55], s[22:23], v54, s5, v[24:25]
	v_mad_i64_i32 v[56:57], s[22:23], v56, s5, v[24:25]
	v_mad_i64_i32 v[58:59], s[22:23], v58, s5, v[24:25]
	v_mad_i64_i32 v[60:61], s[22:23], v60, s5, v[24:25]
	v_mad_i64_i32 v[62:63], s[22:23], v62, s5, v[24:25]
	v_mad_i64_i32 v[64:65], s[22:23], v64, s5, v[24:25]
	v_mad_i64_i32 v[66:67], s[22:23], v66, s5, v[24:25]
	v_mad_i64_i32 v[68:69], s[22:23], v68, s5, v[24:25]
	v_mad_i64_i32 v[70:71], s[22:23], v70, s5, v[24:25]
	v_mad_i64_i32 v[72:73], s[22:23], v72, s5, v[24:25]
	v_mad_i64_i32 v[74:75], s[22:23], v74, s5, v[24:25]
	global_load_dword v188, v[44:45], off
	global_load_dword v189, v[46:47], off
	global_load_dword v190, v[48:49], off
	global_load_dword v191, v[50:51], off
	global_load_dword v192, v[52:53], off
	global_load_dword v193, v[54:55], off
	global_load_dword v194, v[56:57], off
	global_load_dword v195, v[58:59], off
	global_load_dword v196, v[60:61], off
	global_load_dword v197, v[62:63], off
	global_load_dword v198, v[64:65], off
	global_load_dword v199, v[66:67], off
	global_load_dword v200, v[68:69], off
	global_load_dword v201, v[70:71], off
	global_load_dword v202, v[72:73], off
	global_load_dword v203, v[74:75], off
	s_add_i32 s3, s3, 16
	s_add_i32 s2, s2, 16
	s_lshl_b32 s9, s3, 1
	s_lshl_b32 s10, s2, 1
	v_add_u32_e32 v44, s9, v26
	v_add_u32_e32 v43, s10, v21
	v_add_u32_e32 v50, s10, v23
	v_add_u32_e32 v48, s9, v28
	v_add_u32_e32 v54, s10, v27
	v_add_u32_e32 v52, s9, v30
	v_add_u32_e32 v58, s10, v29
	v_add_u32_e32 v56, s9, v32
	v_add_u32_e32 v62, s10, v31
	v_add_u32_e32 v60, s9, v34
	v_add_u32_e32 v66, s10, v33
	v_add_u32_e32 v64, s9, v36
	v_add_u32_e32 v70, s10, v35
	v_add_u32_e32 v68, s9, v38
	v_add_u32_e32 v74, s10, v37
	v_add_u32_e32 v72, s9, v40
	v_mad_i64_i32 v[44:45], s[22:23], v44, s5, v[24:25]
	v_mad_i64_i32 v[46:47], s[22:23], v43, s5, v[24:25]
	v_mad_i64_i32 v[48:49], s[22:23], v48, s5, v[24:25]
	v_mad_i64_i32 v[50:51], s[22:23], v50, s5, v[24:25]
	v_mad_i64_i32 v[52:53], s[22:23], v52, s5, v[24:25]
	v_mad_i64_i32 v[54:55], s[22:23], v54, s5, v[24:25]
	v_mad_i64_i32 v[56:57], s[22:23], v56, s5, v[24:25]
	v_mad_i64_i32 v[58:59], s[22:23], v58, s5, v[24:25]
	v_mad_i64_i32 v[60:61], s[22:23], v60, s5, v[24:25]
	v_mad_i64_i32 v[62:63], s[22:23], v62, s5, v[24:25]
	v_mad_i64_i32 v[64:65], s[22:23], v64, s5, v[24:25]
	v_mad_i64_i32 v[66:67], s[22:23], v66, s5, v[24:25]
	v_mad_i64_i32 v[68:69], s[22:23], v68, s5, v[24:25]
	v_mad_i64_i32 v[70:71], s[22:23], v70, s5, v[24:25]
	v_mad_i64_i32 v[72:73], s[22:23], v72, s5, v[24:25]
	v_mad_i64_i32 v[74:75], s[22:23], v74, s5, v[24:25]
	global_load_dword v204, v[44:45], off
	global_load_dword v205, v[46:47], off
	global_load_dword v206, v[48:49], off
	global_load_dword v207, v[50:51], off
	global_load_dword v208, v[52:53], off
	global_load_dword v209, v[54:55], off
	global_load_dword v210, v[56:57], off
	global_load_dword v211, v[58:59], off
	global_load_dword v212, v[60:61], off
	global_load_dword v213, v[62:63], off
	global_load_dword v214, v[64:65], off
	global_load_dword v215, v[66:67], off
	global_load_dword v216, v[68:69], off
	global_load_dword v217, v[70:71], off
	global_load_dword v218, v[72:73], off
	global_load_dword v219, v[74:75], off
	s_mov_b32 s9, s98
	s_mov_b32 s10, s99
	v_add_u32_e32 v44, s9, v2
	v_add_u32_e32 v46, s10, v1
	v_add_u32_e32 v50, s10, v3
	v_add_u32_e32 v48, s9, v10
	v_add_u32_e32 v54, s10, v5
	v_add_u32_e32 v52, s9, v12
	v_add_u32_e32 v58, s10, v11
	v_add_u32_e32 v56, s9, v14
	v_add_u32_e32 v62, s10, v13
	v_add_u32_e32 v60, s9, v16
	v_add_u32_e32 v66, s10, v15
	v_add_u32_e32 v64, s9, v18
	v_add_u32_e32 v70, s10, v17
	v_add_u32_e32 v68, s9, v20
	v_add_u32_e32 v74, s10, v19
	v_add_u32_e32 v72, s9, v22
	v_mad_u64_u32 v[44:45], s[22:23], v44, s95, v[4:5]
	v_mad_u64_u32 v[46:47], s[22:23], v46, s95, v[4:5]
	v_mad_u64_u32 v[48:49], s[22:23], v48, s95, v[4:5]
	v_mad_u64_u32 v[50:51], s[22:23], v50, s95, v[4:5]
	v_mad_u64_u32 v[52:53], s[22:23], v52, s95, v[4:5]
	v_mad_u64_u32 v[54:55], s[22:23], v54, s95, v[4:5]
	v_mad_u64_u32 v[56:57], s[22:23], v56, s95, v[4:5]
	v_mad_u64_u32 v[58:59], s[22:23], v58, s95, v[4:5]
	v_mad_u64_u32 v[60:61], s[22:23], v60, s95, v[4:5]
	v_mad_u64_u32 v[62:63], s[22:23], v62, s95, v[4:5]
	v_mad_u64_u32 v[64:65], s[22:23], v64, s95, v[4:5]
	v_mad_u64_u32 v[66:67], s[22:23], v66, s95, v[4:5]
	v_mad_u64_u32 v[68:69], s[22:23], v68, s95, v[4:5]
	v_mad_u64_u32 v[70:71], s[22:23], v70, s95, v[4:5]
	v_mad_u64_u32 v[72:73], s[22:23], v72, s95, v[4:5]
	v_mad_u64_u32 v[74:75], s[22:23], v74, s95, v[4:5]
	s_waitcnt vmcnt(31)
	ds_write_b32 v44, v188
	s_waitcnt vmcnt(30)
	ds_write_b32 v46, v189
	s_waitcnt vmcnt(29)
	ds_write_b32 v48, v190
	s_waitcnt vmcnt(28)
	ds_write_b32 v50, v191
	s_waitcnt vmcnt(27)
	ds_write_b32 v52, v192
	s_waitcnt vmcnt(26)
	ds_write_b32 v54, v193
	s_waitcnt vmcnt(25)
	ds_write_b32 v56, v194
	s_waitcnt vmcnt(24)
	ds_write_b32 v58, v195
	s_waitcnt vmcnt(23)
	ds_write_b32 v60, v196
	s_waitcnt vmcnt(22)
	ds_write_b32 v62, v197
	s_waitcnt vmcnt(21)
	ds_write_b32 v64, v198
	s_waitcnt vmcnt(20)
	ds_write_b32 v66, v199
	s_waitcnt vmcnt(19)
	ds_write_b32 v68, v200
	s_waitcnt vmcnt(18)
	ds_write_b32 v70, v201
	s_waitcnt vmcnt(17)
	ds_write_b32 v72, v202
	s_waitcnt vmcnt(16)
	ds_write_b32 v74, v203
	s_lshl_b32 s9, s3, 1
	s_lshl_b32 s10, s2, 1
	v_add_u32_e32 v44, s9, v2
	v_add_u32_e32 v46, s10, v1
	v_add_u32_e32 v50, s10, v3
	v_add_u32_e32 v48, s9, v10
	v_add_u32_e32 v54, s10, v5
	v_add_u32_e32 v52, s9, v12
	v_add_u32_e32 v58, s10, v11
	v_add_u32_e32 v56, s9, v14
	v_add_u32_e32 v62, s10, v13
	v_add_u32_e32 v60, s9, v16
	v_add_u32_e32 v66, s10, v15
	v_add_u32_e32 v64, s9, v18
	v_add_u32_e32 v70, s10, v17
	v_add_u32_e32 v68, s9, v20
	v_add_u32_e32 v74, s10, v19
	v_add_u32_e32 v72, s9, v22
	v_mad_u64_u32 v[44:45], s[22:23], v44, s95, v[4:5]
	v_mad_u64_u32 v[46:47], s[22:23], v46, s95, v[4:5]
	v_mad_u64_u32 v[48:49], s[22:23], v48, s95, v[4:5]
	v_mad_u64_u32 v[50:51], s[22:23], v50, s95, v[4:5]
	v_mad_u64_u32 v[52:53], s[22:23], v52, s95, v[4:5]
	v_mad_u64_u32 v[54:55], s[22:23], v54, s95, v[4:5]
	v_mad_u64_u32 v[56:57], s[22:23], v56, s95, v[4:5]
	v_mad_u64_u32 v[58:59], s[22:23], v58, s95, v[4:5]
	v_mad_u64_u32 v[60:61], s[22:23], v60, s95, v[4:5]
	v_mad_u64_u32 v[62:63], s[22:23], v62, s95, v[4:5]
	v_mad_u64_u32 v[64:65], s[22:23], v64, s95, v[4:5]
	v_mad_u64_u32 v[66:67], s[22:23], v66, s95, v[4:5]
	v_mad_u64_u32 v[68:69], s[22:23], v68, s95, v[4:5]
	v_mad_u64_u32 v[70:71], s[22:23], v70, s95, v[4:5]
	v_mad_u64_u32 v[72:73], s[22:23], v72, s95, v[4:5]
	v_mad_u64_u32 v[74:75], s[22:23], v74, s95, v[4:5]
	s_waitcnt vmcnt(15)
	ds_write_b32 v44, v204
	s_waitcnt vmcnt(14)
	ds_write_b32 v46, v205
	s_waitcnt vmcnt(13)
	ds_write_b32 v48, v206
	s_waitcnt vmcnt(12)
	ds_write_b32 v50, v207
	s_waitcnt vmcnt(11)
	ds_write_b32 v52, v208
	s_waitcnt vmcnt(10)
	ds_write_b32 v54, v209
	s_waitcnt vmcnt(9)
	ds_write_b32 v56, v210
	s_waitcnt vmcnt(8)
	ds_write_b32 v58, v211
	s_waitcnt vmcnt(7)
	ds_write_b32 v60, v212
	s_waitcnt vmcnt(6)
	ds_write_b32 v62, v213
	s_waitcnt vmcnt(5)
	ds_write_b32 v64, v214
	s_waitcnt vmcnt(4)
	ds_write_b32 v66, v215
	s_waitcnt vmcnt(3)
	ds_write_b32 v68, v216
	s_waitcnt vmcnt(2)
	ds_write_b32 v70, v217
	s_waitcnt vmcnt(1)
	ds_write_b32 v72, v218
	s_waitcnt vmcnt(0)
	ds_write_b32 v74, v219
	s_add_i32 s3, s3, 16
	s_add_i32 s2, s2, 16
	s_add_i32 s7, s7, -16
	s_add_i32 s7, s7, -16
	s_cmp_lg_u32 s7, 0
	s_waitcnt lgkmcnt(0)
	ds_read2_b32 v[28:29], v42 offset0:33 offset1:41
	ds_read2_b32 v[30:31], v42 offset1:8
	ds_read2_b32 v[32:33], v42 offset0:66 offset1:74
	ds_read2_b32 v[34:35], v42 offset0:99 offset1:107
	ds_read2_b32 v[36:37], v42 offset0:132 offset1:140
	ds_read2_b32 v[44:45], v42 offset0:165 offset1:173
	ds_read2_b32 v[46:47], v42 offset0:198 offset1:206
	ds_read2_b32 v[48:49], v42 offset0:231 offset1:239
	v_add_u32_e32 v52, s8, v41
	s_ashr_i32 s13, s12, 31
	v_ashrrev_i32_e32 v53, 31, v52
	v_lshl_add_u64 v[50:51], s[12:13], 1, v[8:9]
	v_lshlrev_b64 v[54:55], 12, v[52:53]
	s_waitcnt lgkmcnt(6)
	v_cvt_pk_bf16_f32 v24, v30, v28
	s_waitcnt lgkmcnt(4)
	v_cvt_pk_bf16_f32 v25, v32, v34
	s_waitcnt lgkmcnt(2)
	v_cvt_pk_bf16_f32 v26, v36, v44
	s_waitcnt lgkmcnt(0)
	v_cvt_pk_bf16_f32 v27, v46, v48
	v_lshl_add_u64 v[54:55], v[50:51], 0, v[54:55]
	v_add_u32_e32 v28, 8, v52
	global_store_dwordx4 v[54:55], v[24:27], off
	s_add_i32 s0, s0, s81
	s_cmpk_lt_i32 s0, 0xa00
	v_cvt_pk_bf16_f32 v24, v31, v29
	v_ashrrev_i32_e32 v29, 31, v28
	v_cvt_pk_bf16_f32 v25, v33, v35
	v_cvt_pk_bf16_f32 v26, v37, v45
	v_cvt_pk_bf16_f32 v27, v47, v49
	v_lshlrev_b64 v[28:29], 12, v[28:29]
	ds_read2_b32 v[30:31], v42 offset0:49 offset1:57
	ds_read2_b32 v[32:33], v42 offset0:16 offset1:24
	ds_read2_b32 v[34:35], v42 offset0:82 offset1:90
	ds_read2_b32 v[36:37], v42 offset0:115 offset1:123
	ds_read2_b32 v[44:45], v42 offset0:148 offset1:156
	ds_read2_b32 v[46:47], v42 offset0:181 offset1:189
	ds_read2_b32 v[48:49], v42 offset0:214 offset1:222
	ds_read2_b32 v[54:55], v42 offset0:247 offset1:255
	v_lshl_add_u64 v[28:29], v[50:51], 0, v[28:29]
	global_store_dwordx4 v[28:29], v[24:27], off
	v_add_u32_e32 v28, 16, v52
	v_ashrrev_i32_e32 v29, 31, v28
	v_lshlrev_b64 v[28:29], 12, v[28:29]
	s_waitcnt lgkmcnt(6)
	v_cvt_pk_bf16_f32 v24, v32, v30
	s_waitcnt lgkmcnt(4)
	v_cvt_pk_bf16_f32 v25, v34, v36
	s_waitcnt lgkmcnt(2)
	v_cvt_pk_bf16_f32 v26, v44, v46
	s_waitcnt lgkmcnt(0)
	v_cvt_pk_bf16_f32 v27, v48, v54
	v_lshl_add_u64 v[28:29], v[50:51], 0, v[28:29]
	global_store_dwordx4 v[28:29], v[24:27], off
	v_add_u32_e32 v28, 24, v52
	v_ashrrev_i32_e32 v29, 31, v28
	v_lshlrev_b64 v[28:29], 12, v[28:29]
	v_cvt_pk_bf16_f32 v24, v33, v31
	v_cvt_pk_bf16_f32 v25, v35, v37
	v_cvt_pk_bf16_f32 v26, v45, v47
	v_cvt_pk_bf16_f32 v27, v49, v55
	v_lshl_add_u64 v[28:29], v[50:51], 0, v[28:29]
	global_store_dwordx4 v[28:29], v[24:27], off
	s_waitcnt lgkmcnt(0)
	s_cbranch_scc1 .LBB0_115

.LBB0_121:
	s_lshl_b32 s9, s3, 1
	s_lshl_b32 s10, s2, 1
	s_mov_b32 s98, s9
	s_mov_b32 s99, s10
	v_add_u32_e32 v46, s9, v26
	v_add_u32_e32 v44, s10, v21
	v_add_u32_e32 v48, s10, v23
	v_add_u32_e32 v50, s9, v28
	v_add_u32_e32 v52, s10, v27
	v_add_u32_e32 v54, s9, v30
	v_add_u32_e32 v56, s10, v29
	v_add_u32_e32 v58, s9, v32
	v_add_u32_e32 v60, s10, v31
	v_add_u32_e32 v62, s9, v34
	v_add_u32_e32 v64, s10, v33
	v_add_u32_e32 v66, s9, v36
	v_add_u32_e32 v68, s10, v35
	v_add_u32_e32 v70, s9, v38
	v_add_u32_e32 v72, s10, v37
	v_add_u32_e32 v74, s9, v40
	v_ashrrev_i32_e32 v47, 31, v46
	v_ashrrev_i32_e32 v45, 31, v44
	v_ashrrev_i32_e32 v51, 31, v50
	v_ashrrev_i32_e32 v49, 31, v48
	v_ashrrev_i32_e32 v55, 31, v54
	v_ashrrev_i32_e32 v53, 31, v52
	v_ashrrev_i32_e32 v59, 31, v58
	v_ashrrev_i32_e32 v57, 31, v56
	v_ashrrev_i32_e32 v63, 31, v62
	v_ashrrev_i32_e32 v61, 31, v60
	v_ashrrev_i32_e32 v67, 31, v66
	v_ashrrev_i32_e32 v65, 31, v64
	v_ashrrev_i32_e32 v71, 31, v70
	v_ashrrev_i32_e32 v69, 31, v68
	v_ashrrev_i32_e32 v75, 31, v74
	v_ashrrev_i32_e32 v73, 31, v72
	v_lshlrev_b64 v[46:47], 13, v[46:47]
	v_lshlrev_b64 v[44:45], 13, v[44:45]
	v_lshlrev_b64 v[48:49], 13, v[48:49]
	v_lshlrev_b64 v[50:51], 13, v[50:51]
	v_lshlrev_b64 v[52:53], 13, v[52:53]
	v_lshlrev_b64 v[54:55], 13, v[54:55]
	v_lshlrev_b64 v[56:57], 13, v[56:57]
	v_lshlrev_b64 v[58:59], 13, v[58:59]
	v_lshlrev_b64 v[60:61], 13, v[60:61]
	v_lshlrev_b64 v[62:63], 13, v[62:63]
	v_lshlrev_b64 v[64:65], 13, v[64:65]
	v_lshlrev_b64 v[66:67], 13, v[66:67]
	v_lshlrev_b64 v[68:69], 13, v[68:69]
	v_lshlrev_b64 v[70:71], 13, v[70:71]
	v_lshlrev_b64 v[72:73], 13, v[72:73]
	v_lshlrev_b64 v[74:75], 13, v[74:75]
	v_lshl_add_u64 v[46:47], v[24:25], 0, v[46:47]
	v_lshl_add_u64 v[44:45], v[24:25], 0, v[44:45]
	v_lshl_add_u64 v[50:51], v[24:25], 0, v[50:51]
	v_lshl_add_u64 v[48:49], v[24:25], 0, v[48:49]
	v_lshl_add_u64 v[54:55], v[24:25], 0, v[54:55]
	v_lshl_add_u64 v[52:53], v[24:25], 0, v[52:53]
	v_lshl_add_u64 v[58:59], v[24:25], 0, v[58:59]
	v_lshl_add_u64 v[56:57], v[24:25], 0, v[56:57]
	v_lshl_add_u64 v[62:63], v[24:25], 0, v[62:63]
	v_lshl_add_u64 v[60:61], v[24:25], 0, v[60:61]
	v_lshl_add_u64 v[66:67], v[24:25], 0, v[66:67]
	v_lshl_add_u64 v[64:65], v[24:25], 0, v[64:65]
	v_lshl_add_u64 v[70:71], v[24:25], 0, v[70:71]
	v_lshl_add_u64 v[68:69], v[24:25], 0, v[68:69]
	v_lshl_add_u64 v[74:75], v[24:25], 0, v[74:75]
	v_lshl_add_u64 v[72:73], v[24:25], 0, v[72:73]
	global_load_dword v188, v[46:47], off
	global_load_dword v189, v[44:45], off
	global_load_dword v190, v[50:51], off
	global_load_dword v191, v[48:49], off
	global_load_dword v192, v[54:55], off
	global_load_dword v193, v[52:53], off
	global_load_dword v194, v[58:59], off
	global_load_dword v195, v[56:57], off
	global_load_dword v196, v[62:63], off
	global_load_dword v197, v[60:61], off
	global_load_dword v198, v[66:67], off
	global_load_dword v199, v[64:65], off
	global_load_dword v200, v[70:71], off
	global_load_dword v201, v[68:69], off
	global_load_dword v202, v[74:75], off
	global_load_dword v203, v[72:73], off
	s_add_i32 s3, s3, 16
	s_add_i32 s2, s2, 16
	s_lshl_b32 s9, s3, 1
	s_lshl_b32 s10, s2, 1
	v_add_u32_e32 v46, s9, v26
	v_add_u32_e32 v44, s10, v21
	v_add_u32_e32 v48, s10, v23
	v_add_u32_e32 v50, s9, v28
	v_add_u32_e32 v52, s10, v27
	v_add_u32_e32 v54, s9, v30
	v_add_u32_e32 v56, s10, v29
	v_add_u32_e32 v58, s9, v32
	v_add_u32_e32 v60, s10, v31
	v_add_u32_e32 v62, s9, v34
	v_add_u32_e32 v64, s10, v33
	v_add_u32_e32 v66, s9, v36
	v_add_u32_e32 v68, s10, v35
	v_add_u32_e32 v70, s9, v38
	v_add_u32_e32 v72, s10, v37
	v_add_u32_e32 v74, s9, v40
	v_ashrrev_i32_e32 v47, 31, v46
	v_ashrrev_i32_e32 v45, 31, v44
	v_ashrrev_i32_e32 v51, 31, v50
	v_ashrrev_i32_e32 v49, 31, v48
	v_ashrrev_i32_e32 v55, 31, v54
	v_ashrrev_i32_e32 v53, 31, v52
	v_ashrrev_i32_e32 v59, 31, v58
	v_ashrrev_i32_e32 v57, 31, v56
	v_ashrrev_i32_e32 v63, 31, v62
	v_ashrrev_i32_e32 v61, 31, v60
	v_ashrrev_i32_e32 v67, 31, v66
	v_ashrrev_i32_e32 v65, 31, v64
	v_ashrrev_i32_e32 v71, 31, v70
	v_ashrrev_i32_e32 v69, 31, v68
	v_ashrrev_i32_e32 v75, 31, v74
	v_ashrrev_i32_e32 v73, 31, v72
	v_lshlrev_b64 v[46:47], 13, v[46:47]
	v_lshlrev_b64 v[44:45], 13, v[44:45]
	v_lshlrev_b64 v[48:49], 13, v[48:49]
	v_lshlrev_b64 v[50:51], 13, v[50:51]
	v_lshlrev_b64 v[52:53], 13, v[52:53]
	v_lshlrev_b64 v[54:55], 13, v[54:55]
	v_lshlrev_b64 v[56:57], 13, v[56:57]
	v_lshlrev_b64 v[58:59], 13, v[58:59]
	v_lshlrev_b64 v[60:61], 13, v[60:61]
	v_lshlrev_b64 v[62:63], 13, v[62:63]
	v_lshlrev_b64 v[64:65], 13, v[64:65]
	v_lshlrev_b64 v[66:67], 13, v[66:67]
	v_lshlrev_b64 v[68:69], 13, v[68:69]
	v_lshlrev_b64 v[70:71], 13, v[70:71]
	v_lshlrev_b64 v[72:73], 13, v[72:73]
	v_lshlrev_b64 v[74:75], 13, v[74:75]
	v_lshl_add_u64 v[46:47], v[24:25], 0, v[46:47]
	v_lshl_add_u64 v[44:45], v[24:25], 0, v[44:45]
	v_lshl_add_u64 v[50:51], v[24:25], 0, v[50:51]
	v_lshl_add_u64 v[48:49], v[24:25], 0, v[48:49]
	v_lshl_add_u64 v[54:55], v[24:25], 0, v[54:55]
	v_lshl_add_u64 v[52:53], v[24:25], 0, v[52:53]
	v_lshl_add_u64 v[58:59], v[24:25], 0, v[58:59]
	v_lshl_add_u64 v[56:57], v[24:25], 0, v[56:57]
	v_lshl_add_u64 v[62:63], v[24:25], 0, v[62:63]
	v_lshl_add_u64 v[60:61], v[24:25], 0, v[60:61]
	v_lshl_add_u64 v[66:67], v[24:25], 0, v[66:67]
	v_lshl_add_u64 v[64:65], v[24:25], 0, v[64:65]
	v_lshl_add_u64 v[70:71], v[24:25], 0, v[70:71]
	v_lshl_add_u64 v[68:69], v[24:25], 0, v[68:69]
	v_lshl_add_u64 v[74:75], v[24:25], 0, v[74:75]
	v_lshl_add_u64 v[72:73], v[24:25], 0, v[72:73]
	global_load_dword v204, v[46:47], off
	global_load_dword v205, v[44:45], off
	global_load_dword v206, v[50:51], off
	global_load_dword v207, v[48:49], off
	global_load_dword v208, v[54:55], off
	global_load_dword v209, v[52:53], off
	global_load_dword v210, v[58:59], off
	global_load_dword v211, v[56:57], off
	global_load_dword v212, v[62:63], off
	global_load_dword v213, v[60:61], off
	global_load_dword v214, v[66:67], off
	global_load_dword v215, v[64:65], off
	global_load_dword v216, v[70:71], off
	global_load_dword v217, v[68:69], off
	global_load_dword v218, v[74:75], off
	global_load_dword v219, v[72:73], off
	s_mov_b32 s9, s98
	s_mov_b32 s10, s99
	v_add_u32_e32 v44, s9, v2
	v_add_u32_e32 v46, s10, v1
	v_add_u32_e32 v50, s10, v3
	v_add_u32_e32 v48, s9, v10
	v_add_u32_e32 v54, s10, v5
	v_add_u32_e32 v52, s9, v12
	v_add_u32_e32 v58, s10, v11
	v_add_u32_e32 v56, s9, v14
	v_add_u32_e32 v62, s10, v13
	v_add_u32_e32 v60, s9, v16
	v_add_u32_e32 v66, s10, v15
	v_add_u32_e32 v64, s9, v18
	v_add_u32_e32 v70, s10, v17
	v_add_u32_e32 v68, s9, v20
	v_add_u32_e32 v74, s10, v19
	v_add_u32_e32 v72, s9, v22
	v_mad_u64_u32 v[44:45], s[22:23], v44, s95, v[4:5]
	v_mad_u64_u32 v[46:47], s[22:23], v46, s95, v[4:5]
	v_mad_u64_u32 v[48:49], s[22:23], v48, s95, v[4:5]
	v_mad_u64_u32 v[50:51], s[22:23], v50, s95, v[4:5]
	v_mad_u64_u32 v[52:53], s[22:23], v52, s95, v[4:5]
	v_mad_u64_u32 v[54:55], s[22:23], v54, s95, v[4:5]
	v_mad_u64_u32 v[56:57], s[22:23], v56, s95, v[4:5]
	v_mad_u64_u32 v[58:59], s[22:23], v58, s95, v[4:5]
	v_mad_u64_u32 v[60:61], s[22:23], v60, s95, v[4:5]
	v_mad_u64_u32 v[62:63], s[22:23], v62, s95, v[4:5]
	v_mad_u64_u32 v[64:65], s[22:23], v64, s95, v[4:5]
	v_mad_u64_u32 v[66:67], s[22:23], v66, s95, v[4:5]
	v_mad_u64_u32 v[68:69], s[22:23], v68, s95, v[4:5]
	v_mad_u64_u32 v[70:71], s[22:23], v70, s95, v[4:5]
	v_mad_u64_u32 v[72:73], s[22:23], v72, s95, v[4:5]
	v_mad_u64_u32 v[74:75], s[22:23], v74, s95, v[4:5]
	s_waitcnt vmcnt(31)
	ds_write_b32 v44, v188
	s_waitcnt vmcnt(30)
	ds_write_b32 v46, v189
	s_waitcnt vmcnt(29)
	ds_write_b32 v48, v190
	s_waitcnt vmcnt(28)
	ds_write_b32 v50, v191
	s_waitcnt vmcnt(27)
	ds_write_b32 v52, v192
	s_waitcnt vmcnt(26)
	ds_write_b32 v54, v193
	s_waitcnt vmcnt(25)
	ds_write_b32 v56, v194
	s_waitcnt vmcnt(24)
	ds_write_b32 v58, v195
	s_waitcnt vmcnt(23)
	ds_write_b32 v60, v196
	s_waitcnt vmcnt(22)
	ds_write_b32 v62, v197
	s_waitcnt vmcnt(21)
	ds_write_b32 v64, v198
	s_waitcnt vmcnt(20)
	ds_write_b32 v66, v199
	s_waitcnt vmcnt(19)
	ds_write_b32 v68, v200
	s_waitcnt vmcnt(18)
	ds_write_b32 v70, v201
	s_waitcnt vmcnt(17)
	ds_write_b32 v72, v202
	s_waitcnt vmcnt(16)
	ds_write_b32 v74, v203
	s_lshl_b32 s9, s3, 1
	s_lshl_b32 s10, s2, 1
	v_add_u32_e32 v44, s9, v2
	v_add_u32_e32 v46, s10, v1
	v_add_u32_e32 v50, s10, v3
	v_add_u32_e32 v48, s9, v10
	v_add_u32_e32 v54, s10, v5
	v_add_u32_e32 v52, s9, v12
	v_add_u32_e32 v58, s10, v11
	v_add_u32_e32 v56, s9, v14
	v_add_u32_e32 v62, s10, v13
	v_add_u32_e32 v60, s9, v16
	v_add_u32_e32 v66, s10, v15
	v_add_u32_e32 v64, s9, v18
	v_add_u32_e32 v70, s10, v17
	v_add_u32_e32 v68, s9, v20
	v_add_u32_e32 v74, s10, v19
	v_add_u32_e32 v72, s9, v22
	v_mad_u64_u32 v[44:45], s[22:23], v44, s95, v[4:5]
	v_mad_u64_u32 v[46:47], s[22:23], v46, s95, v[4:5]
	v_mad_u64_u32 v[48:49], s[22:23], v48, s95, v[4:5]
	v_mad_u64_u32 v[50:51], s[22:23], v50, s95, v[4:5]
	v_mad_u64_u32 v[52:53], s[22:23], v52, s95, v[4:5]
	v_mad_u64_u32 v[54:55], s[22:23], v54, s95, v[4:5]
	v_mad_u64_u32 v[56:57], s[22:23], v56, s95, v[4:5]
	v_mad_u64_u32 v[58:59], s[22:23], v58, s95, v[4:5]
	v_mad_u64_u32 v[60:61], s[22:23], v60, s95, v[4:5]
	v_mad_u64_u32 v[62:63], s[22:23], v62, s95, v[4:5]
	v_mad_u64_u32 v[64:65], s[22:23], v64, s95, v[4:5]
	v_mad_u64_u32 v[66:67], s[22:23], v66, s95, v[4:5]
	v_mad_u64_u32 v[68:69], s[22:23], v68, s95, v[4:5]
	v_mad_u64_u32 v[70:71], s[22:23], v70, s95, v[4:5]
	v_mad_u64_u32 v[72:73], s[22:23], v72, s95, v[4:5]
	v_mad_u64_u32 v[74:75], s[22:23], v74, s95, v[4:5]
	s_waitcnt vmcnt(15)
	ds_write_b32 v44, v204
	s_waitcnt vmcnt(14)
	ds_write_b32 v46, v205
	s_waitcnt vmcnt(13)
	ds_write_b32 v48, v206
	s_waitcnt vmcnt(12)
	ds_write_b32 v50, v207
	s_waitcnt vmcnt(11)
	ds_write_b32 v52, v208
	s_waitcnt vmcnt(10)
	ds_write_b32 v54, v209
	s_waitcnt vmcnt(9)
	ds_write_b32 v56, v210
	s_waitcnt vmcnt(8)
	ds_write_b32 v58, v211
	s_waitcnt vmcnt(7)
	ds_write_b32 v60, v212
	s_waitcnt vmcnt(6)
	ds_write_b32 v62, v213
	s_waitcnt vmcnt(5)
	ds_write_b32 v64, v214
	s_waitcnt vmcnt(4)
	ds_write_b32 v66, v215
	s_waitcnt vmcnt(3)
	ds_write_b32 v68, v216
	s_waitcnt vmcnt(2)
	ds_write_b32 v70, v217
	s_waitcnt vmcnt(1)
	ds_write_b32 v72, v218
	s_waitcnt vmcnt(0)
	ds_write_b32 v74, v219
	s_add_i32 s3, s3, 16
	s_add_i32 s2, s2, 16
	s_add_i32 s7, s7, -16
	s_add_i32 s7, s7, -16
	s_cmp_lg_u32 s7, 0
	s_waitcnt lgkmcnt(0)
	ds_read2_b32 v[28:29], v42 offset0:33 offset1:41
	ds_read2_b32 v[30:31], v42 offset1:8
	ds_read2_b32 v[32:33], v42 offset0:66 offset1:74
	ds_read2_b32 v[34:35], v42 offset0:99 offset1:107
	ds_read2_b32 v[36:37], v42 offset0:132 offset1:140
	ds_read2_b32 v[44:45], v42 offset0:165 offset1:173
	ds_read2_b32 v[46:47], v42 offset0:198 offset1:206
	ds_read2_b32 v[48:49], v42 offset0:231 offset1:239
	v_add_u32_e32 v52, s8, v41
	s_ashr_i32 s13, s12, 31
	v_ashrrev_i32_e32 v53, 31, v52
	v_lshl_add_u64 v[50:51], s[12:13], 1, v[8:9]
	v_lshlrev_b64 v[54:55], 12, v[52:53]
	s_waitcnt lgkmcnt(6)
	v_cvt_pk_bf16_f32 v24, v30, v28
	s_waitcnt lgkmcnt(4)
	v_cvt_pk_bf16_f32 v25, v32, v34
	s_waitcnt lgkmcnt(2)
	v_cvt_pk_bf16_f32 v26, v36, v44
	s_waitcnt lgkmcnt(0)
	v_cvt_pk_bf16_f32 v27, v46, v48
	v_lshl_add_u64 v[54:55], v[50:51], 0, v[54:55]
	v_add_u32_e32 v28, 8, v52
	global_store_dwordx4 v[54:55], v[24:27], off
	s_add_i32 s0, s0, s81
	s_cmpk_gt_i32 s0, 0x7ff
	v_cvt_pk_bf16_f32 v24, v31, v29
	v_ashrrev_i32_e32 v29, 31, v28
	v_cvt_pk_bf16_f32 v25, v33, v35
	v_cvt_pk_bf16_f32 v26, v37, v45
	v_cvt_pk_bf16_f32 v27, v47, v49
	v_lshlrev_b64 v[28:29], 12, v[28:29]
	ds_read2_b32 v[30:31], v42 offset0:49 offset1:57
	ds_read2_b32 v[32:33], v42 offset0:16 offset1:24
	ds_read2_b32 v[34:35], v42 offset0:82 offset1:90
	ds_read2_b32 v[36:37], v42 offset0:115 offset1:123
	ds_read2_b32 v[44:45], v42 offset0:148 offset1:156
	ds_read2_b32 v[46:47], v42 offset0:181 offset1:189
	ds_read2_b32 v[48:49], v42 offset0:214 offset1:222
	ds_read2_b32 v[54:55], v42 offset0:247 offset1:255
	v_lshl_add_u64 v[28:29], v[50:51], 0, v[28:29]
	global_store_dwordx4 v[28:29], v[24:27], off
	v_add_u32_e32 v28, 16, v52
	v_ashrrev_i32_e32 v29, 31, v28
	v_lshlrev_b64 v[28:29], 12, v[28:29]
	s_waitcnt lgkmcnt(6)
	v_cvt_pk_bf16_f32 v24, v32, v30
	s_waitcnt lgkmcnt(4)
	v_cvt_pk_bf16_f32 v25, v34, v36
	s_waitcnt lgkmcnt(2)
	v_cvt_pk_bf16_f32 v26, v44, v46
	s_waitcnt lgkmcnt(0)
	v_cvt_pk_bf16_f32 v27, v48, v54
	v_lshl_add_u64 v[28:29], v[50:51], 0, v[28:29]
	global_store_dwordx4 v[28:29], v[24:27], off
	v_add_u32_e32 v28, 24, v52
	v_ashrrev_i32_e32 v29, 31, v28
	v_lshlrev_b64 v[28:29], 12, v[28:29]
	v_cvt_pk_bf16_f32 v24, v33, v31
	v_cvt_pk_bf16_f32 v25, v35, v37
	v_cvt_pk_bf16_f32 v26, v45, v47
	v_cvt_pk_bf16_f32 v27, v49, v55
	v_lshl_add_u64 v[28:29], v[50:51], 0, v[28:29]
	global_store_dwordx4 v[28:29], v[24:27], off
	s_waitcnt lgkmcnt(0)
	s_cbranch_scc0 .LBB0_120

.LBB0_128:
	s_lshl_b32 s9, s3, 1
	s_lshl_b32 s10, s2, 1
	s_mov_b32 s98, s9
	s_mov_b32 s99, s10
	v_add_u32_e32 v48, s9, v28
	v_add_u32_e32 v47, s10, v19
	v_mad_i64_i32 v[48:49], s[26:27], v48, s14, v[26:27]
	v_add_u32_e32 v52, s9, v30
	v_add_u32_e32 v65, s9, v36
	v_mad_i64_i32 v[50:51], s[26:27], v47, s14, v[26:27]
	global_load_dword v188, v[48:49], off
	v_add_u32_e32 v54, s10, v21
	v_add_u32_e32 v64, s10, v31
	v_mad_i64_i32 v[52:53], s[26:27], v52, s14, v[26:27]
	v_mad_i64_i32 v[48:49], s[26:27], v65, s14, v[26:27]
	global_load_dword v189, v[50:51], off
	v_add_u32_e32 v56, s9, v32
	v_add_u32_e32 v67, s9, v38
	v_mad_i64_i32 v[54:55], s[26:27], v54, s14, v[26:27]
	v_mad_i64_i32 v[50:51], s[26:27], v64, s14, v[26:27]
	global_load_dword v190, v[52:53], off
	v_add_u32_e32 v58, s10, v23
	v_add_u32_e32 v66, s10, v33
	v_mad_i64_i32 v[56:57], s[26:27], v56, s14, v[26:27]
	v_mad_i64_i32 v[52:53], s[26:27], v67, s14, v[26:27]
	global_load_dword v191, v[54:55], off
	v_add_u32_e32 v62, s10, v29
	v_add_u32_e32 v60, s9, v34
	v_add_u32_e32 v69, s9, v40
	v_mad_i64_i32 v[58:59], s[26:27], v58, s14, v[26:27]
	v_mad_i64_i32 v[54:55], s[26:27], v66, s14, v[26:27]
	global_load_dword v192, v[56:57], off
	v_add_u32_e32 v68, s10, v35
	v_add_u32_e32 v70, s10, v37
	v_add_u32_e32 v71, s9, v42
	v_mad_i64_i32 v[60:61], s[26:27], v60, s14, v[26:27]
	v_mad_i64_i32 v[62:63], s[26:27], v62, s14, v[26:27]
	v_mad_i64_i32 v[56:57], s[26:27], v69, s14, v[26:27]
	global_load_dword v193, v[58:59], off
	v_mad_i64_i32 v[58:59], s[26:27], v68, s14, v[26:27]
	global_load_dword v194, v[60:61], off
	v_mad_i64_i32 v[60:61], s[26:27], v71, s14, v[26:27]
	global_load_dword v195, v[62:63], off
	v_mad_i64_i32 v[62:63], s[26:27], v70, s14, v[26:27]
	global_load_dword v196, v[48:49], off
	global_load_dword v197, v[50:51], off
	global_load_dword v198, v[52:53], off
	global_load_dword v199, v[54:55], off
	global_load_dword v200, v[56:57], off
	global_load_dword v201, v[58:59], off
	global_load_dword v202, v[60:61], off
	global_load_dword v203, v[62:63], off
	s_add_i32 s3, s3, 16
	s_add_i32 s2, s2, 16
	s_lshl_b32 s9, s3, 1
	s_lshl_b32 s10, s2, 1
	v_add_u32_e32 v48, s9, v28
	v_add_u32_e32 v47, s10, v19
	v_mad_i64_i32 v[48:49], s[26:27], v48, s14, v[26:27]
	v_add_u32_e32 v52, s9, v30
	v_add_u32_e32 v65, s9, v36
	v_mad_i64_i32 v[50:51], s[26:27], v47, s14, v[26:27]
	global_load_dword v204, v[48:49], off
	v_add_u32_e32 v54, s10, v21
	v_add_u32_e32 v64, s10, v31
	v_mad_i64_i32 v[52:53], s[26:27], v52, s14, v[26:27]
	v_mad_i64_i32 v[48:49], s[26:27], v65, s14, v[26:27]
	global_load_dword v205, v[50:51], off
	v_add_u32_e32 v56, s9, v32
	v_add_u32_e32 v67, s9, v38
	v_mad_i64_i32 v[54:55], s[26:27], v54, s14, v[26:27]
	v_mad_i64_i32 v[50:51], s[26:27], v64, s14, v[26:27]
	global_load_dword v206, v[52:53], off
	v_add_u32_e32 v58, s10, v23
	v_add_u32_e32 v66, s10, v33
	v_mad_i64_i32 v[56:57], s[26:27], v56, s14, v[26:27]
	v_mad_i64_i32 v[52:53], s[26:27], v67, s14, v[26:27]
	global_load_dword v207, v[54:55], off
	v_add_u32_e32 v62, s10, v29
	v_add_u32_e32 v60, s9, v34
	v_add_u32_e32 v69, s9, v40
	v_mad_i64_i32 v[58:59], s[26:27], v58, s14, v[26:27]
	v_mad_i64_i32 v[54:55], s[26:27], v66, s14, v[26:27]
	global_load_dword v208, v[56:57], off
	v_add_u32_e32 v68, s10, v35
	v_add_u32_e32 v70, s10, v37
	v_add_u32_e32 v71, s9, v42
	v_mad_i64_i32 v[60:61], s[26:27], v60, s14, v[26:27]
	v_mad_i64_i32 v[62:63], s[26:27], v62, s14, v[26:27]
	v_mad_i64_i32 v[56:57], s[26:27], v69, s14, v[26:27]
	global_load_dword v209, v[58:59], off
	v_mad_i64_i32 v[58:59], s[26:27], v68, s14, v[26:27]
	global_load_dword v210, v[60:61], off
	v_mad_i64_i32 v[60:61], s[26:27], v71, s14, v[26:27]
	global_load_dword v211, v[62:63], off
	v_mad_i64_i32 v[62:63], s[26:27], v70, s14, v[26:27]
	global_load_dword v212, v[48:49], off
	global_load_dword v213, v[50:51], off
	global_load_dword v214, v[52:53], off
	global_load_dword v215, v[54:55], off
	global_load_dword v216, v[56:57], off
	global_load_dword v217, v[58:59], off
	global_load_dword v218, v[60:61], off
	global_load_dword v219, v[62:63], off
	s_mov_b32 s9, s98
	s_mov_b32 s10, s99
	v_add_u32_e32 v48, s9, v4
	v_add_u32_e32 v50, s10, v1
	v_mad_u64_u32 v[48:49], s[26:27], v48, s95, v[6:7]
	v_add_u32_e32 v52, s9, v10
	v_add_u32_e32 v51, s10, v3
	v_add_u32_e32 v54, s9, v12
	v_add_u32_e32 v53, s10, v5
	v_add_u32_e32 v55, s10, v7
	v_add_u32_e32 v57, s9, v16
	v_add_u32_e32 v56, s10, v11
	v_add_u32_e32 v58, s10, v13
	v_add_u32_e32 v59, s9, v18
	v_add_u32_e32 v60, s10, v15
	v_add_u32_e32 v61, s9, v20
	v_add_u32_e32 v62, s10, v17
	v_add_u32_e32 v63, s9, v22
	s_waitcnt vmcnt(31)
	ds_write_b32 v48, v188
	v_mad_u64_u32 v[48:49], s[26:27], v50, s95, v[6:7]
	v_add_u32_e32 v47, s9, v14
	s_waitcnt vmcnt(30)
	ds_write_b32 v48, v189
	v_mad_u64_u32 v[48:49], s[26:27], v52, s95, v[6:7]
	s_waitcnt vmcnt(29)
	ds_write_b32 v48, v190
	v_mad_u64_u32 v[48:49], s[26:27], v51, s95, v[6:7]
	v_mad_u64_u32 v[50:51], s[26:27], v47, s95, v[6:7]
	s_waitcnt vmcnt(28)
	ds_write_b32 v48, v191
	v_mad_u64_u32 v[48:49], s[26:27], v54, s95, v[6:7]
	s_waitcnt vmcnt(27)
	ds_write_b32 v48, v192
	v_mad_u64_u32 v[48:49], s[26:27], v53, s95, v[6:7]
	v_mad_u64_u32 v[52:53], s[26:27], v57, s95, v[6:7]
	s_waitcnt vmcnt(26)
	ds_write_b32 v48, v193
	v_mad_u64_u32 v[48:49], s[26:27], v55, s95, v[6:7]
	v_mad_u64_u32 v[54:55], s[26:27], v56, s95, v[6:7]
	s_waitcnt vmcnt(25)
	ds_write_b32 v50, v194
	v_mad_u64_u32 v[50:51], s[26:27], v59, s95, v[6:7]
	v_mad_u64_u32 v[56:57], s[26:27], v58, s95, v[6:7]
	v_mad_u64_u32 v[58:59], s[26:27], v61, s95, v[6:7]
	s_waitcnt vmcnt(24)
	ds_write_b32 v48, v195
	v_mad_u64_u32 v[48:49], s[26:27], v60, s95, v[6:7]
	v_mad_u64_u32 v[60:61], s[26:27], v63, s95, v[6:7]
	v_mad_u64_u32 v[62:63], s[26:27], v62, s95, v[6:7]
	s_waitcnt vmcnt(23)
	ds_write_b32 v52, v196
	s_waitcnt vmcnt(22)
	ds_write_b32 v54, v197
	s_waitcnt vmcnt(21)
	ds_write_b32 v50, v198
	s_waitcnt vmcnt(20)
	ds_write_b32 v56, v199
	s_waitcnt vmcnt(19)
	ds_write_b32 v58, v200
	s_waitcnt vmcnt(18)
	ds_write_b32 v48, v201
	s_waitcnt vmcnt(17)
	ds_write_b32 v60, v202
	s_waitcnt vmcnt(16)
	ds_write_b32 v62, v203
	s_lshl_b32 s9, s3, 1
	s_lshl_b32 s10, s2, 1
	v_add_u32_e32 v48, s9, v4
	v_add_u32_e32 v50, s10, v1
	v_mad_u64_u32 v[48:49], s[26:27], v48, s95, v[6:7]
	v_add_u32_e32 v52, s9, v10
	v_add_u32_e32 v51, s10, v3
	v_add_u32_e32 v54, s9, v12
	v_add_u32_e32 v53, s10, v5
	v_add_u32_e32 v55, s10, v7
	v_add_u32_e32 v57, s9, v16
	v_add_u32_e32 v56, s10, v11
	v_add_u32_e32 v58, s10, v13
	v_add_u32_e32 v59, s9, v18
	v_add_u32_e32 v60, s10, v15
	v_add_u32_e32 v61, s9, v20
	v_add_u32_e32 v62, s10, v17
	v_add_u32_e32 v63, s9, v22
	s_waitcnt vmcnt(15)
	ds_write_b32 v48, v204
	v_mad_u64_u32 v[48:49], s[26:27], v50, s95, v[6:7]
	v_add_u32_e32 v47, s9, v14
	s_waitcnt vmcnt(14)
	ds_write_b32 v48, v205
	v_mad_u64_u32 v[48:49], s[26:27], v52, s95, v[6:7]
	s_waitcnt vmcnt(13)
	ds_write_b32 v48, v206
	v_mad_u64_u32 v[48:49], s[26:27], v51, s95, v[6:7]
	v_mad_u64_u32 v[50:51], s[26:27], v47, s95, v[6:7]
	s_waitcnt vmcnt(12)
	ds_write_b32 v48, v207
	v_mad_u64_u32 v[48:49], s[26:27], v54, s95, v[6:7]
	s_waitcnt vmcnt(11)
	ds_write_b32 v48, v208
	v_mad_u64_u32 v[48:49], s[26:27], v53, s95, v[6:7]
	v_mad_u64_u32 v[52:53], s[26:27], v57, s95, v[6:7]
	s_waitcnt vmcnt(10)
	ds_write_b32 v48, v209
	v_mad_u64_u32 v[48:49], s[26:27], v55, s95, v[6:7]
	v_mad_u64_u32 v[54:55], s[26:27], v56, s95, v[6:7]
	s_waitcnt vmcnt(9)
	ds_write_b32 v50, v210
	v_mad_u64_u32 v[50:51], s[26:27], v59, s95, v[6:7]
	v_mad_u64_u32 v[56:57], s[26:27], v58, s95, v[6:7]
	v_mad_u64_u32 v[58:59], s[26:27], v61, s95, v[6:7]
	s_waitcnt vmcnt(8)
	ds_write_b32 v48, v211
	v_mad_u64_u32 v[48:49], s[26:27], v60, s95, v[6:7]
	v_mad_u64_u32 v[60:61], s[26:27], v63, s95, v[6:7]
	v_mad_u64_u32 v[62:63], s[26:27], v62, s95, v[6:7]
	s_waitcnt vmcnt(7)
	ds_write_b32 v52, v212
	s_waitcnt vmcnt(6)
	ds_write_b32 v54, v213
	s_waitcnt vmcnt(5)
	ds_write_b32 v50, v214
	s_waitcnt vmcnt(4)
	ds_write_b32 v56, v215
	s_waitcnt vmcnt(3)
	ds_write_b32 v58, v216
	s_waitcnt vmcnt(2)
	ds_write_b32 v48, v217
	s_waitcnt vmcnt(1)
	ds_write_b32 v60, v218
	s_waitcnt vmcnt(0)
	ds_write_b32 v62, v219
	s_add_i32 s3, s3, 16
	s_add_i32 s2, s2, 16
	s_add_i32 s7, s7, -16
	s_add_i32 s7, s7, -16
	s_cmp_lg_u32 s7, 0
	s_waitcnt lgkmcnt(0)
	ds_read2_b32 v[30:31], v43 offset0:33 offset1:41
	ds_read2_b32 v[32:33], v43 offset1:8
	ds_read2_b32 v[34:35], v43 offset0:66 offset1:74
	ds_read2_b32 v[36:37], v43 offset0:99 offset1:107
	ds_read2_b32 v[48:49], v43 offset0:132 offset1:140
	ds_read2_b32 v[50:51], v43 offset0:165 offset1:173
	ds_read2_b32 v[52:53], v43 offset0:198 offset1:206
	ds_read2_b32 v[54:55], v43 offset0:231 offset1:239
	v_add_u32_e32 v58, s8, v41
	s_ashr_i32 s13, s12, 31
	v_ashrrev_i32_e32 v59, 31, v58
	v_lshl_add_u64 v[56:57], s[12:13], 1, v[8:9]
	v_lshlrev_b64 v[58:59], 12, v[58:59]
	s_waitcnt lgkmcnt(6)
	v_cvt_pk_bf16_f32 v26, v32, v30
	s_waitcnt lgkmcnt(4)
	v_cvt_pk_bf16_f32 v27, v34, v36
	s_waitcnt lgkmcnt(2)
	v_cvt_pk_bf16_f32 v28, v48, v50
	s_waitcnt lgkmcnt(0)
	v_cvt_pk_bf16_f32 v29, v52, v54
	v_lshl_add_u64 v[58:59], v[56:57], 0, v[58:59]
	v_add_u32_e32 v30, s8, v44
	global_store_dwordx4 v[58:59], v[26:29], off
	s_add_i32 s0, s0, s81
	s_cmpk_lt_i32 s0, 0x800
	v_cvt_pk_bf16_f32 v26, v33, v31
	v_ashrrev_i32_e32 v31, 31, v30
	v_cvt_pk_bf16_f32 v27, v35, v37
	v_cvt_pk_bf16_f32 v28, v49, v51
	v_cvt_pk_bf16_f32 v29, v53, v55
	v_lshlrev_b64 v[30:31], 12, v[30:31]
	ds_read2_b32 v[32:33], v43 offset0:49 offset1:57
	ds_read2_b32 v[34:35], v43 offset0:16 offset1:24
	ds_read2_b32 v[36:37], v43 offset0:82 offset1:90
	ds_read2_b32 v[48:49], v43 offset0:115 offset1:123
	ds_read2_b32 v[50:51], v43 offset0:148 offset1:156
	ds_read2_b32 v[52:53], v43 offset0:181 offset1:189
	ds_read2_b32 v[54:55], v43 offset0:214 offset1:222
	ds_read2_b32 v[58:59], v43 offset0:247 offset1:255
	v_lshl_add_u64 v[30:31], v[56:57], 0, v[30:31]
	global_store_dwordx4 v[30:31], v[26:29], off
	v_add_u32_e32 v30, s8, v45
	v_ashrrev_i32_e32 v31, 31, v30
	v_lshlrev_b64 v[30:31], 12, v[30:31]
	s_waitcnt lgkmcnt(6)
	v_cvt_pk_bf16_f32 v26, v34, v32
	s_waitcnt lgkmcnt(4)
	v_cvt_pk_bf16_f32 v27, v36, v48
	s_waitcnt lgkmcnt(2)
	v_cvt_pk_bf16_f32 v28, v50, v52
	s_waitcnt lgkmcnt(0)
	v_cvt_pk_bf16_f32 v29, v54, v58
	v_lshl_add_u64 v[30:31], v[56:57], 0, v[30:31]
	global_store_dwordx4 v[30:31], v[26:29], off
	v_add_u32_e32 v30, s8, v46
	v_ashrrev_i32_e32 v31, 31, v30
	v_lshlrev_b64 v[30:31], 12, v[30:31]
	v_cvt_pk_bf16_f32 v26, v35, v33
	v_cvt_pk_bf16_f32 v27, v37, v49
	v_cvt_pk_bf16_f32 v28, v51, v53
	v_cvt_pk_bf16_f32 v29, v55, v59
	v_lshl_add_u64 v[30:31], v[56:57], 0, v[30:31]
	global_store_dwordx4 v[30:31], v[26:29], off
	s_waitcnt lgkmcnt(0)
	s_cbranch_scc1 .LBB0_127
	v_lshlrev_b32_e32 v24, 2, v2
	v_mov_b32_e32 v25, v225
	v_lshl_add_u64 v[24:25], s[22:23], 0, v[24:25]
	s_mov_b64 s[2:3], 0x2000
	v_lshl_add_u64 v[24:25], v[24:25], 0, s[2:3]
	s_mov_b32 s0, s53

.LBB0_132:
	s_lshl_b32 s9, s3, 1
	s_lshl_b32 s10, s2, 1
	s_mov_b32 s98, s9
	s_mov_b32 s99, s10
	v_add_u32_e32 v48, s9, v28
	v_add_u32_e32 v47, s10, v19
	v_add_u32_e32 v54, s10, v21
	v_add_u32_e32 v52, s9, v30
	v_add_u32_e32 v58, s10, v23
	v_add_u32_e32 v56, s9, v32
	v_add_u32_e32 v62, s10, v29
	v_add_u32_e32 v60, s9, v34
	v_add_u32_e32 v66, s10, v31
	v_add_u32_e32 v64, s9, v36
	v_add_u32_e32 v70, s10, v33
	v_add_u32_e32 v68, s9, v38
	v_add_u32_e32 v74, s10, v35
	v_add_u32_e32 v72, s9, v40
	v_add_u32_e32 v78, s10, v37
	v_add_u32_e32 v76, s9, v42
	v_mad_i64_i32 v[48:49], s[26:27], v48, s14, v[26:27]
	v_mad_i64_i32 v[50:51], s[26:27], v47, s14, v[26:27]
	v_mad_i64_i32 v[52:53], s[26:27], v52, s14, v[26:27]
	v_mad_i64_i32 v[54:55], s[26:27], v54, s14, v[26:27]
	v_mad_i64_i32 v[56:57], s[26:27], v56, s14, v[26:27]
	v_mad_i64_i32 v[58:59], s[26:27], v58, s14, v[26:27]
	v_mad_i64_i32 v[60:61], s[26:27], v60, s14, v[26:27]
	v_mad_i64_i32 v[62:63], s[26:27], v62, s14, v[26:27]
	v_mad_i64_i32 v[64:65], s[26:27], v64, s14, v[26:27]
	v_mad_i64_i32 v[66:67], s[26:27], v66, s14, v[26:27]
	v_mad_i64_i32 v[68:69], s[26:27], v68, s14, v[26:27]
	v_mad_i64_i32 v[70:71], s[26:27], v70, s14, v[26:27]
	v_mad_i64_i32 v[72:73], s[26:27], v72, s14, v[26:27]
	v_mad_i64_i32 v[74:75], s[26:27], v74, s14, v[26:27]
	v_mad_i64_i32 v[76:77], s[26:27], v76, s14, v[26:27]
	v_mad_i64_i32 v[78:79], s[26:27], v78, s14, v[26:27]
	global_load_dword v188, v[48:49], off
	global_load_dword v189, v[50:51], off
	global_load_dword v190, v[52:53], off
	global_load_dword v191, v[54:55], off
	global_load_dword v192, v[56:57], off
	global_load_dword v193, v[58:59], off
	global_load_dword v194, v[60:61], off
	global_load_dword v195, v[62:63], off
	global_load_dword v196, v[64:65], off
	global_load_dword v197, v[66:67], off
	global_load_dword v198, v[68:69], off
	global_load_dword v199, v[70:71], off
	global_load_dword v200, v[72:73], off
	global_load_dword v201, v[74:75], off
	global_load_dword v202, v[76:77], off
	global_load_dword v203, v[78:79], off
	s_add_i32 s3, s3, 16
	s_add_i32 s2, s2, 16
	s_lshl_b32 s9, s3, 1
	s_lshl_b32 s10, s2, 1
	v_add_u32_e32 v48, s9, v28
	v_add_u32_e32 v47, s10, v19
	v_add_u32_e32 v54, s10, v21
	v_add_u32_e32 v52, s9, v30
	v_add_u32_e32 v58, s10, v23
	v_add_u32_e32 v56, s9, v32
	v_add_u32_e32 v62, s10, v29
	v_add_u32_e32 v60, s9, v34
	v_add_u32_e32 v66, s10, v31
	v_add_u32_e32 v64, s9, v36
	v_add_u32_e32 v70, s10, v33
	v_add_u32_e32 v68, s9, v38
	v_add_u32_e32 v74, s10, v35
	v_add_u32_e32 v72, s9, v40
	v_add_u32_e32 v78, s10, v37
	v_add_u32_e32 v76, s9, v42
	v_mad_i64_i32 v[48:49], s[26:27], v48, s14, v[26:27]
	v_mad_i64_i32 v[50:51], s[26:27], v47, s14, v[26:27]
	v_mad_i64_i32 v[52:53], s[26:27], v52, s14, v[26:27]
	v_mad_i64_i32 v[54:55], s[26:27], v54, s14, v[26:27]
	v_mad_i64_i32 v[56:57], s[26:27], v56, s14, v[26:27]
	v_mad_i64_i32 v[58:59], s[26:27], v58, s14, v[26:27]
	v_mad_i64_i32 v[60:61], s[26:27], v60, s14, v[26:27]
	v_mad_i64_i32 v[62:63], s[26:27], v62, s14, v[26:27]
	v_mad_i64_i32 v[64:65], s[26:27], v64, s14, v[26:27]
	v_mad_i64_i32 v[66:67], s[26:27], v66, s14, v[26:27]
	v_mad_i64_i32 v[68:69], s[26:27], v68, s14, v[26:27]
	v_mad_i64_i32 v[70:71], s[26:27], v70, s14, v[26:27]
	v_mad_i64_i32 v[72:73], s[26:27], v72, s14, v[26:27]
	v_mad_i64_i32 v[74:75], s[26:27], v74, s14, v[26:27]
	v_mad_i64_i32 v[76:77], s[26:27], v76, s14, v[26:27]
	v_mad_i64_i32 v[78:79], s[26:27], v78, s14, v[26:27]
	global_load_dword v204, v[48:49], off
	global_load_dword v205, v[50:51], off
	global_load_dword v206, v[52:53], off
	global_load_dword v207, v[54:55], off
	global_load_dword v208, v[56:57], off
	global_load_dword v209, v[58:59], off
	global_load_dword v210, v[60:61], off
	global_load_dword v211, v[62:63], off
	global_load_dword v212, v[64:65], off
	global_load_dword v213, v[66:67], off
	global_load_dword v214, v[68:69], off
	global_load_dword v215, v[70:71], off
	global_load_dword v216, v[72:73], off
	global_load_dword v217, v[74:75], off
	global_load_dword v218, v[76:77], off
	global_load_dword v219, v[78:79], off
	s_mov_b32 s9, s98
	s_mov_b32 s10, s99
	v_add_u32_e32 v48, s9, v4
	v_add_u32_e32 v50, s10, v1
	v_add_u32_e32 v54, s10, v3
	v_add_u32_e32 v52, s9, v10
	v_add_u32_e32 v58, s10, v5
	v_add_u32_e32 v56, s9, v12
	v_add_u32_e32 v62, s10, v7
	v_add_u32_e32 v60, s9, v14
	v_add_u32_e32 v66, s10, v11
	v_add_u32_e32 v64, s9, v16
	v_add_u32_e32 v70, s10, v13
	v_add_u32_e32 v68, s9, v18
	v_add_u32_e32 v74, s10, v15
	v_add_u32_e32 v72, s9, v20
	v_add_u32_e32 v78, s10, v17
	v_add_u32_e32 v76, s9, v22
	v_mad_u64_u32 v[48:49], s[26:27], v48, s95, v[6:7]
	v_mad_u64_u32 v[50:51], s[26:27], v50, s95, v[6:7]
	v_mad_u64_u32 v[52:53], s[26:27], v52, s95, v[6:7]
	v_mad_u64_u32 v[54:55], s[26:27], v54, s95, v[6:7]
	v_mad_u64_u32 v[56:57], s[26:27], v56, s95, v[6:7]
	v_mad_u64_u32 v[58:59], s[26:27], v58, s95, v[6:7]
	v_mad_u64_u32 v[60:61], s[26:27], v60, s95, v[6:7]
	v_mad_u64_u32 v[62:63], s[26:27], v62, s95, v[6:7]
	v_mad_u64_u32 v[64:65], s[26:27], v64, s95, v[6:7]
	v_mad_u64_u32 v[66:67], s[26:27], v66, s95, v[6:7]
	v_mad_u64_u32 v[68:69], s[26:27], v68, s95, v[6:7]
	v_mad_u64_u32 v[70:71], s[26:27], v70, s95, v[6:7]
	v_mad_u64_u32 v[72:73], s[26:27], v72, s95, v[6:7]
	v_mad_u64_u32 v[74:75], s[26:27], v74, s95, v[6:7]
	v_mad_u64_u32 v[76:77], s[26:27], v76, s95, v[6:7]
	v_mad_u64_u32 v[78:79], s[26:27], v78, s95, v[6:7]
	s_waitcnt vmcnt(31)
	ds_write_b32 v48, v188
	s_waitcnt vmcnt(30)
	ds_write_b32 v50, v189
	s_waitcnt vmcnt(29)
	ds_write_b32 v52, v190
	s_waitcnt vmcnt(28)
	ds_write_b32 v54, v191
	s_waitcnt vmcnt(27)
	ds_write_b32 v56, v192
	s_waitcnt vmcnt(26)
	ds_write_b32 v58, v193
	s_waitcnt vmcnt(25)
	ds_write_b32 v60, v194
	s_waitcnt vmcnt(24)
	ds_write_b32 v62, v195
	s_waitcnt vmcnt(23)
	ds_write_b32 v64, v196
	s_waitcnt vmcnt(22)
	ds_write_b32 v66, v197
	s_waitcnt vmcnt(21)
	ds_write_b32 v68, v198
	s_waitcnt vmcnt(20)
	ds_write_b32 v70, v199
	s_waitcnt vmcnt(19)
	ds_write_b32 v72, v200
	s_waitcnt vmcnt(18)
	ds_write_b32 v74, v201
	s_waitcnt vmcnt(17)
	ds_write_b32 v76, v202
	s_waitcnt vmcnt(16)
	ds_write_b32 v78, v203
	s_lshl_b32 s9, s3, 1
	s_lshl_b32 s10, s2, 1
	v_add_u32_e32 v48, s9, v4
	v_add_u32_e32 v50, s10, v1
	v_add_u32_e32 v54, s10, v3
	v_add_u32_e32 v52, s9, v10
	v_add_u32_e32 v58, s10, v5
	v_add_u32_e32 v56, s9, v12
	v_add_u32_e32 v62, s10, v7
	v_add_u32_e32 v60, s9, v14
	v_add_u32_e32 v66, s10, v11
	v_add_u32_e32 v64, s9, v16
	v_add_u32_e32 v70, s10, v13
	v_add_u32_e32 v68, s9, v18
	v_add_u32_e32 v74, s10, v15
	v_add_u32_e32 v72, s9, v20
	v_add_u32_e32 v78, s10, v17
	v_add_u32_e32 v76, s9, v22
	v_mad_u64_u32 v[48:49], s[26:27], v48, s95, v[6:7]
	v_mad_u64_u32 v[50:51], s[26:27], v50, s95, v[6:7]
	v_mad_u64_u32 v[52:53], s[26:27], v52, s95, v[6:7]
	v_mad_u64_u32 v[54:55], s[26:27], v54, s95, v[6:7]
	v_mad_u64_u32 v[56:57], s[26:27], v56, s95, v[6:7]
	v_mad_u64_u32 v[58:59], s[26:27], v58, s95, v[6:7]
	v_mad_u64_u32 v[60:61], s[26:27], v60, s95, v[6:7]
	v_mad_u64_u32 v[62:63], s[26:27], v62, s95, v[6:7]
	v_mad_u64_u32 v[64:65], s[26:27], v64, s95, v[6:7]
	v_mad_u64_u32 v[66:67], s[26:27], v66, s95, v[6:7]
	v_mad_u64_u32 v[68:69], s[26:27], v68, s95, v[6:7]
	v_mad_u64_u32 v[70:71], s[26:27], v70, s95, v[6:7]
	v_mad_u64_u32 v[72:73], s[26:27], v72, s95, v[6:7]
	v_mad_u64_u32 v[74:75], s[26:27], v74, s95, v[6:7]
	v_mad_u64_u32 v[76:77], s[26:27], v76, s95, v[6:7]
	v_mad_u64_u32 v[78:79], s[26:27], v78, s95, v[6:7]
	s_waitcnt vmcnt(15)
	ds_write_b32 v48, v204
	s_waitcnt vmcnt(14)
	ds_write_b32 v50, v205
	s_waitcnt vmcnt(13)
	ds_write_b32 v52, v206
	s_waitcnt vmcnt(12)
	ds_write_b32 v54, v207
	s_waitcnt vmcnt(11)
	ds_write_b32 v56, v208
	s_waitcnt vmcnt(10)
	ds_write_b32 v58, v209
	s_waitcnt vmcnt(9)
	ds_write_b32 v60, v210
	s_waitcnt vmcnt(8)
	ds_write_b32 v62, v211
	s_waitcnt vmcnt(7)
	ds_write_b32 v64, v212
	s_waitcnt vmcnt(6)
	ds_write_b32 v66, v213
	s_waitcnt vmcnt(5)
	ds_write_b32 v68, v214
	s_waitcnt vmcnt(4)
	ds_write_b32 v70, v215
	s_waitcnt vmcnt(3)
	ds_write_b32 v72, v216
	s_waitcnt vmcnt(2)
	ds_write_b32 v74, v217
	s_waitcnt vmcnt(1)
	ds_write_b32 v76, v218
	s_waitcnt vmcnt(0)
	ds_write_b32 v78, v219
	s_add_i32 s3, s3, 16
	s_add_i32 s2, s2, 16
	s_add_i32 s7, s7, -16
	s_add_i32 s7, s7, -16
	s_cmp_lg_u32 s7, 0
	s_waitcnt lgkmcnt(0)
	ds_read2_b32 v[30:31], v43 offset0:33 offset1:41
	ds_read2_b32 v[32:33], v43 offset1:8
	ds_read2_b32 v[34:35], v43 offset0:66 offset1:74
	ds_read2_b32 v[36:37], v43 offset0:99 offset1:107
	ds_read2_b32 v[48:49], v43 offset0:132 offset1:140
	ds_read2_b32 v[50:51], v43 offset0:165 offset1:173
	ds_read2_b32 v[52:53], v43 offset0:198 offset1:206
	ds_read2_b32 v[54:55], v43 offset0:231 offset1:239
	s_add_i32 s2, s12, 0x800
	v_add_u32_e32 v58, s2, v41
	s_ashr_i32 s9, s8, 31
	v_ashrrev_i32_e32 v59, 31, v58
	v_lshl_add_u64 v[56:57], s[8:9], 1, v[8:9]
	v_lshlrev_b64 v[58:59], 12, v[58:59]
	s_waitcnt lgkmcnt(6)
	v_cvt_pk_bf16_f32 v26, v32, v30
	s_waitcnt lgkmcnt(4)
	v_cvt_pk_bf16_f32 v27, v34, v36
	s_waitcnt lgkmcnt(2)
	v_cvt_pk_bf16_f32 v28, v48, v50
	s_waitcnt lgkmcnt(0)
	v_cvt_pk_bf16_f32 v29, v52, v54
	v_lshl_add_u64 v[58:59], v[56:57], 0, v[58:59]
	v_add_u32_e32 v30, s2, v44
	global_store_dwordx4 v[58:59], v[26:29], off
	s_add_i32 s0, s0, s81
	s_cmpk_lt_i32 s0, 0x800
	v_cvt_pk_bf16_f32 v26, v33, v31
	v_ashrrev_i32_e32 v31, 31, v30
	v_cvt_pk_bf16_f32 v27, v35, v37
	v_cvt_pk_bf16_f32 v28, v49, v51
	v_cvt_pk_bf16_f32 v29, v53, v55
	v_lshlrev_b64 v[30:31], 12, v[30:31]
	ds_read2_b32 v[32:33], v43 offset0:49 offset1:57
	ds_read2_b32 v[34:35], v43 offset0:16 offset1:24
	ds_read2_b32 v[36:37], v43 offset0:82 offset1:90
	ds_read2_b32 v[48:49], v43 offset0:115 offset1:123
	ds_read2_b32 v[50:51], v43 offset0:148 offset1:156
	ds_read2_b32 v[52:53], v43 offset0:181 offset1:189
	ds_read2_b32 v[54:55], v43 offset0:214 offset1:222
	ds_read2_b32 v[58:59], v43 offset0:247 offset1:255
	v_lshl_add_u64 v[30:31], v[56:57], 0, v[30:31]
	global_store_dwordx4 v[30:31], v[26:29], off
	v_add_u32_e32 v30, s2, v45
	v_ashrrev_i32_e32 v31, 31, v30
	v_lshlrev_b64 v[30:31], 12, v[30:31]
	s_waitcnt lgkmcnt(6)
	v_cvt_pk_bf16_f32 v26, v34, v32
	s_waitcnt lgkmcnt(4)
	v_cvt_pk_bf16_f32 v27, v36, v48
	s_waitcnt lgkmcnt(2)
	v_cvt_pk_bf16_f32 v28, v50, v52
	s_waitcnt lgkmcnt(0)
	v_cvt_pk_bf16_f32 v29, v54, v58
	v_lshl_add_u64 v[30:31], v[56:57], 0, v[30:31]
	global_store_dwordx4 v[30:31], v[26:29], off
	v_add_u32_e32 v30, s2, v46
	v_ashrrev_i32_e32 v31, 31, v30
	v_lshlrev_b64 v[30:31], 12, v[30:31]
	v_cvt_pk_bf16_f32 v26, v35, v33
	v_cvt_pk_bf16_f32 v27, v37, v49
	v_cvt_pk_bf16_f32 v28, v51, v53
	v_cvt_pk_bf16_f32 v29, v55, v59
	v_lshl_add_u64 v[30:31], v[56:57], 0, v[30:31]
	global_store_dwordx4 v[30:31], v[26:29], off
	s_waitcnt lgkmcnt(0)
	s_cbranch_scc1 .LBB0_131

.LBB0_137:
	s_lshl_b32 s9, s3, 1
	s_lshl_b32 s10, s2, 1
	s_mov_b32 s98, s9
	s_mov_b32 s99, s10
	v_add_u32_e32 v48, s9, v30
	v_add_u32_e32 v50, s10, v17
	v_add_u32_e32 v54, s10, v19
	v_add_u32_e32 v52, s9, v32
	v_add_u32_e32 v58, s10, v21
	v_add_u32_e32 v56, s9, v34
	v_add_u32_e32 v62, s10, v23
	v_add_u32_e32 v60, s9, v36
	v_add_u32_e32 v66, s10, v31
	v_add_u32_e32 v64, s9, v38
	v_add_u32_e32 v70, s10, v33
	v_add_u32_e32 v68, s9, v40
	v_add_u32_e32 v74, s10, v35
	v_add_u32_e32 v72, s9, v42
	v_add_u32_e32 v78, s10, v37
	v_add_u32_e32 v76, s9, v44
	v_mad_i64_i32 v[48:49], s[20:21], v48, s14, v[28:29]
	v_mad_i64_i32 v[50:51], s[20:21], v50, s14, v[28:29]
	v_mad_i64_i32 v[52:53], s[20:21], v52, s14, v[28:29]
	v_mad_i64_i32 v[54:55], s[20:21], v54, s14, v[28:29]
	v_mad_i64_i32 v[56:57], s[20:21], v56, s14, v[28:29]
	v_mad_i64_i32 v[58:59], s[20:21], v58, s14, v[28:29]
	v_mad_i64_i32 v[60:61], s[20:21], v60, s14, v[28:29]
	v_mad_i64_i32 v[62:63], s[20:21], v62, s14, v[28:29]
	v_mad_i64_i32 v[64:65], s[20:21], v64, s14, v[28:29]
	v_mad_i64_i32 v[66:67], s[20:21], v66, s14, v[28:29]
	v_mad_i64_i32 v[68:69], s[20:21], v68, s14, v[28:29]
	v_mad_i64_i32 v[70:71], s[20:21], v70, s14, v[28:29]
	v_mad_i64_i32 v[72:73], s[20:21], v72, s14, v[28:29]
	v_mad_i64_i32 v[74:75], s[20:21], v74, s14, v[28:29]
	v_mad_i64_i32 v[76:77], s[20:21], v76, s14, v[28:29]
	v_mad_i64_i32 v[78:79], s[20:21], v78, s14, v[28:29]
	global_load_dword v188, v[48:49], off
	global_load_dword v189, v[50:51], off
	global_load_dword v190, v[52:53], off
	global_load_dword v191, v[54:55], off
	global_load_dword v192, v[56:57], off
	global_load_dword v193, v[58:59], off
	global_load_dword v194, v[60:61], off
	global_load_dword v195, v[62:63], off
	global_load_dword v196, v[64:65], off
	global_load_dword v197, v[66:67], off
	global_load_dword v198, v[68:69], off
	global_load_dword v199, v[70:71], off
	global_load_dword v200, v[72:73], off
	global_load_dword v201, v[74:75], off
	global_load_dword v202, v[76:77], off
	global_load_dword v203, v[78:79], off
	s_add_i32 s3, s3, 16
	s_add_i32 s2, s2, 16
	s_lshl_b32 s9, s3, 1
	s_lshl_b32 s10, s2, 1
	v_add_u32_e32 v48, s9, v30
	v_add_u32_e32 v50, s10, v17
	v_add_u32_e32 v54, s10, v19
	v_add_u32_e32 v52, s9, v32
	v_add_u32_e32 v58, s10, v21
	v_add_u32_e32 v56, s9, v34
	v_add_u32_e32 v62, s10, v23
	v_add_u32_e32 v60, s9, v36
	v_add_u32_e32 v66, s10, v31
	v_add_u32_e32 v64, s9, v38
	v_add_u32_e32 v70, s10, v33
	v_add_u32_e32 v68, s9, v40
	v_add_u32_e32 v74, s10, v35
	v_add_u32_e32 v72, s9, v42
	v_add_u32_e32 v78, s10, v37
	v_add_u32_e32 v76, s9, v44
	v_mad_i64_i32 v[48:49], s[20:21], v48, s14, v[28:29]
	v_mad_i64_i32 v[50:51], s[20:21], v50, s14, v[28:29]
	v_mad_i64_i32 v[52:53], s[20:21], v52, s14, v[28:29]
	v_mad_i64_i32 v[54:55], s[20:21], v54, s14, v[28:29]
	v_mad_i64_i32 v[56:57], s[20:21], v56, s14, v[28:29]
	v_mad_i64_i32 v[58:59], s[20:21], v58, s14, v[28:29]
	v_mad_i64_i32 v[60:61], s[20:21], v60, s14, v[28:29]
	v_mad_i64_i32 v[62:63], s[20:21], v62, s14, v[28:29]
	v_mad_i64_i32 v[64:65], s[20:21], v64, s14, v[28:29]
	v_mad_i64_i32 v[66:67], s[20:21], v66, s14, v[28:29]
	v_mad_i64_i32 v[68:69], s[20:21], v68, s14, v[28:29]
	v_mad_i64_i32 v[70:71], s[20:21], v70, s14, v[28:29]
	v_mad_i64_i32 v[72:73], s[20:21], v72, s14, v[28:29]
	v_mad_i64_i32 v[74:75], s[20:21], v74, s14, v[28:29]
	v_mad_i64_i32 v[76:77], s[20:21], v76, s14, v[28:29]
	v_mad_i64_i32 v[78:79], s[20:21], v78, s14, v[28:29]
	global_load_dword v204, v[48:49], off
	global_load_dword v205, v[50:51], off
	global_load_dword v206, v[52:53], off
	global_load_dword v207, v[54:55], off
	global_load_dword v208, v[56:57], off
	global_load_dword v209, v[58:59], off
	global_load_dword v210, v[60:61], off
	global_load_dword v211, v[62:63], off
	global_load_dword v212, v[64:65], off
	global_load_dword v213, v[66:67], off
	global_load_dword v214, v[68:69], off
	global_load_dword v215, v[70:71], off
	global_load_dword v216, v[72:73], off
	global_load_dword v217, v[74:75], off
	global_load_dword v218, v[76:77], off
	global_load_dword v219, v[78:79], off
	s_mov_b32 s9, s98
	s_mov_b32 s10, s99
	v_add_u32_e32 v48, s9, v4
	v_add_u32_e32 v50, s10, v1
	v_add_u32_e32 v54, s10, v3
	v_add_u32_e32 v52, s9, v8
	v_add_u32_e32 v58, s10, v5
	v_add_u32_e32 v56, s9, v10
	v_add_u32_e32 v62, s10, v7
	v_add_u32_e32 v60, s9, v12
	v_add_u32_e32 v66, s10, v9
	v_add_u32_e32 v64, s9, v14
	v_add_u32_e32 v70, s10, v11
	v_add_u32_e32 v68, s9, v16
	v_add_u32_e32 v74, s10, v13
	v_add_u32_e32 v72, s9, v18
	v_add_u32_e32 v78, s10, v15
	v_add_u32_e32 v76, s9, v20
	v_mad_u64_u32 v[48:49], s[20:21], v48, s95, v[6:7]
	v_mad_u64_u32 v[50:51], s[20:21], v50, s95, v[6:7]
	v_mad_u64_u32 v[52:53], s[20:21], v52, s95, v[6:7]
	v_mad_u64_u32 v[54:55], s[20:21], v54, s95, v[6:7]
	v_mad_u64_u32 v[56:57], s[20:21], v56, s95, v[6:7]
	v_mad_u64_u32 v[58:59], s[20:21], v58, s95, v[6:7]
	v_mad_u64_u32 v[60:61], s[20:21], v60, s95, v[6:7]
	v_mad_u64_u32 v[62:63], s[20:21], v62, s95, v[6:7]
	v_mad_u64_u32 v[64:65], s[20:21], v64, s95, v[6:7]
	v_mad_u64_u32 v[66:67], s[20:21], v66, s95, v[6:7]
	v_mad_u64_u32 v[68:69], s[20:21], v68, s95, v[6:7]
	v_mad_u64_u32 v[70:71], s[20:21], v70, s95, v[6:7]
	v_mad_u64_u32 v[72:73], s[20:21], v72, s95, v[6:7]
	v_mad_u64_u32 v[74:75], s[20:21], v74, s95, v[6:7]
	v_mad_u64_u32 v[76:77], s[20:21], v76, s95, v[6:7]
	v_mad_u64_u32 v[78:79], s[20:21], v78, s95, v[6:7]
	s_waitcnt vmcnt(31)
	ds_write_b32 v48, v188
	s_waitcnt vmcnt(30)
	ds_write_b32 v50, v189
	s_waitcnt vmcnt(29)
	ds_write_b32 v52, v190
	s_waitcnt vmcnt(28)
	ds_write_b32 v54, v191
	s_waitcnt vmcnt(27)
	ds_write_b32 v56, v192
	s_waitcnt vmcnt(26)
	ds_write_b32 v58, v193
	s_waitcnt vmcnt(25)
	ds_write_b32 v60, v194
	s_waitcnt vmcnt(24)
	ds_write_b32 v62, v195
	s_waitcnt vmcnt(23)
	ds_write_b32 v64, v196
	s_waitcnt vmcnt(22)
	ds_write_b32 v66, v197
	s_waitcnt vmcnt(21)
	ds_write_b32 v68, v198
	s_waitcnt vmcnt(20)
	ds_write_b32 v70, v199
	s_waitcnt vmcnt(19)
	ds_write_b32 v72, v200
	s_waitcnt vmcnt(18)
	ds_write_b32 v74, v201
	s_waitcnt vmcnt(17)
	ds_write_b32 v76, v202
	s_waitcnt vmcnt(16)
	ds_write_b32 v78, v203
	s_lshl_b32 s9, s3, 1
	s_lshl_b32 s10, s2, 1
	v_add_u32_e32 v48, s9, v4
	v_add_u32_e32 v50, s10, v1
	v_add_u32_e32 v54, s10, v3
	v_add_u32_e32 v52, s9, v8
	v_add_u32_e32 v58, s10, v5
	v_add_u32_e32 v56, s9, v10
	v_add_u32_e32 v62, s10, v7
	v_add_u32_e32 v60, s9, v12
	v_add_u32_e32 v66, s10, v9
	v_add_u32_e32 v64, s9, v14
	v_add_u32_e32 v70, s10, v11
	v_add_u32_e32 v68, s9, v16
	v_add_u32_e32 v74, s10, v13
	v_add_u32_e32 v72, s9, v18
	v_add_u32_e32 v78, s10, v15
	v_add_u32_e32 v76, s9, v20
	v_mad_u64_u32 v[48:49], s[20:21], v48, s95, v[6:7]
	v_mad_u64_u32 v[50:51], s[20:21], v50, s95, v[6:7]
	v_mad_u64_u32 v[52:53], s[20:21], v52, s95, v[6:7]
	v_mad_u64_u32 v[54:55], s[20:21], v54, s95, v[6:7]
	v_mad_u64_u32 v[56:57], s[20:21], v56, s95, v[6:7]
	v_mad_u64_u32 v[58:59], s[20:21], v58, s95, v[6:7]
	v_mad_u64_u32 v[60:61], s[20:21], v60, s95, v[6:7]
	v_mad_u64_u32 v[62:63], s[20:21], v62, s95, v[6:7]
	v_mad_u64_u32 v[64:65], s[20:21], v64, s95, v[6:7]
	v_mad_u64_u32 v[66:67], s[20:21], v66, s95, v[6:7]
	v_mad_u64_u32 v[68:69], s[20:21], v68, s95, v[6:7]
	v_mad_u64_u32 v[70:71], s[20:21], v70, s95, v[6:7]
	v_mad_u64_u32 v[72:73], s[20:21], v72, s95, v[6:7]
	v_mad_u64_u32 v[74:75], s[20:21], v74, s95, v[6:7]
	v_mad_u64_u32 v[76:77], s[20:21], v76, s95, v[6:7]
	v_mad_u64_u32 v[78:79], s[20:21], v78, s95, v[6:7]
	s_waitcnt vmcnt(15)
	ds_write_b32 v48, v204
	s_waitcnt vmcnt(14)
	ds_write_b32 v50, v205
	s_waitcnt vmcnt(13)
	ds_write_b32 v52, v206
	s_waitcnt vmcnt(12)
	ds_write_b32 v54, v207
	s_waitcnt vmcnt(11)
	ds_write_b32 v56, v208
	s_waitcnt vmcnt(10)
	ds_write_b32 v58, v209
	s_waitcnt vmcnt(9)
	ds_write_b32 v60, v210
	s_waitcnt vmcnt(8)
	ds_write_b32 v62, v211
	s_waitcnt vmcnt(7)
	ds_write_b32 v64, v212
	s_waitcnt vmcnt(6)
	ds_write_b32 v66, v213
	s_waitcnt vmcnt(5)
	ds_write_b32 v68, v214
	s_waitcnt vmcnt(4)
	ds_write_b32 v70, v215
	s_waitcnt vmcnt(3)
	ds_write_b32 v72, v216
	s_waitcnt vmcnt(2)
	ds_write_b32 v74, v217
	s_waitcnt vmcnt(1)
	ds_write_b32 v76, v218
	s_waitcnt vmcnt(0)
	ds_write_b32 v78, v219
	s_add_i32 s3, s3, 16
	s_add_i32 s2, s2, 16
	s_add_i32 s7, s7, -16
	s_add_i32 s7, s7, -16
	s_cmp_lg_u32 s7, 0
	s_waitcnt lgkmcnt(0)
	ds_read2_b32 v[32:33], v43 offset0:33 offset1:41
	ds_read2_b32 v[34:35], v43 offset1:8
	ds_read2_b32 v[36:37], v43 offset0:66 offset1:74
	ds_read2_b32 v[48:49], v43 offset0:99 offset1:107
	ds_read2_b32 v[50:51], v43 offset0:132 offset1:140
	ds_read2_b32 v[52:53], v43 offset0:165 offset1:173
	ds_read2_b32 v[54:55], v43 offset0:198 offset1:206
	ds_read2_b32 v[56:57], v43 offset0:231 offset1:239
	s_add_i32 s2, s12, 0x1000
	v_add_u32_e32 v60, s2, v41
	s_ashr_i32 s9, s8, 31
	v_ashrrev_i32_e32 v61, 31, v60
	v_lshl_add_u64 v[58:59], s[8:9], 1, v[26:27]
	v_lshlrev_b64 v[60:61], 12, v[60:61]
	s_waitcnt lgkmcnt(6)
	v_cvt_pk_bf16_f32 v28, v34, v32
	s_waitcnt lgkmcnt(4)
	v_cvt_pk_bf16_f32 v29, v36, v48
	s_waitcnt lgkmcnt(2)
	v_cvt_pk_bf16_f32 v30, v50, v52
	s_waitcnt lgkmcnt(0)
	v_cvt_pk_bf16_f32 v31, v54, v56
	v_lshl_add_u64 v[60:61], v[58:59], 0, v[60:61]
	v_add_u32_e32 v32, s2, v45
	global_store_dwordx4 v[60:61], v[28:31], off
	s_add_i32 s0, s0, s81
	s_cmpk_lt_i32 s0, 0x1000
	v_cvt_pk_bf16_f32 v28, v35, v33
	v_ashrrev_i32_e32 v33, 31, v32
	v_cvt_pk_bf16_f32 v29, v37, v49
	v_cvt_pk_bf16_f32 v30, v51, v53
	v_cvt_pk_bf16_f32 v31, v55, v57
	v_lshlrev_b64 v[32:33], 12, v[32:33]
	ds_read2_b32 v[34:35], v43 offset0:49 offset1:57
	ds_read2_b32 v[36:37], v43 offset0:16 offset1:24
	ds_read2_b32 v[48:49], v43 offset0:82 offset1:90
	ds_read2_b32 v[50:51], v43 offset0:115 offset1:123
	ds_read2_b32 v[52:53], v43 offset0:148 offset1:156
	ds_read2_b32 v[54:55], v43 offset0:181 offset1:189
	ds_read2_b32 v[56:57], v43 offset0:214 offset1:222
	ds_read2_b32 v[60:61], v43 offset0:247 offset1:255
	v_lshl_add_u64 v[32:33], v[58:59], 0, v[32:33]
	global_store_dwordx4 v[32:33], v[28:31], off
	v_add_u32_e32 v32, s2, v46
	v_ashrrev_i32_e32 v33, 31, v32
	v_lshlrev_b64 v[32:33], 12, v[32:33]
	s_waitcnt lgkmcnt(6)
	v_cvt_pk_bf16_f32 v28, v36, v34
	s_waitcnt lgkmcnt(4)
	v_cvt_pk_bf16_f32 v29, v48, v50
	s_waitcnt lgkmcnt(2)
	v_cvt_pk_bf16_f32 v30, v52, v54
	s_waitcnt lgkmcnt(0)
	v_cvt_pk_bf16_f32 v31, v56, v60
	v_lshl_add_u64 v[32:33], v[58:59], 0, v[32:33]
	global_store_dwordx4 v[32:33], v[28:31], off
	v_add_u32_e32 v32, s2, v47
	v_ashrrev_i32_e32 v33, 31, v32
	v_lshlrev_b64 v[32:33], 12, v[32:33]
	v_cvt_pk_bf16_f32 v28, v37, v35
	v_cvt_pk_bf16_f32 v29, v49, v51
	v_cvt_pk_bf16_f32 v30, v53, v55
	v_cvt_pk_bf16_f32 v31, v57, v61
	v_lshl_add_u64 v[32:33], v[58:59], 0, v[32:33]
	global_store_dwordx4 v[32:33], v[28:31], off
	s_waitcnt lgkmcnt(0)
	s_cbranch_scc1 .LBB0_136
	v_lshlrev_b32_e32 v224, 2, v2
	v_lshl_add_u64 v[24:25], s[22:23], 0, v[224:225]
	s_mov_b64 s[2:3], 0x4000
	v_lshlrev_b32_e32 v224, 1, v22
	v_lshl_add_u64 v[24:25], v[24:25], 0, s[2:3]
	v_lshl_add_u64 v[22:23], s[18:19], 0, v[224:225]
	s_mov_b64 s[2:3], 0x3900000
	v_lshl_add_u64 v[22:23], v[22:23], 0, s[2:3]
	s_mov_b32 s0, s53

.LBB0_141:
	s_lshl_b32 s9, s3, 1
	s_lshl_b32 s10, s2, 1
	s_mov_b32 s98, s9
	s_mov_b32 s99, s10
	v_add_u32_e32 v44, s9, v2
	v_add_u32_e32 v42, s10, v17
	v_add_u32_e32 v54, s10, v19
	v_add_u32_e32 v52, s9, v28
	v_add_u32_e32 v58, s10, v21
	v_add_u32_e32 v56, s9, v30
	v_add_u32_e32 v62, s10, v29
	v_add_u32_e32 v60, s9, v32
	v_add_u32_e32 v66, s10, v31
	v_add_u32_e32 v64, s9, v34
	v_add_u32_e32 v70, s10, v33
	v_add_u32_e32 v68, s9, v36
	v_add_u32_e32 v74, s10, v35
	v_add_u32_e32 v72, s9, v38
	v_add_u32_e32 v78, s10, v37
	v_add_u32_e32 v76, s9, v40
	v_mad_i64_i32 v[48:49], s[20:21], v44, s14, v[26:27]
	v_mad_i64_i32 v[50:51], s[20:21], v42, s14, v[26:27]
	v_mad_i64_i32 v[52:53], s[20:21], v52, s14, v[26:27]
	v_mad_i64_i32 v[54:55], s[20:21], v54, s14, v[26:27]
	v_mad_i64_i32 v[56:57], s[20:21], v56, s14, v[26:27]
	v_mad_i64_i32 v[58:59], s[20:21], v58, s14, v[26:27]
	v_mad_i64_i32 v[60:61], s[20:21], v60, s14, v[26:27]
	v_mad_i64_i32 v[62:63], s[20:21], v62, s14, v[26:27]
	v_mad_i64_i32 v[64:65], s[20:21], v64, s14, v[26:27]
	v_mad_i64_i32 v[66:67], s[20:21], v66, s14, v[26:27]
	v_mad_i64_i32 v[68:69], s[20:21], v68, s14, v[26:27]
	v_mad_i64_i32 v[70:71], s[20:21], v70, s14, v[26:27]
	v_mad_i64_i32 v[72:73], s[20:21], v72, s14, v[26:27]
	v_mad_i64_i32 v[74:75], s[20:21], v74, s14, v[26:27]
	v_mad_i64_i32 v[76:77], s[20:21], v76, s14, v[26:27]
	v_mad_i64_i32 v[78:79], s[20:21], v78, s14, v[26:27]
	global_load_dword v188, v[48:49], off
	global_load_dword v189, v[50:51], off
	global_load_dword v190, v[52:53], off
	global_load_dword v191, v[54:55], off
	global_load_dword v192, v[56:57], off
	global_load_dword v193, v[58:59], off
	global_load_dword v194, v[60:61], off
	global_load_dword v195, v[62:63], off
	global_load_dword v196, v[64:65], off
	global_load_dword v197, v[66:67], off
	global_load_dword v198, v[68:69], off
	global_load_dword v199, v[70:71], off
	global_load_dword v200, v[72:73], off
	global_load_dword v201, v[74:75], off
	global_load_dword v202, v[76:77], off
	global_load_dword v203, v[78:79], off
	s_add_i32 s3, s3, 16
	s_add_i32 s2, s2, 16
	s_lshl_b32 s9, s3, 1
	s_lshl_b32 s10, s2, 1
	v_add_u32_e32 v44, s9, v2
	v_add_u32_e32 v42, s10, v17
	v_add_u32_e32 v54, s10, v19
	v_add_u32_e32 v52, s9, v28
	v_add_u32_e32 v58, s10, v21
	v_add_u32_e32 v56, s9, v30
	v_add_u32_e32 v62, s10, v29
	v_add_u32_e32 v60, s9, v32
	v_add_u32_e32 v66, s10, v31
	v_add_u32_e32 v64, s9, v34
	v_add_u32_e32 v70, s10, v33
	v_add_u32_e32 v68, s9, v36
	v_add_u32_e32 v74, s10, v35
	v_add_u32_e32 v72, s9, v38
	v_add_u32_e32 v78, s10, v37
	v_add_u32_e32 v76, s9, v40
	v_mad_i64_i32 v[48:49], s[20:21], v44, s14, v[26:27]
	v_mad_i64_i32 v[50:51], s[20:21], v42, s14, v[26:27]
	v_mad_i64_i32 v[52:53], s[20:21], v52, s14, v[26:27]
	v_mad_i64_i32 v[54:55], s[20:21], v54, s14, v[26:27]
	v_mad_i64_i32 v[56:57], s[20:21], v56, s14, v[26:27]
	v_mad_i64_i32 v[58:59], s[20:21], v58, s14, v[26:27]
	v_mad_i64_i32 v[60:61], s[20:21], v60, s14, v[26:27]
	v_mad_i64_i32 v[62:63], s[20:21], v62, s14, v[26:27]
	v_mad_i64_i32 v[64:65], s[20:21], v64, s14, v[26:27]
	v_mad_i64_i32 v[66:67], s[20:21], v66, s14, v[26:27]
	v_mad_i64_i32 v[68:69], s[20:21], v68, s14, v[26:27]
	v_mad_i64_i32 v[70:71], s[20:21], v70, s14, v[26:27]
	v_mad_i64_i32 v[72:73], s[20:21], v72, s14, v[26:27]
	v_mad_i64_i32 v[74:75], s[20:21], v74, s14, v[26:27]
	v_mad_i64_i32 v[76:77], s[20:21], v76, s14, v[26:27]
	v_mad_i64_i32 v[78:79], s[20:21], v78, s14, v[26:27]
	global_load_dword v204, v[48:49], off
	global_load_dword v205, v[50:51], off
	global_load_dword v206, v[52:53], off
	global_load_dword v207, v[54:55], off
	global_load_dword v208, v[56:57], off
	global_load_dword v209, v[58:59], off
	global_load_dword v210, v[60:61], off
	global_load_dword v211, v[62:63], off
	global_load_dword v212, v[64:65], off
	global_load_dword v213, v[66:67], off
	global_load_dword v214, v[68:69], off
	global_load_dword v215, v[70:71], off
	global_load_dword v216, v[72:73], off
	global_load_dword v217, v[74:75], off
	global_load_dword v218, v[76:77], off
	global_load_dword v219, v[78:79], off
	s_mov_b32 s9, s98
	s_mov_b32 s10, s99
	v_add_u32_e32 v48, s9, v4
	v_add_u32_e32 v50, s10, v1
	v_add_u32_e32 v54, s10, v3
	v_add_u32_e32 v52, s9, v8
	v_add_u32_e32 v58, s10, v5
	v_add_u32_e32 v56, s9, v10
	v_add_u32_e32 v62, s10, v7
	v_add_u32_e32 v60, s9, v12
	v_add_u32_e32 v66, s10, v9
	v_add_u32_e32 v64, s9, v14
	v_add_u32_e32 v70, s10, v11
	v_add_u32_e32 v68, s9, v16
	v_add_u32_e32 v74, s10, v13
	v_add_u32_e32 v72, s9, v18
	v_add_u32_e32 v78, s10, v15
	v_add_u32_e32 v76, s9, v20
	v_mad_u64_u32 v[48:49], s[20:21], v48, s95, v[6:7]
	v_mad_u64_u32 v[50:51], s[20:21], v50, s95, v[6:7]
	v_mad_u64_u32 v[52:53], s[20:21], v52, s95, v[6:7]
	v_mad_u64_u32 v[54:55], s[20:21], v54, s95, v[6:7]
	v_mad_u64_u32 v[56:57], s[20:21], v56, s95, v[6:7]
	v_mad_u64_u32 v[58:59], s[20:21], v58, s95, v[6:7]
	v_mad_u64_u32 v[60:61], s[20:21], v60, s95, v[6:7]
	v_mad_u64_u32 v[62:63], s[20:21], v62, s95, v[6:7]
	v_mad_u64_u32 v[64:65], s[20:21], v64, s95, v[6:7]
	v_mad_u64_u32 v[66:67], s[20:21], v66, s95, v[6:7]
	v_mad_u64_u32 v[68:69], s[20:21], v68, s95, v[6:7]
	v_mad_u64_u32 v[70:71], s[20:21], v70, s95, v[6:7]
	v_mad_u64_u32 v[72:73], s[20:21], v72, s95, v[6:7]
	v_mad_u64_u32 v[74:75], s[20:21], v74, s95, v[6:7]
	v_mad_u64_u32 v[76:77], s[20:21], v76, s95, v[6:7]
	v_mad_u64_u32 v[78:79], s[20:21], v78, s95, v[6:7]
	s_waitcnt vmcnt(31)
	ds_write_b32 v48, v188
	s_waitcnt vmcnt(30)
	ds_write_b32 v50, v189
	s_waitcnt vmcnt(29)
	ds_write_b32 v52, v190
	s_waitcnt vmcnt(28)
	ds_write_b32 v54, v191
	s_waitcnt vmcnt(27)
	ds_write_b32 v56, v192
	s_waitcnt vmcnt(26)
	ds_write_b32 v58, v193
	s_waitcnt vmcnt(25)
	ds_write_b32 v60, v194
	s_waitcnt vmcnt(24)
	ds_write_b32 v62, v195
	s_waitcnt vmcnt(23)
	ds_write_b32 v64, v196
	s_waitcnt vmcnt(22)
	ds_write_b32 v66, v197
	s_waitcnt vmcnt(21)
	ds_write_b32 v68, v198
	s_waitcnt vmcnt(20)
	ds_write_b32 v70, v199
	s_waitcnt vmcnt(19)
	ds_write_b32 v72, v200
	s_waitcnt vmcnt(18)
	ds_write_b32 v74, v201
	s_waitcnt vmcnt(17)
	ds_write_b32 v76, v202
	s_waitcnt vmcnt(16)
	ds_write_b32 v78, v203
	s_lshl_b32 s9, s3, 1
	s_lshl_b32 s10, s2, 1
	v_add_u32_e32 v48, s9, v4
	v_add_u32_e32 v50, s10, v1
	v_add_u32_e32 v54, s10, v3
	v_add_u32_e32 v52, s9, v8
	v_add_u32_e32 v58, s10, v5
	v_add_u32_e32 v56, s9, v10
	v_add_u32_e32 v62, s10, v7
	v_add_u32_e32 v60, s9, v12
	v_add_u32_e32 v66, s10, v9
	v_add_u32_e32 v64, s9, v14
	v_add_u32_e32 v70, s10, v11
	v_add_u32_e32 v68, s9, v16
	v_add_u32_e32 v74, s10, v13
	v_add_u32_e32 v72, s9, v18
	v_add_u32_e32 v78, s10, v15
	v_add_u32_e32 v76, s9, v20
	v_mad_u64_u32 v[48:49], s[20:21], v48, s95, v[6:7]
	v_mad_u64_u32 v[50:51], s[20:21], v50, s95, v[6:7]
	v_mad_u64_u32 v[52:53], s[20:21], v52, s95, v[6:7]
	v_mad_u64_u32 v[54:55], s[20:21], v54, s95, v[6:7]
	v_mad_u64_u32 v[56:57], s[20:21], v56, s95, v[6:7]
	v_mad_u64_u32 v[58:59], s[20:21], v58, s95, v[6:7]
	v_mad_u64_u32 v[60:61], s[20:21], v60, s95, v[6:7]
	v_mad_u64_u32 v[62:63], s[20:21], v62, s95, v[6:7]
	v_mad_u64_u32 v[64:65], s[20:21], v64, s95, v[6:7]
	v_mad_u64_u32 v[66:67], s[20:21], v66, s95, v[6:7]
	v_mad_u64_u32 v[68:69], s[20:21], v68, s95, v[6:7]
	v_mad_u64_u32 v[70:71], s[20:21], v70, s95, v[6:7]
	v_mad_u64_u32 v[72:73], s[20:21], v72, s95, v[6:7]
	v_mad_u64_u32 v[74:75], s[20:21], v74, s95, v[6:7]
	v_mad_u64_u32 v[76:77], s[20:21], v76, s95, v[6:7]
	v_mad_u64_u32 v[78:79], s[20:21], v78, s95, v[6:7]
	s_waitcnt vmcnt(15)
	ds_write_b32 v48, v204
	s_waitcnt vmcnt(14)
	ds_write_b32 v50, v205
	s_waitcnt vmcnt(13)
	ds_write_b32 v52, v206
	s_waitcnt vmcnt(12)
	ds_write_b32 v54, v207
	s_waitcnt vmcnt(11)
	ds_write_b32 v56, v208
	s_waitcnt vmcnt(10)
	ds_write_b32 v58, v209
	s_waitcnt vmcnt(9)
	ds_write_b32 v60, v210
	s_waitcnt vmcnt(8)
	ds_write_b32 v62, v211
	s_waitcnt vmcnt(7)
	ds_write_b32 v64, v212
	s_waitcnt vmcnt(6)
	ds_write_b32 v66, v213
	s_waitcnt vmcnt(5)
	ds_write_b32 v68, v214
	s_waitcnt vmcnt(4)
	ds_write_b32 v70, v215
	s_waitcnt vmcnt(3)
	ds_write_b32 v72, v216
	s_waitcnt vmcnt(2)
	ds_write_b32 v74, v217
	s_waitcnt vmcnt(1)
	ds_write_b32 v76, v218
	s_waitcnt vmcnt(0)
	ds_write_b32 v78, v219
	s_add_i32 s3, s3, 16
	s_add_i32 s2, s2, 16
	s_add_i32 s7, s7, -16
	s_add_i32 s7, s7, -16
	s_cmp_lg_u32 s7, 0
	s_waitcnt lgkmcnt(0)
	ds_read2_b32 v[30:31], v43 offset0:33 offset1:41
	ds_read2_b32 v[32:33], v43 offset1:8
	ds_read2_b32 v[34:35], v43 offset0:66 offset1:74
	ds_read2_b32 v[36:37], v43 offset0:99 offset1:107
	ds_read2_b32 v[48:49], v43 offset0:132 offset1:140
	ds_read2_b32 v[50:51], v43 offset0:165 offset1:173
	ds_read2_b32 v[52:53], v43 offset0:198 offset1:206
	ds_read2_b32 v[54:55], v43 offset0:231 offset1:239
	v_add_u32_e32 v58, s8, v41
	s_ashr_i32 s13, s12, 31
	v_ashrrev_i32_e32 v59, 31, v58
	v_lshl_add_u64 v[56:57], s[12:13], 1, v[22:23]
	v_lshlrev_b64 v[58:59], 12, v[58:59]
	s_waitcnt lgkmcnt(6)
	v_cvt_pk_bf16_f32 v26, v32, v30
	s_waitcnt lgkmcnt(4)
	v_cvt_pk_bf16_f32 v27, v34, v36
	s_waitcnt lgkmcnt(2)
	v_cvt_pk_bf16_f32 v28, v48, v50
	s_waitcnt lgkmcnt(0)
	v_cvt_pk_bf16_f32 v29, v52, v54
	v_lshl_add_u64 v[58:59], v[56:57], 0, v[58:59]
	v_add_u32_e32 v30, s8, v45
	global_store_dwordx4 v[58:59], v[26:29], off
	s_add_i32 s0, s0, s81
	s_cmpk_lt_i32 s0, 0x1000
	v_cvt_pk_bf16_f32 v26, v33, v31
	v_ashrrev_i32_e32 v31, 31, v30
	v_cvt_pk_bf16_f32 v27, v35, v37
	v_cvt_pk_bf16_f32 v28, v49, v51
	v_cvt_pk_bf16_f32 v29, v53, v55
	v_lshlrev_b64 v[30:31], 12, v[30:31]
	ds_read2_b32 v[32:33], v43 offset0:49 offset1:57
	ds_read2_b32 v[34:35], v43 offset0:16 offset1:24
	ds_read2_b32 v[36:37], v43 offset0:82 offset1:90
	ds_read2_b32 v[48:49], v43 offset0:115 offset1:123
	ds_read2_b32 v[50:51], v43 offset0:148 offset1:156
	ds_read2_b32 v[52:53], v43 offset0:181 offset1:189
	ds_read2_b32 v[54:55], v43 offset0:214 offset1:222
	ds_read2_b32 v[58:59], v43 offset0:247 offset1:255
	v_lshl_add_u64 v[30:31], v[56:57], 0, v[30:31]
	global_store_dwordx4 v[30:31], v[26:29], off
	v_add_u32_e32 v30, s8, v46
	v_ashrrev_i32_e32 v31, 31, v30
	v_lshlrev_b64 v[30:31], 12, v[30:31]
	s_waitcnt lgkmcnt(6)
	v_cvt_pk_bf16_f32 v26, v34, v32
	s_waitcnt lgkmcnt(4)
	v_cvt_pk_bf16_f32 v27, v36, v48
	s_waitcnt lgkmcnt(2)
	v_cvt_pk_bf16_f32 v28, v50, v52
	s_waitcnt lgkmcnt(0)
	v_cvt_pk_bf16_f32 v29, v54, v58
	v_lshl_add_u64 v[30:31], v[56:57], 0, v[30:31]
	global_store_dwordx4 v[30:31], v[26:29], off
	v_add_u32_e32 v30, s8, v47
	v_ashrrev_i32_e32 v31, 31, v30
	v_lshlrev_b64 v[30:31], 12, v[30:31]
	v_cvt_pk_bf16_f32 v26, v35, v33
	v_cvt_pk_bf16_f32 v27, v37, v49
	v_cvt_pk_bf16_f32 v28, v51, v53
	v_cvt_pk_bf16_f32 v29, v55, v59
	v_lshl_add_u64 v[30:31], v[56:57], 0, v[30:31]
	global_store_dwordx4 v[30:31], v[26:29], off
	s_waitcnt lgkmcnt(0)
	s_cbranch_scc1 .LBB0_140

.LBB0_146:
	s_lshl_b32 s9, s3, 1
	s_lshl_b32 s10, s2, 1
	s_mov_b32 s98, s9
	s_mov_b32 s99, s10
	v_add_u32_e32 v46, s9, v26
	v_add_u32_e32 v44, s10, v21
	v_add_u32_e32 v48, s10, v23
	v_add_u32_e32 v50, s9, v28
	v_add_u32_e32 v52, s10, v27
	v_add_u32_e32 v54, s9, v30
	v_add_u32_e32 v56, s10, v29
	v_add_u32_e32 v58, s9, v32
	v_add_u32_e32 v60, s10, v31
	v_add_u32_e32 v62, s9, v34
	v_add_u32_e32 v64, s10, v33
	v_add_u32_e32 v66, s9, v36
	v_add_u32_e32 v68, s10, v35
	v_add_u32_e32 v70, s9, v38
	v_add_u32_e32 v72, s10, v37
	v_add_u32_e32 v74, s9, v40
	v_ashrrev_i32_e32 v47, 31, v46
	v_ashrrev_i32_e32 v45, 31, v44
	v_ashrrev_i32_e32 v51, 31, v50
	v_ashrrev_i32_e32 v49, 31, v48
	v_ashrrev_i32_e32 v55, 31, v54
	v_ashrrev_i32_e32 v53, 31, v52
	v_ashrrev_i32_e32 v59, 31, v58
	v_ashrrev_i32_e32 v57, 31, v56
	v_ashrrev_i32_e32 v63, 31, v62
	v_ashrrev_i32_e32 v61, 31, v60
	v_ashrrev_i32_e32 v67, 31, v66
	v_ashrrev_i32_e32 v65, 31, v64
	v_ashrrev_i32_e32 v71, 31, v70
	v_ashrrev_i32_e32 v69, 31, v68
	v_ashrrev_i32_e32 v75, 31, v74
	v_ashrrev_i32_e32 v73, 31, v72
	v_lshlrev_b64 v[46:47], 13, v[46:47]
	v_lshlrev_b64 v[44:45], 13, v[44:45]
	v_lshlrev_b64 v[48:49], 13, v[48:49]
	v_lshlrev_b64 v[50:51], 13, v[50:51]
	v_lshlrev_b64 v[52:53], 13, v[52:53]
	v_lshlrev_b64 v[54:55], 13, v[54:55]
	v_lshlrev_b64 v[56:57], 13, v[56:57]
	v_lshlrev_b64 v[58:59], 13, v[58:59]
	v_lshlrev_b64 v[60:61], 13, v[60:61]
	v_lshlrev_b64 v[62:63], 13, v[62:63]
	v_lshlrev_b64 v[64:65], 13, v[64:65]
	v_lshlrev_b64 v[66:67], 13, v[66:67]
	v_lshlrev_b64 v[68:69], 13, v[68:69]
	v_lshlrev_b64 v[70:71], 13, v[70:71]
	v_lshlrev_b64 v[72:73], 13, v[72:73]
	v_lshlrev_b64 v[74:75], 13, v[74:75]
	v_lshl_add_u64 v[46:47], v[24:25], 0, v[46:47]
	v_lshl_add_u64 v[44:45], v[24:25], 0, v[44:45]
	v_lshl_add_u64 v[50:51], v[24:25], 0, v[50:51]
	v_lshl_add_u64 v[48:49], v[24:25], 0, v[48:49]
	v_lshl_add_u64 v[54:55], v[24:25], 0, v[54:55]
	v_lshl_add_u64 v[52:53], v[24:25], 0, v[52:53]
	v_lshl_add_u64 v[58:59], v[24:25], 0, v[58:59]
	v_lshl_add_u64 v[56:57], v[24:25], 0, v[56:57]
	v_lshl_add_u64 v[62:63], v[24:25], 0, v[62:63]
	v_lshl_add_u64 v[60:61], v[24:25], 0, v[60:61]
	v_lshl_add_u64 v[66:67], v[24:25], 0, v[66:67]
	v_lshl_add_u64 v[64:65], v[24:25], 0, v[64:65]
	v_lshl_add_u64 v[70:71], v[24:25], 0, v[70:71]
	v_lshl_add_u64 v[68:69], v[24:25], 0, v[68:69]
	v_lshl_add_u64 v[74:75], v[24:25], 0, v[74:75]
	v_lshl_add_u64 v[72:73], v[24:25], 0, v[72:73]
	global_load_dword v188, v[46:47], off
	global_load_dword v189, v[44:45], off
	global_load_dword v190, v[50:51], off
	global_load_dword v191, v[48:49], off
	global_load_dword v192, v[54:55], off
	global_load_dword v193, v[52:53], off
	global_load_dword v194, v[58:59], off
	global_load_dword v195, v[56:57], off
	global_load_dword v196, v[62:63], off
	global_load_dword v197, v[60:61], off
	global_load_dword v198, v[66:67], off
	global_load_dword v199, v[64:65], off
	global_load_dword v200, v[70:71], off
	global_load_dword v201, v[68:69], off
	global_load_dword v202, v[74:75], off
	global_load_dword v203, v[72:73], off
	s_add_i32 s3, s3, 16
	s_add_i32 s2, s2, 16
	s_lshl_b32 s9, s3, 1
	s_lshl_b32 s10, s2, 1
	v_add_u32_e32 v46, s9, v26
	v_add_u32_e32 v44, s10, v21
	v_add_u32_e32 v48, s10, v23
	v_add_u32_e32 v50, s9, v28
	v_add_u32_e32 v52, s10, v27
	v_add_u32_e32 v54, s9, v30
	v_add_u32_e32 v56, s10, v29
	v_add_u32_e32 v58, s9, v32
	v_add_u32_e32 v60, s10, v31
	v_add_u32_e32 v62, s9, v34
	v_add_u32_e32 v64, s10, v33
	v_add_u32_e32 v66, s9, v36
	v_add_u32_e32 v68, s10, v35
	v_add_u32_e32 v70, s9, v38
	v_add_u32_e32 v72, s10, v37
	v_add_u32_e32 v74, s9, v40
	v_ashrrev_i32_e32 v47, 31, v46
	v_ashrrev_i32_e32 v45, 31, v44
	v_ashrrev_i32_e32 v51, 31, v50
	v_ashrrev_i32_e32 v49, 31, v48
	v_ashrrev_i32_e32 v55, 31, v54
	v_ashrrev_i32_e32 v53, 31, v52
	v_ashrrev_i32_e32 v59, 31, v58
	v_ashrrev_i32_e32 v57, 31, v56
	v_ashrrev_i32_e32 v63, 31, v62
	v_ashrrev_i32_e32 v61, 31, v60
	v_ashrrev_i32_e32 v67, 31, v66
	v_ashrrev_i32_e32 v65, 31, v64
	v_ashrrev_i32_e32 v71, 31, v70
	v_ashrrev_i32_e32 v69, 31, v68
	v_ashrrev_i32_e32 v75, 31, v74
	v_ashrrev_i32_e32 v73, 31, v72
	v_lshlrev_b64 v[46:47], 13, v[46:47]
	v_lshlrev_b64 v[44:45], 13, v[44:45]
	v_lshlrev_b64 v[48:49], 13, v[48:49]
	v_lshlrev_b64 v[50:51], 13, v[50:51]
	v_lshlrev_b64 v[52:53], 13, v[52:53]
	v_lshlrev_b64 v[54:55], 13, v[54:55]
	v_lshlrev_b64 v[56:57], 13, v[56:57]
	v_lshlrev_b64 v[58:59], 13, v[58:59]
	v_lshlrev_b64 v[60:61], 13, v[60:61]
	v_lshlrev_b64 v[62:63], 13, v[62:63]
	v_lshlrev_b64 v[64:65], 13, v[64:65]
	v_lshlrev_b64 v[66:67], 13, v[66:67]
	v_lshlrev_b64 v[68:69], 13, v[68:69]
	v_lshlrev_b64 v[70:71], 13, v[70:71]
	v_lshlrev_b64 v[72:73], 13, v[72:73]
	v_lshlrev_b64 v[74:75], 13, v[74:75]
	v_lshl_add_u64 v[46:47], v[24:25], 0, v[46:47]
	v_lshl_add_u64 v[44:45], v[24:25], 0, v[44:45]
	v_lshl_add_u64 v[50:51], v[24:25], 0, v[50:51]
	v_lshl_add_u64 v[48:49], v[24:25], 0, v[48:49]
	v_lshl_add_u64 v[54:55], v[24:25], 0, v[54:55]
	v_lshl_add_u64 v[52:53], v[24:25], 0, v[52:53]
	v_lshl_add_u64 v[58:59], v[24:25], 0, v[58:59]
	v_lshl_add_u64 v[56:57], v[24:25], 0, v[56:57]
	v_lshl_add_u64 v[62:63], v[24:25], 0, v[62:63]
	v_lshl_add_u64 v[60:61], v[24:25], 0, v[60:61]
	v_lshl_add_u64 v[66:67], v[24:25], 0, v[66:67]
	v_lshl_add_u64 v[64:65], v[24:25], 0, v[64:65]
	v_lshl_add_u64 v[70:71], v[24:25], 0, v[70:71]
	v_lshl_add_u64 v[68:69], v[24:25], 0, v[68:69]
	v_lshl_add_u64 v[74:75], v[24:25], 0, v[74:75]
	v_lshl_add_u64 v[72:73], v[24:25], 0, v[72:73]
	global_load_dword v204, v[46:47], off
	global_load_dword v205, v[44:45], off
	global_load_dword v206, v[50:51], off
	global_load_dword v207, v[48:49], off
	global_load_dword v208, v[54:55], off
	global_load_dword v209, v[52:53], off
	global_load_dword v210, v[58:59], off
	global_load_dword v211, v[56:57], off
	global_load_dword v212, v[62:63], off
	global_load_dword v213, v[60:61], off
	global_load_dword v214, v[66:67], off
	global_load_dword v215, v[64:65], off
	global_load_dword v216, v[70:71], off
	global_load_dword v217, v[68:69], off
	global_load_dword v218, v[74:75], off
	global_load_dword v219, v[72:73], off
	s_mov_b32 s9, s98
	s_mov_b32 s10, s99
	v_add_u32_e32 v44, s9, v2
	v_add_u32_e32 v46, s10, v1
	v_add_u32_e32 v50, s10, v3
	v_add_u32_e32 v48, s9, v10
	v_add_u32_e32 v54, s10, v7
	v_add_u32_e32 v52, s9, v12
	v_add_u32_e32 v58, s10, v11
	v_add_u32_e32 v56, s9, v14
	v_add_u32_e32 v62, s10, v13
	v_add_u32_e32 v60, s9, v16
	v_add_u32_e32 v66, s10, v15
	v_add_u32_e32 v64, s9, v18
	v_add_u32_e32 v70, s10, v17
	v_add_u32_e32 v68, s9, v20
	v_add_u32_e32 v74, s10, v19
	v_add_u32_e32 v72, s9, v22
	v_mad_u64_u32 v[44:45], s[16:17], v44, s95, v[6:7]
	v_mad_u64_u32 v[46:47], s[16:17], v46, s95, v[6:7]
	v_mad_u64_u32 v[48:49], s[16:17], v48, s95, v[6:7]
	v_mad_u64_u32 v[50:51], s[16:17], v50, s95, v[6:7]
	v_mad_u64_u32 v[52:53], s[16:17], v52, s95, v[6:7]
	v_mad_u64_u32 v[54:55], s[16:17], v54, s95, v[6:7]
	v_mad_u64_u32 v[56:57], s[16:17], v56, s95, v[6:7]
	v_mad_u64_u32 v[58:59], s[16:17], v58, s95, v[6:7]
	v_mad_u64_u32 v[60:61], s[16:17], v60, s95, v[6:7]
	v_mad_u64_u32 v[62:63], s[16:17], v62, s95, v[6:7]
	v_mad_u64_u32 v[64:65], s[16:17], v64, s95, v[6:7]
	v_mad_u64_u32 v[66:67], s[16:17], v66, s95, v[6:7]
	v_mad_u64_u32 v[68:69], s[16:17], v68, s95, v[6:7]
	v_mad_u64_u32 v[70:71], s[16:17], v70, s95, v[6:7]
	v_mad_u64_u32 v[72:73], s[16:17], v72, s95, v[6:7]
	v_mad_u64_u32 v[74:75], s[16:17], v74, s95, v[6:7]
	s_waitcnt vmcnt(31)
	ds_write_b32 v44, v188
	s_waitcnt vmcnt(30)
	ds_write_b32 v46, v189
	s_waitcnt vmcnt(29)
	ds_write_b32 v48, v190
	s_waitcnt vmcnt(28)
	ds_write_b32 v50, v191
	s_waitcnt vmcnt(27)
	ds_write_b32 v52, v192
	s_waitcnt vmcnt(26)
	ds_write_b32 v54, v193
	s_waitcnt vmcnt(25)
	ds_write_b32 v56, v194
	s_waitcnt vmcnt(24)
	ds_write_b32 v58, v195
	s_waitcnt vmcnt(23)
	ds_write_b32 v60, v196
	s_waitcnt vmcnt(22)
	ds_write_b32 v62, v197
	s_waitcnt vmcnt(21)
	ds_write_b32 v64, v198
	s_waitcnt vmcnt(20)
	ds_write_b32 v66, v199
	s_waitcnt vmcnt(19)
	ds_write_b32 v68, v200
	s_waitcnt vmcnt(18)
	ds_write_b32 v70, v201
	s_waitcnt vmcnt(17)
	ds_write_b32 v72, v202
	s_waitcnt vmcnt(16)
	ds_write_b32 v74, v203
	s_lshl_b32 s9, s3, 1
	s_lshl_b32 s10, s2, 1
	v_add_u32_e32 v44, s9, v2
	v_add_u32_e32 v46, s10, v1
	v_add_u32_e32 v50, s10, v3
	v_add_u32_e32 v48, s9, v10
	v_add_u32_e32 v54, s10, v7
	v_add_u32_e32 v52, s9, v12
	v_add_u32_e32 v58, s10, v11
	v_add_u32_e32 v56, s9, v14
	v_add_u32_e32 v62, s10, v13
	v_add_u32_e32 v60, s9, v16
	v_add_u32_e32 v66, s10, v15
	v_add_u32_e32 v64, s9, v18
	v_add_u32_e32 v70, s10, v17
	v_add_u32_e32 v68, s9, v20
	v_add_u32_e32 v74, s10, v19
	v_add_u32_e32 v72, s9, v22
	v_mad_u64_u32 v[44:45], s[16:17], v44, s95, v[6:7]
	v_mad_u64_u32 v[46:47], s[16:17], v46, s95, v[6:7]
	v_mad_u64_u32 v[48:49], s[16:17], v48, s95, v[6:7]
	v_mad_u64_u32 v[50:51], s[16:17], v50, s95, v[6:7]
	v_mad_u64_u32 v[52:53], s[16:17], v52, s95, v[6:7]
	v_mad_u64_u32 v[54:55], s[16:17], v54, s95, v[6:7]
	v_mad_u64_u32 v[56:57], s[16:17], v56, s95, v[6:7]
	v_mad_u64_u32 v[58:59], s[16:17], v58, s95, v[6:7]
	v_mad_u64_u32 v[60:61], s[16:17], v60, s95, v[6:7]
	v_mad_u64_u32 v[62:63], s[16:17], v62, s95, v[6:7]
	v_mad_u64_u32 v[64:65], s[16:17], v64, s95, v[6:7]
	v_mad_u64_u32 v[66:67], s[16:17], v66, s95, v[6:7]
	v_mad_u64_u32 v[68:69], s[16:17], v68, s95, v[6:7]
	v_mad_u64_u32 v[70:71], s[16:17], v70, s95, v[6:7]
	v_mad_u64_u32 v[72:73], s[16:17], v72, s95, v[6:7]
	v_mad_u64_u32 v[74:75], s[16:17], v74, s95, v[6:7]
	s_waitcnt vmcnt(15)
	ds_write_b32 v44, v204
	s_waitcnt vmcnt(14)
	ds_write_b32 v46, v205
	s_waitcnt vmcnt(13)
	ds_write_b32 v48, v206
	s_waitcnt vmcnt(12)
	ds_write_b32 v50, v207
	s_waitcnt vmcnt(11)
	ds_write_b32 v52, v208
	s_waitcnt vmcnt(10)
	ds_write_b32 v54, v209
	s_waitcnt vmcnt(9)
	ds_write_b32 v56, v210
	s_waitcnt vmcnt(8)
	ds_write_b32 v58, v211
	s_waitcnt vmcnt(7)
	ds_write_b32 v60, v212
	s_waitcnt vmcnt(6)
	ds_write_b32 v62, v213
	s_waitcnt vmcnt(5)
	ds_write_b32 v64, v214
	s_waitcnt vmcnt(4)
	ds_write_b32 v66, v215
	s_waitcnt vmcnt(3)
	ds_write_b32 v68, v216
	s_waitcnt vmcnt(2)
	ds_write_b32 v70, v217
	s_waitcnt vmcnt(1)
	ds_write_b32 v72, v218
	s_waitcnt vmcnt(0)
	ds_write_b32 v74, v219
	s_add_i32 s3, s3, 16
	s_add_i32 s2, s2, 16
	s_add_i32 s7, s7, -16
	s_add_i32 s7, s7, -16
	s_cmp_lg_u32 s7, 0
	s_waitcnt lgkmcnt(0)
	ds_read2_b32 v[28:29], v42 offset0:33 offset1:41
	ds_read2_b32 v[30:31], v42 offset1:8
	ds_read2_b32 v[32:33], v42 offset0:66 offset1:74
	ds_read2_b32 v[34:35], v42 offset0:99 offset1:107
	ds_read2_b32 v[36:37], v42 offset0:132 offset1:140
	ds_read2_b32 v[44:45], v42 offset0:165 offset1:173
	ds_read2_b32 v[46:47], v42 offset0:198 offset1:206
	ds_read2_b32 v[48:49], v42 offset0:231 offset1:239
	v_add_u32_e32 v52, s8, v41
	s_ashr_i32 s13, s12, 31
	v_ashrrev_i32_e32 v53, 31, v52
	v_lshl_add_u64 v[50:51], s[12:13], 1, v[8:9]
	v_lshlrev_b64 v[54:55], 13, v[52:53]
	s_waitcnt lgkmcnt(6)
	v_cvt_pk_bf16_f32 v24, v30, v28
	s_waitcnt lgkmcnt(4)
	v_cvt_pk_bf16_f32 v25, v32, v34
	s_waitcnt lgkmcnt(2)
	v_cvt_pk_bf16_f32 v26, v36, v44
	s_waitcnt lgkmcnt(0)
	v_cvt_pk_bf16_f32 v27, v46, v48
	v_lshl_add_u64 v[54:55], v[50:51], 0, v[54:55]
	v_add_u32_e32 v28, 8, v52
	global_store_dwordx4 v[54:55], v[24:27], off
	s_add_i32 s0, s0, s81
	s_cmpk_gt_i32 s0, 0xfff
	v_cvt_pk_bf16_f32 v24, v31, v29
	v_ashrrev_i32_e32 v29, 31, v28
	v_cvt_pk_bf16_f32 v25, v33, v35
	v_cvt_pk_bf16_f32 v26, v37, v45
	v_cvt_pk_bf16_f32 v27, v47, v49
	v_lshlrev_b64 v[28:29], 13, v[28:29]
	ds_read2_b32 v[30:31], v42 offset0:49 offset1:57
	ds_read2_b32 v[32:33], v42 offset0:16 offset1:24
	ds_read2_b32 v[34:35], v42 offset0:82 offset1:90
	ds_read2_b32 v[36:37], v42 offset0:115 offset1:123
	ds_read2_b32 v[44:45], v42 offset0:148 offset1:156
	ds_read2_b32 v[46:47], v42 offset0:181 offset1:189
	ds_read2_b32 v[48:49], v42 offset0:214 offset1:222
	ds_read2_b32 v[54:55], v42 offset0:247 offset1:255
	v_lshl_add_u64 v[28:29], v[50:51], 0, v[28:29]
	global_store_dwordx4 v[28:29], v[24:27], off
	v_add_u32_e32 v28, 16, v52
	v_ashrrev_i32_e32 v29, 31, v28
	v_lshlrev_b64 v[28:29], 13, v[28:29]
	s_waitcnt lgkmcnt(6)
	v_cvt_pk_bf16_f32 v24, v32, v30
	s_waitcnt lgkmcnt(4)
	v_cvt_pk_bf16_f32 v25, v34, v36
	s_waitcnt lgkmcnt(2)
	v_cvt_pk_bf16_f32 v26, v44, v46
	s_waitcnt lgkmcnt(0)
	v_cvt_pk_bf16_f32 v27, v48, v54
	v_lshl_add_u64 v[28:29], v[50:51], 0, v[28:29]
	global_store_dwordx4 v[28:29], v[24:27], off
	v_add_u32_e32 v28, 24, v52
	v_ashrrev_i32_e32 v29, 31, v28
	v_lshlrev_b64 v[28:29], 13, v[28:29]
	v_cvt_pk_bf16_f32 v24, v33, v31
	v_cvt_pk_bf16_f32 v25, v35, v37
	v_cvt_pk_bf16_f32 v26, v45, v47
	v_cvt_pk_bf16_f32 v27, v49, v55
	v_lshl_add_u64 v[28:29], v[50:51], 0, v[28:29]
	global_store_dwordx4 v[28:29], v[24:27], off
	s_waitcnt lgkmcnt(0)
	s_cbranch_scc0 .LBB0_145

.LBB0_151:
	s_lshl_b32 s10, s7, 1
	s_lshl_b32 s16, s3, 1
	s_mov_b32 s98, s10
	s_mov_b32 s99, s16
	v_add_u32_e32 v44, s10, v26
	v_add_u32_e32 v46, s16, v17
	v_add_u32_e32 v50, s16, v19
	v_add_u32_e32 v48, s10, v28
	v_add_u32_e32 v54, s16, v27
	v_add_u32_e32 v52, s10, v30
	v_add_u32_e32 v58, s16, v29
	v_add_u32_e32 v56, s10, v32
	v_add_u32_e32 v62, s16, v31
	v_add_u32_e32 v60, s10, v34
	v_add_u32_e32 v66, s16, v33
	v_add_u32_e32 v64, s10, v36
	v_add_u32_e32 v70, s16, v35
	v_add_u32_e32 v68, s10, v38
	v_add_u32_e32 v74, s16, v37
	v_add_u32_e32 v72, s10, v40
	v_mad_i64_i32 v[44:45], s[12:13], v44, s15, v[24:25]
	v_mad_i64_i32 v[46:47], s[12:13], v46, s15, v[24:25]
	v_mad_i64_i32 v[48:49], s[12:13], v48, s15, v[24:25]
	v_mad_i64_i32 v[50:51], s[12:13], v50, s15, v[24:25]
	v_mad_i64_i32 v[52:53], s[12:13], v52, s15, v[24:25]
	v_mad_i64_i32 v[54:55], s[12:13], v54, s15, v[24:25]
	v_mad_i64_i32 v[56:57], s[12:13], v56, s15, v[24:25]
	v_mad_i64_i32 v[58:59], s[12:13], v58, s15, v[24:25]
	v_mad_i64_i32 v[60:61], s[12:13], v60, s15, v[24:25]
	v_mad_i64_i32 v[62:63], s[12:13], v62, s15, v[24:25]
	v_mad_i64_i32 v[64:65], s[12:13], v64, s15, v[24:25]
	v_mad_i64_i32 v[66:67], s[12:13], v66, s15, v[24:25]
	v_mad_i64_i32 v[68:69], s[12:13], v68, s15, v[24:25]
	v_mad_i64_i32 v[70:71], s[12:13], v70, s15, v[24:25]
	v_mad_i64_i32 v[72:73], s[12:13], v72, s15, v[24:25]
	v_mad_i64_i32 v[74:75], s[12:13], v74, s15, v[24:25]
	global_load_dword v188, v[44:45], off
	global_load_dword v189, v[46:47], off
	global_load_dword v190, v[48:49], off
	global_load_dword v191, v[50:51], off
	global_load_dword v192, v[52:53], off
	global_load_dword v193, v[54:55], off
	global_load_dword v194, v[56:57], off
	global_load_dword v195, v[58:59], off
	global_load_dword v196, v[60:61], off
	global_load_dword v197, v[62:63], off
	global_load_dword v198, v[64:65], off
	global_load_dword v199, v[66:67], off
	global_load_dword v200, v[68:69], off
	global_load_dword v201, v[70:71], off
	global_load_dword v202, v[72:73], off
	global_load_dword v203, v[74:75], off
	s_add_i32 s7, s7, 16
	s_add_i32 s3, s3, 16
	s_lshl_b32 s10, s7, 1
	s_lshl_b32 s16, s3, 1
	v_add_u32_e32 v44, s10, v26
	v_add_u32_e32 v46, s16, v17
	v_add_u32_e32 v50, s16, v19
	v_add_u32_e32 v48, s10, v28
	v_add_u32_e32 v54, s16, v27
	v_add_u32_e32 v52, s10, v30
	v_add_u32_e32 v58, s16, v29
	v_add_u32_e32 v56, s10, v32
	v_add_u32_e32 v62, s16, v31
	v_add_u32_e32 v60, s10, v34
	v_add_u32_e32 v66, s16, v33
	v_add_u32_e32 v64, s10, v36
	v_add_u32_e32 v70, s16, v35
	v_add_u32_e32 v68, s10, v38
	v_add_u32_e32 v74, s16, v37
	v_add_u32_e32 v72, s10, v40
	v_mad_i64_i32 v[44:45], s[12:13], v44, s15, v[24:25]
	v_mad_i64_i32 v[46:47], s[12:13], v46, s15, v[24:25]
	v_mad_i64_i32 v[48:49], s[12:13], v48, s15, v[24:25]
	v_mad_i64_i32 v[50:51], s[12:13], v50, s15, v[24:25]
	v_mad_i64_i32 v[52:53], s[12:13], v52, s15, v[24:25]
	v_mad_i64_i32 v[54:55], s[12:13], v54, s15, v[24:25]
	v_mad_i64_i32 v[56:57], s[12:13], v56, s15, v[24:25]
	v_mad_i64_i32 v[58:59], s[12:13], v58, s15, v[24:25]
	v_mad_i64_i32 v[60:61], s[12:13], v60, s15, v[24:25]
	v_mad_i64_i32 v[62:63], s[12:13], v62, s15, v[24:25]
	v_mad_i64_i32 v[64:65], s[12:13], v64, s15, v[24:25]
	v_mad_i64_i32 v[66:67], s[12:13], v66, s15, v[24:25]
	v_mad_i64_i32 v[68:69], s[12:13], v68, s15, v[24:25]
	v_mad_i64_i32 v[70:71], s[12:13], v70, s15, v[24:25]
	v_mad_i64_i32 v[72:73], s[12:13], v72, s15, v[24:25]
	v_mad_i64_i32 v[74:75], s[12:13], v74, s15, v[24:25]
	global_load_dword v204, v[44:45], off
	global_load_dword v205, v[46:47], off
	global_load_dword v206, v[48:49], off
	global_load_dword v207, v[50:51], off
	global_load_dword v208, v[52:53], off
	global_load_dword v209, v[54:55], off
	global_load_dword v210, v[56:57], off
	global_load_dword v211, v[58:59], off
	global_load_dword v212, v[60:61], off
	global_load_dword v213, v[62:63], off
	global_load_dword v214, v[64:65], off
	global_load_dword v215, v[66:67], off
	global_load_dword v216, v[68:69], off
	global_load_dword v217, v[70:71], off
	global_load_dword v218, v[72:73], off
	global_load_dword v219, v[74:75], off
	s_mov_b32 s10, s98
	s_mov_b32 s16, s99
	v_add_u32_e32 v44, s10, v2
	v_add_u32_e32 v46, s16, v1
	v_add_u32_e32 v50, s16, v3
	v_add_u32_e32 v48, s10, v4
	v_add_u32_e32 v54, s16, v5
	v_add_u32_e32 v52, s10, v6
	v_add_u32_e32 v58, s16, v7
	v_add_u32_e32 v56, s10, v8
	v_add_u32_e32 v62, s16, v9
	v_add_u32_e32 v60, s10, v10
	v_add_u32_e32 v66, s16, v11
	v_add_u32_e32 v64, s10, v12
	v_add_u32_e32 v70, s16, v13
	v_add_u32_e32 v68, s10, v14
	v_add_u32_e32 v74, s16, v15
	v_add_u32_e32 v72, s10, v16
	v_mad_u64_u32 v[44:45], s[12:13], v44, s95, v[18:19]
	v_mad_u64_u32 v[46:47], s[12:13], v46, s95, v[18:19]
	v_mad_u64_u32 v[48:49], s[12:13], v48, s95, v[18:19]
	v_mad_u64_u32 v[50:51], s[12:13], v50, s95, v[18:19]
	v_mad_u64_u32 v[52:53], s[12:13], v52, s95, v[18:19]
	v_mad_u64_u32 v[54:55], s[12:13], v54, s95, v[18:19]
	v_mad_u64_u32 v[56:57], s[12:13], v56, s95, v[18:19]
	v_mad_u64_u32 v[58:59], s[12:13], v58, s95, v[18:19]
	v_mad_u64_u32 v[60:61], s[12:13], v60, s95, v[18:19]
	v_mad_u64_u32 v[62:63], s[12:13], v62, s95, v[18:19]
	v_mad_u64_u32 v[64:65], s[12:13], v64, s95, v[18:19]
	v_mad_u64_u32 v[66:67], s[12:13], v66, s95, v[18:19]
	v_mad_u64_u32 v[68:69], s[12:13], v68, s95, v[18:19]
	v_mad_u64_u32 v[70:71], s[12:13], v70, s95, v[18:19]
	v_mad_u64_u32 v[72:73], s[12:13], v72, s95, v[18:19]
	v_mad_u64_u32 v[74:75], s[12:13], v74, s95, v[18:19]
	s_waitcnt vmcnt(31)
	ds_write_b32 v44, v188
	s_waitcnt vmcnt(30)
	ds_write_b32 v46, v189
	s_waitcnt vmcnt(29)
	ds_write_b32 v48, v190
	s_waitcnt vmcnt(28)
	ds_write_b32 v50, v191
	s_waitcnt vmcnt(27)
	ds_write_b32 v52, v192
	s_waitcnt vmcnt(26)
	ds_write_b32 v54, v193
	s_waitcnt vmcnt(25)
	ds_write_b32 v56, v194
	s_waitcnt vmcnt(24)
	ds_write_b32 v58, v195
	s_waitcnt vmcnt(23)
	ds_write_b32 v60, v196
	s_waitcnt vmcnt(22)
	ds_write_b32 v62, v197
	s_waitcnt vmcnt(21)
	ds_write_b32 v64, v198
	s_waitcnt vmcnt(20)
	ds_write_b32 v66, v199
	s_waitcnt vmcnt(19)
	ds_write_b32 v68, v200
	s_waitcnt vmcnt(18)
	ds_write_b32 v70, v201
	s_waitcnt vmcnt(17)
	ds_write_b32 v72, v202
	s_waitcnt vmcnt(16)
	ds_write_b32 v74, v203
	s_lshl_b32 s10, s7, 1
	s_lshl_b32 s16, s3, 1
	v_add_u32_e32 v44, s10, v2
	v_add_u32_e32 v46, s16, v1
	v_add_u32_e32 v50, s16, v3
	v_add_u32_e32 v48, s10, v4
	v_add_u32_e32 v54, s16, v5
	v_add_u32_e32 v52, s10, v6
	v_add_u32_e32 v58, s16, v7
	v_add_u32_e32 v56, s10, v8
	v_add_u32_e32 v62, s16, v9
	v_add_u32_e32 v60, s10, v10
	v_add_u32_e32 v66, s16, v11
	v_add_u32_e32 v64, s10, v12
	v_add_u32_e32 v70, s16, v13
	v_add_u32_e32 v68, s10, v14
	v_add_u32_e32 v74, s16, v15
	v_add_u32_e32 v72, s10, v16
	v_mad_u64_u32 v[44:45], s[12:13], v44, s95, v[18:19]
	v_mad_u64_u32 v[46:47], s[12:13], v46, s95, v[18:19]
	v_mad_u64_u32 v[48:49], s[12:13], v48, s95, v[18:19]
	v_mad_u64_u32 v[50:51], s[12:13], v50, s95, v[18:19]
	v_mad_u64_u32 v[52:53], s[12:13], v52, s95, v[18:19]
	v_mad_u64_u32 v[54:55], s[12:13], v54, s95, v[18:19]
	v_mad_u64_u32 v[56:57], s[12:13], v56, s95, v[18:19]
	v_mad_u64_u32 v[58:59], s[12:13], v58, s95, v[18:19]
	v_mad_u64_u32 v[60:61], s[12:13], v60, s95, v[18:19]
	v_mad_u64_u32 v[62:63], s[12:13], v62, s95, v[18:19]
	v_mad_u64_u32 v[64:65], s[12:13], v64, s95, v[18:19]
	v_mad_u64_u32 v[66:67], s[12:13], v66, s95, v[18:19]
	v_mad_u64_u32 v[68:69], s[12:13], v68, s95, v[18:19]
	v_mad_u64_u32 v[70:71], s[12:13], v70, s95, v[18:19]
	v_mad_u64_u32 v[72:73], s[12:13], v72, s95, v[18:19]
	v_mad_u64_u32 v[74:75], s[12:13], v74, s95, v[18:19]
	s_waitcnt vmcnt(15)
	ds_write_b32 v44, v204
	s_waitcnt vmcnt(14)
	ds_write_b32 v46, v205
	s_waitcnt vmcnt(13)
	ds_write_b32 v48, v206
	s_waitcnt vmcnt(12)
	ds_write_b32 v50, v207
	s_waitcnt vmcnt(11)
	ds_write_b32 v52, v208
	s_waitcnt vmcnt(10)
	ds_write_b32 v54, v209
	s_waitcnt vmcnt(9)
	ds_write_b32 v56, v210
	s_waitcnt vmcnt(8)
	ds_write_b32 v58, v211
	s_waitcnt vmcnt(7)
	ds_write_b32 v60, v212
	s_waitcnt vmcnt(6)
	ds_write_b32 v62, v213
	s_waitcnt vmcnt(5)
	ds_write_b32 v64, v214
	s_waitcnt vmcnt(4)
	ds_write_b32 v66, v215
	s_waitcnt vmcnt(3)
	ds_write_b32 v68, v216
	s_waitcnt vmcnt(2)
	ds_write_b32 v70, v217
	s_waitcnt vmcnt(1)
	ds_write_b32 v72, v218
	s_waitcnt vmcnt(0)
	ds_write_b32 v74, v219
	s_add_i32 s7, s7, 16
	s_add_i32 s3, s3, 16
	s_add_i32 s9, s9, -16
	s_add_i32 s9, s9, -16
	s_cmp_lg_u32 s9, 0
	s_waitcnt lgkmcnt(0)
	ds_read2_b32 v[28:29], v43 offset0:33 offset1:41
	ds_read2_b32 v[30:31], v43 offset1:8
	ds_read2_b32 v[32:33], v43 offset0:66 offset1:74
	ds_read2_b32 v[34:35], v43 offset0:99 offset1:107
	ds_read2_b32 v[36:37], v43 offset0:132 offset1:140
	ds_read2_b32 v[44:45], v43 offset0:165 offset1:173
	ds_read2_b32 v[46:47], v43 offset0:198 offset1:206
	ds_read2_b32 v[48:49], v43 offset0:231 offset1:239
	v_lshl_add_u32 v52, s2, 5, v41
	s_ashr_i32 s9, s8, 31
	v_ashrrev_i32_e32 v53, 31, v52
	v_lshl_add_u64 v[50:51], s[8:9], 1, v[22:23]
	v_lshlrev_b64 v[54:55], 12, v[52:53]
	s_waitcnt lgkmcnt(6)
	v_cvt_pk_bf16_f32 v24, v30, v28
	s_waitcnt lgkmcnt(4)
	v_cvt_pk_bf16_f32 v25, v32, v34
	s_waitcnt lgkmcnt(2)
	v_cvt_pk_bf16_f32 v26, v36, v44
	s_waitcnt lgkmcnt(0)
	v_cvt_pk_bf16_f32 v27, v46, v48
	v_lshl_add_u64 v[54:55], v[50:51], 0, v[54:55]
	v_add_u32_e32 v28, 8, v52
	global_store_dwordx4 v[54:55], v[24:27], off
	s_add_i32 s0, s0, s81
	s_cmpk_lt_i32 s0, 0x2b00
	v_cvt_pk_bf16_f32 v24, v31, v29
	v_ashrrev_i32_e32 v29, 31, v28
	v_cvt_pk_bf16_f32 v25, v33, v35
	v_cvt_pk_bf16_f32 v26, v37, v45
	v_cvt_pk_bf16_f32 v27, v47, v49
	v_lshlrev_b64 v[28:29], 12, v[28:29]
	ds_read2_b32 v[30:31], v43 offset0:49 offset1:57
	ds_read2_b32 v[32:33], v43 offset0:16 offset1:24
	ds_read2_b32 v[34:35], v43 offset0:82 offset1:90
	ds_read2_b32 v[36:37], v43 offset0:115 offset1:123
	ds_read2_b32 v[44:45], v43 offset0:148 offset1:156
	ds_read2_b32 v[46:47], v43 offset0:181 offset1:189
	ds_read2_b32 v[48:49], v43 offset0:214 offset1:222
	ds_read2_b32 v[54:55], v43 offset0:247 offset1:255
	v_lshl_add_u64 v[28:29], v[50:51], 0, v[28:29]
	global_store_dwordx4 v[28:29], v[24:27], off
	v_add_u32_e32 v28, 16, v52
	v_ashrrev_i32_e32 v29, 31, v28
	v_lshlrev_b64 v[28:29], 12, v[28:29]
	s_waitcnt lgkmcnt(6)
	v_cvt_pk_bf16_f32 v24, v32, v30
	s_waitcnt lgkmcnt(4)
	v_cvt_pk_bf16_f32 v25, v34, v36
	s_waitcnt lgkmcnt(2)
	v_cvt_pk_bf16_f32 v26, v44, v46
	s_waitcnt lgkmcnt(0)
	v_cvt_pk_bf16_f32 v27, v48, v54
	v_lshl_add_u64 v[28:29], v[50:51], 0, v[28:29]
	global_store_dwordx4 v[28:29], v[24:27], off
	v_add_u32_e32 v28, 24, v52
	v_ashrrev_i32_e32 v29, 31, v28
	v_lshlrev_b64 v[28:29], 12, v[28:29]
	v_cvt_pk_bf16_f32 v24, v33, v31
	v_cvt_pk_bf16_f32 v25, v35, v37
	v_cvt_pk_bf16_f32 v26, v45, v47
	v_cvt_pk_bf16_f32 v27, v49, v55
	v_lshl_add_u64 v[28:29], v[50:51], 0, v[28:29]
	global_store_dwordx4 v[28:29], v[24:27], off
	s_waitcnt lgkmcnt(0)
	s_cbranch_scc1 .LBB0_150

.LBB0_156:
	s_lshl_b32 s9, s3, 1
	s_lshl_b32 s10, s2, 1
	s_mov_b32 s98, s9
	s_mov_b32 s99, s10
	v_add_u32_e32 v46, s9, v26
	v_add_u32_e32 v44, s10, v17
	v_add_u32_e32 v48, s10, v19
	v_add_u32_e32 v50, s9, v28
	v_add_u32_e32 v52, s10, v27
	v_add_u32_e32 v54, s9, v30
	v_add_u32_e32 v56, s10, v29
	v_add_u32_e32 v58, s9, v32
	v_add_u32_e32 v60, s10, v31
	v_add_u32_e32 v62, s9, v34
	v_add_u32_e32 v64, s10, v33
	v_add_u32_e32 v66, s9, v36
	v_add_u32_e32 v68, s10, v35
	v_add_u32_e32 v70, s9, v38
	v_add_u32_e32 v72, s10, v37
	v_add_u32_e32 v74, s9, v40
	v_ashrrev_i32_e32 v47, 31, v46
	v_ashrrev_i32_e32 v45, 31, v44
	v_ashrrev_i32_e32 v51, 31, v50
	v_ashrrev_i32_e32 v49, 31, v48
	v_ashrrev_i32_e32 v55, 31, v54
	v_ashrrev_i32_e32 v53, 31, v52
	v_ashrrev_i32_e32 v59, 31, v58
	v_ashrrev_i32_e32 v57, 31, v56
	v_ashrrev_i32_e32 v63, 31, v62
	v_ashrrev_i32_e32 v61, 31, v60
	v_ashrrev_i32_e32 v67, 31, v66
	v_ashrrev_i32_e32 v65, 31, v64
	v_ashrrev_i32_e32 v71, 31, v70
	v_ashrrev_i32_e32 v69, 31, v68
	v_ashrrev_i32_e32 v75, 31, v74
	v_ashrrev_i32_e32 v73, 31, v72
	v_lshlrev_b64 v[46:47], 13, v[46:47]
	v_lshlrev_b64 v[44:45], 13, v[44:45]
	v_lshlrev_b64 v[48:49], 13, v[48:49]
	v_lshlrev_b64 v[50:51], 13, v[50:51]
	v_lshlrev_b64 v[52:53], 13, v[52:53]
	v_lshlrev_b64 v[54:55], 13, v[54:55]
	v_lshlrev_b64 v[56:57], 13, v[56:57]
	v_lshlrev_b64 v[58:59], 13, v[58:59]
	v_lshlrev_b64 v[60:61], 13, v[60:61]
	v_lshlrev_b64 v[62:63], 13, v[62:63]
	v_lshlrev_b64 v[64:65], 13, v[64:65]
	v_lshlrev_b64 v[66:67], 13, v[66:67]
	v_lshlrev_b64 v[68:69], 13, v[68:69]
	v_lshlrev_b64 v[70:71], 13, v[70:71]
	v_lshlrev_b64 v[72:73], 13, v[72:73]
	v_lshlrev_b64 v[74:75], 13, v[74:75]
	v_lshl_add_u64 v[46:47], v[24:25], 0, v[46:47]
	v_lshl_add_u64 v[44:45], v[24:25], 0, v[44:45]
	v_lshl_add_u64 v[50:51], v[24:25], 0, v[50:51]
	v_lshl_add_u64 v[48:49], v[24:25], 0, v[48:49]
	v_lshl_add_u64 v[54:55], v[24:25], 0, v[54:55]
	v_lshl_add_u64 v[52:53], v[24:25], 0, v[52:53]
	v_lshl_add_u64 v[58:59], v[24:25], 0, v[58:59]
	v_lshl_add_u64 v[56:57], v[24:25], 0, v[56:57]
	v_lshl_add_u64 v[62:63], v[24:25], 0, v[62:63]
	v_lshl_add_u64 v[60:61], v[24:25], 0, v[60:61]
	v_lshl_add_u64 v[66:67], v[24:25], 0, v[66:67]
	v_lshl_add_u64 v[64:65], v[24:25], 0, v[64:65]
	v_lshl_add_u64 v[70:71], v[24:25], 0, v[70:71]
	v_lshl_add_u64 v[68:69], v[24:25], 0, v[68:69]
	v_lshl_add_u64 v[74:75], v[24:25], 0, v[74:75]
	v_lshl_add_u64 v[72:73], v[24:25], 0, v[72:73]
	global_load_dword v188, v[46:47], off
	global_load_dword v189, v[44:45], off
	global_load_dword v190, v[50:51], off
	global_load_dword v191, v[48:49], off
	global_load_dword v192, v[54:55], off
	global_load_dword v193, v[52:53], off
	global_load_dword v194, v[58:59], off
	global_load_dword v195, v[56:57], off
	global_load_dword v196, v[62:63], off
	global_load_dword v197, v[60:61], off
	global_load_dword v198, v[66:67], off
	global_load_dword v199, v[64:65], off
	global_load_dword v200, v[70:71], off
	global_load_dword v201, v[68:69], off
	global_load_dword v202, v[74:75], off
	global_load_dword v203, v[72:73], off
	s_add_i32 s3, s3, 16
	s_add_i32 s2, s2, 16
	s_lshl_b32 s9, s3, 1
	s_lshl_b32 s10, s2, 1
	v_add_u32_e32 v46, s9, v26
	v_add_u32_e32 v44, s10, v17
	v_add_u32_e32 v48, s10, v19
	v_add_u32_e32 v50, s9, v28
	v_add_u32_e32 v52, s10, v27
	v_add_u32_e32 v54, s9, v30
	v_add_u32_e32 v56, s10, v29
	v_add_u32_e32 v58, s9, v32
	v_add_u32_e32 v60, s10, v31
	v_add_u32_e32 v62, s9, v34
	v_add_u32_e32 v64, s10, v33
	v_add_u32_e32 v66, s9, v36
	v_add_u32_e32 v68, s10, v35
	v_add_u32_e32 v70, s9, v38
	v_add_u32_e32 v72, s10, v37
	v_add_u32_e32 v74, s9, v40
	v_ashrrev_i32_e32 v47, 31, v46
	v_ashrrev_i32_e32 v45, 31, v44
	v_ashrrev_i32_e32 v51, 31, v50
	v_ashrrev_i32_e32 v49, 31, v48
	v_ashrrev_i32_e32 v55, 31, v54
	v_ashrrev_i32_e32 v53, 31, v52
	v_ashrrev_i32_e32 v59, 31, v58
	v_ashrrev_i32_e32 v57, 31, v56
	v_ashrrev_i32_e32 v63, 31, v62
	v_ashrrev_i32_e32 v61, 31, v60
	v_ashrrev_i32_e32 v67, 31, v66
	v_ashrrev_i32_e32 v65, 31, v64
	v_ashrrev_i32_e32 v71, 31, v70
	v_ashrrev_i32_e32 v69, 31, v68
	v_ashrrev_i32_e32 v75, 31, v74
	v_ashrrev_i32_e32 v73, 31, v72
	v_lshlrev_b64 v[46:47], 13, v[46:47]
	v_lshlrev_b64 v[44:45], 13, v[44:45]
	v_lshlrev_b64 v[48:49], 13, v[48:49]
	v_lshlrev_b64 v[50:51], 13, v[50:51]
	v_lshlrev_b64 v[52:53], 13, v[52:53]
	v_lshlrev_b64 v[54:55], 13, v[54:55]
	v_lshlrev_b64 v[56:57], 13, v[56:57]
	v_lshlrev_b64 v[58:59], 13, v[58:59]
	v_lshlrev_b64 v[60:61], 13, v[60:61]
	v_lshlrev_b64 v[62:63], 13, v[62:63]
	v_lshlrev_b64 v[64:65], 13, v[64:65]
	v_lshlrev_b64 v[66:67], 13, v[66:67]
	v_lshlrev_b64 v[68:69], 13, v[68:69]
	v_lshlrev_b64 v[70:71], 13, v[70:71]
	v_lshlrev_b64 v[72:73], 13, v[72:73]
	v_lshlrev_b64 v[74:75], 13, v[74:75]
	v_lshl_add_u64 v[46:47], v[24:25], 0, v[46:47]
	v_lshl_add_u64 v[44:45], v[24:25], 0, v[44:45]
	v_lshl_add_u64 v[50:51], v[24:25], 0, v[50:51]
	v_lshl_add_u64 v[48:49], v[24:25], 0, v[48:49]
	v_lshl_add_u64 v[54:55], v[24:25], 0, v[54:55]
	v_lshl_add_u64 v[52:53], v[24:25], 0, v[52:53]
	v_lshl_add_u64 v[58:59], v[24:25], 0, v[58:59]
	v_lshl_add_u64 v[56:57], v[24:25], 0, v[56:57]
	v_lshl_add_u64 v[62:63], v[24:25], 0, v[62:63]
	v_lshl_add_u64 v[60:61], v[24:25], 0, v[60:61]
	v_lshl_add_u64 v[66:67], v[24:25], 0, v[66:67]
	v_lshl_add_u64 v[64:65], v[24:25], 0, v[64:65]
	v_lshl_add_u64 v[70:71], v[24:25], 0, v[70:71]
	v_lshl_add_u64 v[68:69], v[24:25], 0, v[68:69]
	v_lshl_add_u64 v[74:75], v[24:25], 0, v[74:75]
	v_lshl_add_u64 v[72:73], v[24:25], 0, v[72:73]
	global_load_dword v204, v[46:47], off
	global_load_dword v205, v[44:45], off
	global_load_dword v206, v[50:51], off
	global_load_dword v207, v[48:49], off
	global_load_dword v208, v[54:55], off
	global_load_dword v209, v[52:53], off
	global_load_dword v210, v[58:59], off
	global_load_dword v211, v[56:57], off
	global_load_dword v212, v[62:63], off
	global_load_dword v213, v[60:61], off
	global_load_dword v214, v[66:67], off
	global_load_dword v215, v[64:65], off
	global_load_dword v216, v[70:71], off
	global_load_dword v217, v[68:69], off
	global_load_dword v218, v[74:75], off
	global_load_dword v219, v[72:73], off
	s_mov_b32 s9, s98
	s_mov_b32 s10, s99
	v_add_u32_e32 v44, s9, v2
	v_add_u32_e32 v46, s10, v1
	v_add_u32_e32 v50, s10, v3
	v_add_u32_e32 v48, s9, v4
	v_add_u32_e32 v54, s10, v5
	v_add_u32_e32 v52, s9, v6
	v_add_u32_e32 v58, s10, v7
	v_add_u32_e32 v56, s9, v8
	v_add_u32_e32 v62, s10, v9
	v_add_u32_e32 v60, s9, v10
	v_add_u32_e32 v66, s10, v11
	v_add_u32_e32 v64, s9, v12
	v_add_u32_e32 v70, s10, v13
	v_add_u32_e32 v68, s9, v14
	v_add_u32_e32 v74, s10, v15
	v_add_u32_e32 v72, s9, v16
	v_mad_u64_u32 v[44:45], s[16:17], v44, s95, v[18:19]
	v_mad_u64_u32 v[46:47], s[16:17], v46, s95, v[18:19]
	v_mad_u64_u32 v[48:49], s[16:17], v48, s95, v[18:19]
	v_mad_u64_u32 v[50:51], s[16:17], v50, s95, v[18:19]
	v_mad_u64_u32 v[52:53], s[16:17], v52, s95, v[18:19]
	v_mad_u64_u32 v[54:55], s[16:17], v54, s95, v[18:19]
	v_mad_u64_u32 v[56:57], s[16:17], v56, s95, v[18:19]
	v_mad_u64_u32 v[58:59], s[16:17], v58, s95, v[18:19]
	v_mad_u64_u32 v[60:61], s[16:17], v60, s95, v[18:19]
	v_mad_u64_u32 v[62:63], s[16:17], v62, s95, v[18:19]
	v_mad_u64_u32 v[64:65], s[16:17], v64, s95, v[18:19]
	v_mad_u64_u32 v[66:67], s[16:17], v66, s95, v[18:19]
	v_mad_u64_u32 v[68:69], s[16:17], v68, s95, v[18:19]
	v_mad_u64_u32 v[70:71], s[16:17], v70, s95, v[18:19]
	v_mad_u64_u32 v[72:73], s[16:17], v72, s95, v[18:19]
	v_mad_u64_u32 v[74:75], s[16:17], v74, s95, v[18:19]
	s_waitcnt vmcnt(31)
	ds_write_b32 v44, v188
	s_waitcnt vmcnt(30)
	ds_write_b32 v46, v189
	s_waitcnt vmcnt(29)
	ds_write_b32 v48, v190
	s_waitcnt vmcnt(28)
	ds_write_b32 v50, v191
	s_waitcnt vmcnt(27)
	ds_write_b32 v52, v192
	s_waitcnt vmcnt(26)
	ds_write_b32 v54, v193
	s_waitcnt vmcnt(25)
	ds_write_b32 v56, v194
	s_waitcnt vmcnt(24)
	ds_write_b32 v58, v195
	s_waitcnt vmcnt(23)
	ds_write_b32 v60, v196
	s_waitcnt vmcnt(22)
	ds_write_b32 v62, v197
	s_waitcnt vmcnt(21)
	ds_write_b32 v64, v198
	s_waitcnt vmcnt(20)
	ds_write_b32 v66, v199
	s_waitcnt vmcnt(19)
	ds_write_b32 v68, v200
	s_waitcnt vmcnt(18)
	ds_write_b32 v70, v201
	s_waitcnt vmcnt(17)
	ds_write_b32 v72, v202
	s_waitcnt vmcnt(16)
	ds_write_b32 v74, v203
	s_lshl_b32 s9, s3, 1
	s_lshl_b32 s10, s2, 1
	v_add_u32_e32 v44, s9, v2
	v_add_u32_e32 v46, s10, v1
	v_add_u32_e32 v50, s10, v3
	v_add_u32_e32 v48, s9, v4
	v_add_u32_e32 v54, s10, v5
	v_add_u32_e32 v52, s9, v6
	v_add_u32_e32 v58, s10, v7
	v_add_u32_e32 v56, s9, v8
	v_add_u32_e32 v62, s10, v9
	v_add_u32_e32 v60, s9, v10
	v_add_u32_e32 v66, s10, v11
	v_add_u32_e32 v64, s9, v12
	v_add_u32_e32 v70, s10, v13
	v_add_u32_e32 v68, s9, v14
	v_add_u32_e32 v74, s10, v15
	v_add_u32_e32 v72, s9, v16
	v_mad_u64_u32 v[44:45], s[16:17], v44, s95, v[18:19]
	v_mad_u64_u32 v[46:47], s[16:17], v46, s95, v[18:19]
	v_mad_u64_u32 v[48:49], s[16:17], v48, s95, v[18:19]
	v_mad_u64_u32 v[50:51], s[16:17], v50, s95, v[18:19]
	v_mad_u64_u32 v[52:53], s[16:17], v52, s95, v[18:19]
	v_mad_u64_u32 v[54:55], s[16:17], v54, s95, v[18:19]
	v_mad_u64_u32 v[56:57], s[16:17], v56, s95, v[18:19]
	v_mad_u64_u32 v[58:59], s[16:17], v58, s95, v[18:19]
	v_mad_u64_u32 v[60:61], s[16:17], v60, s95, v[18:19]
	v_mad_u64_u32 v[62:63], s[16:17], v62, s95, v[18:19]
	v_mad_u64_u32 v[64:65], s[16:17], v64, s95, v[18:19]
	v_mad_u64_u32 v[66:67], s[16:17], v66, s95, v[18:19]
	v_mad_u64_u32 v[68:69], s[16:17], v68, s95, v[18:19]
	v_mad_u64_u32 v[70:71], s[16:17], v70, s95, v[18:19]
	v_mad_u64_u32 v[72:73], s[16:17], v72, s95, v[18:19]
	v_mad_u64_u32 v[74:75], s[16:17], v74, s95, v[18:19]
	s_waitcnt vmcnt(15)
	ds_write_b32 v44, v204
	s_waitcnt vmcnt(14)
	ds_write_b32 v46, v205
	s_waitcnt vmcnt(13)
	ds_write_b32 v48, v206
	s_waitcnt vmcnt(12)
	ds_write_b32 v50, v207
	s_waitcnt vmcnt(11)
	ds_write_b32 v52, v208
	s_waitcnt vmcnt(10)
	ds_write_b32 v54, v209
	s_waitcnt vmcnt(9)
	ds_write_b32 v56, v210
	s_waitcnt vmcnt(8)
	ds_write_b32 v58, v211
	s_waitcnt vmcnt(7)
	ds_write_b32 v60, v212
	s_waitcnt vmcnt(6)
	ds_write_b32 v62, v213
	s_waitcnt vmcnt(5)
	ds_write_b32 v64, v214
	s_waitcnt vmcnt(4)
	ds_write_b32 v66, v215
	s_waitcnt vmcnt(3)
	ds_write_b32 v68, v216
	s_waitcnt vmcnt(2)
	ds_write_b32 v70, v217
	s_waitcnt vmcnt(1)
	ds_write_b32 v72, v218
	s_waitcnt vmcnt(0)
	ds_write_b32 v74, v219
	s_add_i32 s3, s3, 16
	s_add_i32 s2, s2, 16
	s_add_i32 s7, s7, -16
	s_add_i32 s7, s7, -16
	s_cmp_lg_u32 s7, 0
	s_waitcnt lgkmcnt(0)
	ds_read2_b32 v[28:29], v43 offset0:33 offset1:41
	ds_read2_b32 v[30:31], v43 offset1:8
	ds_read2_b32 v[32:33], v43 offset0:66 offset1:74
	ds_read2_b32 v[34:35], v43 offset0:99 offset1:107
	ds_read2_b32 v[36:37], v43 offset0:132 offset1:140
	ds_read2_b32 v[44:45], v43 offset0:165 offset1:173
	ds_read2_b32 v[46:47], v43 offset0:198 offset1:206
	ds_read2_b32 v[48:49], v43 offset0:231 offset1:239
	s_ashr_i32 s13, s12, 31
	v_lshl_add_u64 v[50:51], s[12:13], 1, v[22:23]
	v_add_u32_e32 v17, s8, v41
	s_movk_i32 s7, 0x2b00
	s_waitcnt lgkmcnt(6)
	v_cvt_pk_bf16_f32 v24, v30, v28
	s_waitcnt lgkmcnt(4)
	v_cvt_pk_bf16_f32 v25, v32, v34
	s_waitcnt lgkmcnt(2)
	v_cvt_pk_bf16_f32 v26, v36, v44
	s_waitcnt lgkmcnt(0)
	v_cvt_pk_bf16_f32 v27, v46, v48
	v_mad_i64_i32 v[52:53], s[2:3], v17, s7, v[50:51]
	global_store_dwordx4 v[52:53], v[24:27], off
	v_add_u32_e32 v19, 8, v17
	s_add_i32 s0, s0, s81
	v_cvt_pk_bf16_f32 v24, v31, v29
	v_cvt_pk_bf16_f32 v25, v33, v35
	v_cvt_pk_bf16_f32 v26, v37, v45
	v_cvt_pk_bf16_f32 v27, v47, v49
	ds_read2_b32 v[30:31], v43 offset0:49 offset1:57
	ds_read2_b32 v[32:33], v43 offset0:16 offset1:24
	ds_read2_b32 v[34:35], v43 offset0:82 offset1:90
	ds_read2_b32 v[36:37], v43 offset0:115 offset1:123
	ds_read2_b32 v[44:45], v43 offset0:148 offset1:156
	ds_read2_b32 v[46:47], v43 offset0:181 offset1:189
	ds_read2_b32 v[48:49], v43 offset0:214 offset1:222
	ds_read2_b32 v[52:53], v43 offset0:247 offset1:255
	v_mad_i64_i32 v[28:29], s[2:3], v19, s7, v[50:51]
	v_add_u32_e32 v19, 16, v17
	global_store_dwordx4 v[28:29], v[24:27], off
	v_mad_i64_i32 v[28:29], s[2:3], v19, s7, v[50:51]
	s_waitcnt lgkmcnt(6)
	v_cvt_pk_bf16_f32 v24, v32, v30
	s_waitcnt lgkmcnt(4)
	v_cvt_pk_bf16_f32 v25, v34, v36
	s_waitcnt lgkmcnt(2)
	v_cvt_pk_bf16_f32 v26, v44, v46
	s_waitcnt lgkmcnt(0)
	v_cvt_pk_bf16_f32 v27, v48, v52
	v_add_u32_e32 v17, 24, v17
	global_store_dwordx4 v[28:29], v[24:27], off
	v_mad_i64_i32 v[28:29], s[2:3], v17, s7, v[50:51]
	s_nop 0
	v_cvt_pk_bf16_f32 v24, v33, v31
	v_cvt_pk_bf16_f32 v25, v35, v37
	v_cvt_pk_bf16_f32 v26, v45, v47
	v_cvt_pk_bf16_f32 v27, v49, v53
	global_store_dwordx4 v[28:29], v[24:27], off
	s_waitcnt lgkmcnt(0)
	s_cmpk_lt_i32 s0, 0x1580
	s_cbranch_scc1 .LBB0_155

.LBB0_161:
	s_lshl_b32 s9, s3, 1
	s_lshl_b32 s10, s2, 1
	s_mov_b32 s98, s9
	s_mov_b32 s99, s10
	v_add_u32_e32 v46, s9, v26
	v_add_u32_e32 v44, s10, v17
	v_add_u32_e32 v48, s10, v19
	v_add_u32_e32 v50, s9, v28
	v_add_u32_e32 v52, s10, v27
	v_add_u32_e32 v54, s9, v30
	v_add_u32_e32 v56, s10, v29
	v_add_u32_e32 v58, s9, v32
	v_add_u32_e32 v60, s10, v31
	v_add_u32_e32 v62, s9, v34
	v_add_u32_e32 v64, s10, v33
	v_add_u32_e32 v66, s9, v36
	v_add_u32_e32 v68, s10, v35
	v_add_u32_e32 v70, s9, v38
	v_add_u32_e32 v72, s10, v37
	v_add_u32_e32 v74, s9, v40
	v_ashrrev_i32_e32 v47, 31, v46
	v_ashrrev_i32_e32 v45, 31, v44
	v_ashrrev_i32_e32 v51, 31, v50
	v_ashrrev_i32_e32 v49, 31, v48
	v_ashrrev_i32_e32 v55, 31, v54
	v_ashrrev_i32_e32 v53, 31, v52
	v_ashrrev_i32_e32 v59, 31, v58
	v_ashrrev_i32_e32 v57, 31, v56
	v_ashrrev_i32_e32 v63, 31, v62
	v_ashrrev_i32_e32 v61, 31, v60
	v_ashrrev_i32_e32 v67, 31, v66
	v_ashrrev_i32_e32 v65, 31, v64
	v_ashrrev_i32_e32 v71, 31, v70
	v_ashrrev_i32_e32 v69, 31, v68
	v_ashrrev_i32_e32 v75, 31, v74
	v_ashrrev_i32_e32 v73, 31, v72
	v_lshlrev_b64 v[46:47], 13, v[46:47]
	v_lshlrev_b64 v[44:45], 13, v[44:45]
	v_lshlrev_b64 v[48:49], 13, v[48:49]
	v_lshlrev_b64 v[50:51], 13, v[50:51]
	v_lshlrev_b64 v[52:53], 13, v[52:53]
	v_lshlrev_b64 v[54:55], 13, v[54:55]
	v_lshlrev_b64 v[56:57], 13, v[56:57]
	v_lshlrev_b64 v[58:59], 13, v[58:59]
	v_lshlrev_b64 v[60:61], 13, v[60:61]
	v_lshlrev_b64 v[62:63], 13, v[62:63]
	v_lshlrev_b64 v[64:65], 13, v[64:65]
	v_lshlrev_b64 v[66:67], 13, v[66:67]
	v_lshlrev_b64 v[68:69], 13, v[68:69]
	v_lshlrev_b64 v[70:71], 13, v[70:71]
	v_lshlrev_b64 v[72:73], 13, v[72:73]
	v_lshlrev_b64 v[74:75], 13, v[74:75]
	v_lshl_add_u64 v[46:47], v[24:25], 0, v[46:47]
	v_lshl_add_u64 v[44:45], v[24:25], 0, v[44:45]
	v_lshl_add_u64 v[50:51], v[24:25], 0, v[50:51]
	v_lshl_add_u64 v[48:49], v[24:25], 0, v[48:49]
	v_lshl_add_u64 v[54:55], v[24:25], 0, v[54:55]
	v_lshl_add_u64 v[52:53], v[24:25], 0, v[52:53]
	v_lshl_add_u64 v[58:59], v[24:25], 0, v[58:59]
	v_lshl_add_u64 v[56:57], v[24:25], 0, v[56:57]
	v_lshl_add_u64 v[62:63], v[24:25], 0, v[62:63]
	v_lshl_add_u64 v[60:61], v[24:25], 0, v[60:61]
	v_lshl_add_u64 v[66:67], v[24:25], 0, v[66:67]
	v_lshl_add_u64 v[64:65], v[24:25], 0, v[64:65]
	v_lshl_add_u64 v[70:71], v[24:25], 0, v[70:71]
	v_lshl_add_u64 v[68:69], v[24:25], 0, v[68:69]
	v_lshl_add_u64 v[74:75], v[24:25], 0, v[74:75]
	v_lshl_add_u64 v[72:73], v[24:25], 0, v[72:73]
	global_load_dword v188, v[46:47], off
	global_load_dword v189, v[44:45], off
	global_load_dword v190, v[50:51], off
	global_load_dword v191, v[48:49], off
	global_load_dword v192, v[54:55], off
	global_load_dword v193, v[52:53], off
	global_load_dword v194, v[58:59], off
	global_load_dword v195, v[56:57], off
	global_load_dword v196, v[62:63], off
	global_load_dword v197, v[60:61], off
	global_load_dword v198, v[66:67], off
	global_load_dword v199, v[64:65], off
	global_load_dword v200, v[70:71], off
	global_load_dword v201, v[68:69], off
	global_load_dword v202, v[74:75], off
	global_load_dword v203, v[72:73], off
	s_add_i32 s3, s3, 16
	s_add_i32 s2, s2, 16
	s_lshl_b32 s9, s3, 1
	s_lshl_b32 s10, s2, 1
	v_add_u32_e32 v46, s9, v26
	v_add_u32_e32 v44, s10, v17
	v_add_u32_e32 v48, s10, v19
	v_add_u32_e32 v50, s9, v28
	v_add_u32_e32 v52, s10, v27
	v_add_u32_e32 v54, s9, v30
	v_add_u32_e32 v56, s10, v29
	v_add_u32_e32 v58, s9, v32
	v_add_u32_e32 v60, s10, v31
	v_add_u32_e32 v62, s9, v34
	v_add_u32_e32 v64, s10, v33
	v_add_u32_e32 v66, s9, v36
	v_add_u32_e32 v68, s10, v35
	v_add_u32_e32 v70, s9, v38
	v_add_u32_e32 v72, s10, v37
	v_add_u32_e32 v74, s9, v40
	v_ashrrev_i32_e32 v47, 31, v46
	v_ashrrev_i32_e32 v45, 31, v44
	v_ashrrev_i32_e32 v51, 31, v50
	v_ashrrev_i32_e32 v49, 31, v48
	v_ashrrev_i32_e32 v55, 31, v54
	v_ashrrev_i32_e32 v53, 31, v52
	v_ashrrev_i32_e32 v59, 31, v58
	v_ashrrev_i32_e32 v57, 31, v56
	v_ashrrev_i32_e32 v63, 31, v62
	v_ashrrev_i32_e32 v61, 31, v60
	v_ashrrev_i32_e32 v67, 31, v66
	v_ashrrev_i32_e32 v65, 31, v64
	v_ashrrev_i32_e32 v71, 31, v70
	v_ashrrev_i32_e32 v69, 31, v68
	v_ashrrev_i32_e32 v75, 31, v74
	v_ashrrev_i32_e32 v73, 31, v72
	v_lshlrev_b64 v[46:47], 13, v[46:47]
	v_lshlrev_b64 v[44:45], 13, v[44:45]
	v_lshlrev_b64 v[48:49], 13, v[48:49]
	v_lshlrev_b64 v[50:51], 13, v[50:51]
	v_lshlrev_b64 v[52:53], 13, v[52:53]
	v_lshlrev_b64 v[54:55], 13, v[54:55]
	v_lshlrev_b64 v[56:57], 13, v[56:57]
	v_lshlrev_b64 v[58:59], 13, v[58:59]
	v_lshlrev_b64 v[60:61], 13, v[60:61]
	v_lshlrev_b64 v[62:63], 13, v[62:63]
	v_lshlrev_b64 v[64:65], 13, v[64:65]
	v_lshlrev_b64 v[66:67], 13, v[66:67]
	v_lshlrev_b64 v[68:69], 13, v[68:69]
	v_lshlrev_b64 v[70:71], 13, v[70:71]
	v_lshlrev_b64 v[72:73], 13, v[72:73]
	v_lshlrev_b64 v[74:75], 13, v[74:75]
	v_lshl_add_u64 v[46:47], v[24:25], 0, v[46:47]
	v_lshl_add_u64 v[44:45], v[24:25], 0, v[44:45]
	v_lshl_add_u64 v[50:51], v[24:25], 0, v[50:51]
	v_lshl_add_u64 v[48:49], v[24:25], 0, v[48:49]
	v_lshl_add_u64 v[54:55], v[24:25], 0, v[54:55]
	v_lshl_add_u64 v[52:53], v[24:25], 0, v[52:53]
	v_lshl_add_u64 v[58:59], v[24:25], 0, v[58:59]
	v_lshl_add_u64 v[56:57], v[24:25], 0, v[56:57]
	v_lshl_add_u64 v[62:63], v[24:25], 0, v[62:63]
	v_lshl_add_u64 v[60:61], v[24:25], 0, v[60:61]
	v_lshl_add_u64 v[66:67], v[24:25], 0, v[66:67]
	v_lshl_add_u64 v[64:65], v[24:25], 0, v[64:65]
	v_lshl_add_u64 v[70:71], v[24:25], 0, v[70:71]
	v_lshl_add_u64 v[68:69], v[24:25], 0, v[68:69]
	v_lshl_add_u64 v[74:75], v[24:25], 0, v[74:75]
	v_lshl_add_u64 v[72:73], v[24:25], 0, v[72:73]
	global_load_dword v204, v[46:47], off
	global_load_dword v205, v[44:45], off
	global_load_dword v206, v[50:51], off
	global_load_dword v207, v[48:49], off
	global_load_dword v208, v[54:55], off
	global_load_dword v209, v[52:53], off
	global_load_dword v210, v[58:59], off
	global_load_dword v211, v[56:57], off
	global_load_dword v212, v[62:63], off
	global_load_dword v213, v[60:61], off
	global_load_dword v214, v[66:67], off
	global_load_dword v215, v[64:65], off
	global_load_dword v216, v[70:71], off
	global_load_dword v217, v[68:69], off
	global_load_dword v218, v[74:75], off
	global_load_dword v219, v[72:73], off
	s_mov_b32 s9, s98
	s_mov_b32 s10, s99
	v_add_u32_e32 v44, s9, v2
	v_add_u32_e32 v46, s10, v1
	v_add_u32_e32 v50, s10, v3
	v_add_u32_e32 v48, s9, v4
	v_add_u32_e32 v54, s10, v5
	v_add_u32_e32 v52, s9, v6
	v_add_u32_e32 v58, s10, v7
	v_add_u32_e32 v56, s9, v8
	v_add_u32_e32 v62, s10, v9
	v_add_u32_e32 v60, s9, v10
	v_add_u32_e32 v66, s10, v11
	v_add_u32_e32 v64, s9, v12
	v_add_u32_e32 v70, s10, v13
	v_add_u32_e32 v68, s9, v14
	v_add_u32_e32 v74, s10, v15
	v_add_u32_e32 v72, s9, v16
	v_mad_u64_u32 v[44:45], s[16:17], v44, s95, v[18:19]
	v_mad_u64_u32 v[46:47], s[16:17], v46, s95, v[18:19]
	v_mad_u64_u32 v[48:49], s[16:17], v48, s95, v[18:19]
	v_mad_u64_u32 v[50:51], s[16:17], v50, s95, v[18:19]
	v_mad_u64_u32 v[52:53], s[16:17], v52, s95, v[18:19]
	v_mad_u64_u32 v[54:55], s[16:17], v54, s95, v[18:19]
	v_mad_u64_u32 v[56:57], s[16:17], v56, s95, v[18:19]
	v_mad_u64_u32 v[58:59], s[16:17], v58, s95, v[18:19]
	v_mad_u64_u32 v[60:61], s[16:17], v60, s95, v[18:19]
	v_mad_u64_u32 v[62:63], s[16:17], v62, s95, v[18:19]
	v_mad_u64_u32 v[64:65], s[16:17], v64, s95, v[18:19]
	v_mad_u64_u32 v[66:67], s[16:17], v66, s95, v[18:19]
	v_mad_u64_u32 v[68:69], s[16:17], v68, s95, v[18:19]
	v_mad_u64_u32 v[70:71], s[16:17], v70, s95, v[18:19]
	v_mad_u64_u32 v[72:73], s[16:17], v72, s95, v[18:19]
	v_mad_u64_u32 v[74:75], s[16:17], v74, s95, v[18:19]
	s_waitcnt vmcnt(31)
	ds_write_b32 v44, v188
	s_waitcnt vmcnt(30)
	ds_write_b32 v46, v189
	s_waitcnt vmcnt(29)
	ds_write_b32 v48, v190
	s_waitcnt vmcnt(28)
	ds_write_b32 v50, v191
	s_waitcnt vmcnt(27)
	ds_write_b32 v52, v192
	s_waitcnt vmcnt(26)
	ds_write_b32 v54, v193
	s_waitcnt vmcnt(25)
	ds_write_b32 v56, v194
	s_waitcnt vmcnt(24)
	ds_write_b32 v58, v195
	s_waitcnt vmcnt(23)
	ds_write_b32 v60, v196
	s_waitcnt vmcnt(22)
	ds_write_b32 v62, v197
	s_waitcnt vmcnt(21)
	ds_write_b32 v64, v198
	s_waitcnt vmcnt(20)
	ds_write_b32 v66, v199
	s_waitcnt vmcnt(19)
	ds_write_b32 v68, v200
	s_waitcnt vmcnt(18)
	ds_write_b32 v70, v201
	s_waitcnt vmcnt(17)
	ds_write_b32 v72, v202
	s_waitcnt vmcnt(16)
	ds_write_b32 v74, v203
	s_lshl_b32 s9, s3, 1
	s_lshl_b32 s10, s2, 1
	v_add_u32_e32 v44, s9, v2
	v_add_u32_e32 v46, s10, v1
	v_add_u32_e32 v50, s10, v3
	v_add_u32_e32 v48, s9, v4
	v_add_u32_e32 v54, s10, v5
	v_add_u32_e32 v52, s9, v6
	v_add_u32_e32 v58, s10, v7
	v_add_u32_e32 v56, s9, v8
	v_add_u32_e32 v62, s10, v9
	v_add_u32_e32 v60, s9, v10
	v_add_u32_e32 v66, s10, v11
	v_add_u32_e32 v64, s9, v12
	v_add_u32_e32 v70, s10, v13
	v_add_u32_e32 v68, s9, v14
	v_add_u32_e32 v74, s10, v15
	v_add_u32_e32 v72, s9, v16
	v_mad_u64_u32 v[44:45], s[16:17], v44, s95, v[18:19]
	v_mad_u64_u32 v[46:47], s[16:17], v46, s95, v[18:19]
	v_mad_u64_u32 v[48:49], s[16:17], v48, s95, v[18:19]
	v_mad_u64_u32 v[50:51], s[16:17], v50, s95, v[18:19]
	v_mad_u64_u32 v[52:53], s[16:17], v52, s95, v[18:19]
	v_mad_u64_u32 v[54:55], s[16:17], v54, s95, v[18:19]
	v_mad_u64_u32 v[56:57], s[16:17], v56, s95, v[18:19]
	v_mad_u64_u32 v[58:59], s[16:17], v58, s95, v[18:19]
	v_mad_u64_u32 v[60:61], s[16:17], v60, s95, v[18:19]
	v_mad_u64_u32 v[62:63], s[16:17], v62, s95, v[18:19]
	v_mad_u64_u32 v[64:65], s[16:17], v64, s95, v[18:19]
	v_mad_u64_u32 v[66:67], s[16:17], v66, s95, v[18:19]
	v_mad_u64_u32 v[68:69], s[16:17], v68, s95, v[18:19]
	v_mad_u64_u32 v[70:71], s[16:17], v70, s95, v[18:19]
	v_mad_u64_u32 v[72:73], s[16:17], v72, s95, v[18:19]
	v_mad_u64_u32 v[74:75], s[16:17], v74, s95, v[18:19]
	s_waitcnt vmcnt(15)
	ds_write_b32 v44, v204
	s_waitcnt vmcnt(14)
	ds_write_b32 v46, v205
	s_waitcnt vmcnt(13)
	ds_write_b32 v48, v206
	s_waitcnt vmcnt(12)
	ds_write_b32 v50, v207
	s_waitcnt vmcnt(11)
	ds_write_b32 v52, v208
	s_waitcnt vmcnt(10)
	ds_write_b32 v54, v209
	s_waitcnt vmcnt(9)
	ds_write_b32 v56, v210
	s_waitcnt vmcnt(8)
	ds_write_b32 v58, v211
	s_waitcnt vmcnt(7)
	ds_write_b32 v60, v212
	s_waitcnt vmcnt(6)
	ds_write_b32 v62, v213
	s_waitcnt vmcnt(5)
	ds_write_b32 v64, v214
	s_waitcnt vmcnt(4)
	ds_write_b32 v66, v215
	s_waitcnt vmcnt(3)
	ds_write_b32 v68, v216
	s_waitcnt vmcnt(2)
	ds_write_b32 v70, v217
	s_waitcnt vmcnt(1)
	ds_write_b32 v72, v218
	s_waitcnt vmcnt(0)
	ds_write_b32 v74, v219
	s_add_i32 s3, s3, 16
	s_add_i32 s2, s2, 16
	s_add_i32 s7, s7, -16
	s_add_i32 s7, s7, -16
	s_cmp_lg_u32 s7, 0
	s_waitcnt lgkmcnt(0)
	ds_read2_b32 v[28:29], v43 offset0:33 offset1:41
	ds_read2_b32 v[30:31], v43 offset1:8
	ds_read2_b32 v[32:33], v43 offset0:66 offset1:74
	ds_read2_b32 v[34:35], v43 offset0:99 offset1:107
	ds_read2_b32 v[36:37], v43 offset0:132 offset1:140
	ds_read2_b32 v[44:45], v43 offset0:165 offset1:173
	ds_read2_b32 v[46:47], v43 offset0:198 offset1:206
	ds_read2_b32 v[48:49], v43 offset0:231 offset1:239
	v_add_u32_e32 v52, s8, v41
	s_ashr_i32 s13, s12, 31
	v_ashrrev_i32_e32 v53, 31, v52
	v_lshl_add_u64 v[50:51], s[12:13], 1, v[22:23]
	v_lshlrev_b64 v[54:55], 9, v[52:53]
	s_waitcnt lgkmcnt(6)
	v_cvt_pk_bf16_f32 v24, v30, v28
	s_waitcnt lgkmcnt(4)
	v_cvt_pk_bf16_f32 v25, v32, v34
	s_waitcnt lgkmcnt(2)
	v_cvt_pk_bf16_f32 v26, v36, v44
	s_waitcnt lgkmcnt(0)
	v_cvt_pk_bf16_f32 v27, v46, v48
	v_lshl_add_u64 v[54:55], v[50:51], 0, v[54:55]
	v_add_u32_e32 v28, 8, v52
	global_store_dwordx4 v[54:55], v[24:27], off
	s_add_i32 s0, s0, s81
	s_cmpk_lt_i32 s0, 0x100
	v_cvt_pk_bf16_f32 v24, v31, v29
	v_ashrrev_i32_e32 v29, 31, v28
	v_cvt_pk_bf16_f32 v25, v33, v35
	v_cvt_pk_bf16_f32 v26, v37, v45
	v_cvt_pk_bf16_f32 v27, v47, v49
	v_lshlrev_b64 v[28:29], 9, v[28:29]
	ds_read2_b32 v[30:31], v43 offset0:49 offset1:57
	ds_read2_b32 v[32:33], v43 offset0:16 offset1:24
	ds_read2_b32 v[34:35], v43 offset0:82 offset1:90
	ds_read2_b32 v[36:37], v43 offset0:115 offset1:123
	ds_read2_b32 v[44:45], v43 offset0:148 offset1:156
	ds_read2_b32 v[46:47], v43 offset0:181 offset1:189
	ds_read2_b32 v[48:49], v43 offset0:214 offset1:222
	ds_read2_b32 v[54:55], v43 offset0:247 offset1:255
	v_lshl_add_u64 v[28:29], v[50:51], 0, v[28:29]
	global_store_dwordx4 v[28:29], v[24:27], off
	v_add_u32_e32 v28, 16, v52
	v_ashrrev_i32_e32 v29, 31, v28
	v_lshlrev_b64 v[28:29], 9, v[28:29]
	s_waitcnt lgkmcnt(6)
	v_cvt_pk_bf16_f32 v24, v32, v30
	s_waitcnt lgkmcnt(4)
	v_cvt_pk_bf16_f32 v25, v34, v36
	s_waitcnt lgkmcnt(2)
	v_cvt_pk_bf16_f32 v26, v44, v46
	s_waitcnt lgkmcnt(0)
	v_cvt_pk_bf16_f32 v27, v48, v54
	v_lshl_add_u64 v[28:29], v[50:51], 0, v[28:29]
	global_store_dwordx4 v[28:29], v[24:27], off
	v_add_u32_e32 v28, 24, v52
	v_ashrrev_i32_e32 v29, 31, v28
	v_lshlrev_b64 v[28:29], 9, v[28:29]
	v_cvt_pk_bf16_f32 v24, v33, v31
	v_cvt_pk_bf16_f32 v25, v35, v37
	v_cvt_pk_bf16_f32 v26, v45, v47
	v_cvt_pk_bf16_f32 v27, v49, v55
	v_lshl_add_u64 v[28:29], v[50:51], 0, v[28:29]
	global_store_dwordx4 v[28:29], v[24:27], off
	s_waitcnt lgkmcnt(0)
	s_cbranch_scc1 .LBB0_160

.LBB0_166:
	s_lshl_b32 s7, s2, 1
	s_lshl_b32 s9, s0, 1
	s_mov_b32 s98, s7
	s_mov_b32 s99, s9
	v_add_u32_e32 v44, s7, v26
	v_add_u32_e32 v42, s9, v17
	v_add_u32_e32 v46, s9, v19
	v_add_u32_e32 v48, s7, v28
	v_add_u32_e32 v50, s9, v27
	v_add_u32_e32 v52, s7, v30
	v_add_u32_e32 v54, s9, v29
	v_add_u32_e32 v56, s7, v32
	v_add_u32_e32 v58, s9, v31
	v_add_u32_e32 v60, s7, v34
	v_add_u32_e32 v62, s9, v33
	v_add_u32_e32 v64, s7, v36
	v_add_u32_e32 v66, s9, v35
	v_add_u32_e32 v68, s7, v38
	v_add_u32_e32 v70, s9, v37
	v_add_u32_e32 v72, s7, v40
	v_ashrrev_i32_e32 v45, 31, v44
	v_ashrrev_i32_e32 v43, 31, v42
	v_ashrrev_i32_e32 v49, 31, v48
	v_ashrrev_i32_e32 v47, 31, v46
	v_ashrrev_i32_e32 v53, 31, v52
	v_ashrrev_i32_e32 v51, 31, v50
	v_ashrrev_i32_e32 v57, 31, v56
	v_ashrrev_i32_e32 v55, 31, v54
	v_ashrrev_i32_e32 v61, 31, v60
	v_ashrrev_i32_e32 v59, 31, v58
	v_ashrrev_i32_e32 v65, 31, v64
	v_ashrrev_i32_e32 v63, 31, v62
	v_ashrrev_i32_e32 v69, 31, v68
	v_ashrrev_i32_e32 v67, 31, v66
	v_ashrrev_i32_e32 v73, 31, v72
	v_ashrrev_i32_e32 v71, 31, v70
	v_lshlrev_b64 v[44:45], 13, v[44:45]
	v_lshlrev_b64 v[42:43], 13, v[42:43]
	v_lshlrev_b64 v[46:47], 13, v[46:47]
	v_lshlrev_b64 v[48:49], 13, v[48:49]
	v_lshlrev_b64 v[50:51], 13, v[50:51]
	v_lshlrev_b64 v[52:53], 13, v[52:53]
	v_lshlrev_b64 v[54:55], 13, v[54:55]
	v_lshlrev_b64 v[56:57], 13, v[56:57]
	v_lshlrev_b64 v[58:59], 13, v[58:59]
	v_lshlrev_b64 v[60:61], 13, v[60:61]
	v_lshlrev_b64 v[62:63], 13, v[62:63]
	v_lshlrev_b64 v[64:65], 13, v[64:65]
	v_lshlrev_b64 v[66:67], 13, v[66:67]
	v_lshlrev_b64 v[68:69], 13, v[68:69]
	v_lshlrev_b64 v[70:71], 13, v[70:71]
	v_lshlrev_b64 v[72:73], 13, v[72:73]
	v_lshl_add_u64 v[44:45], v[24:25], 0, v[44:45]
	v_lshl_add_u64 v[42:43], v[24:25], 0, v[42:43]
	v_lshl_add_u64 v[48:49], v[24:25], 0, v[48:49]
	v_lshl_add_u64 v[46:47], v[24:25], 0, v[46:47]
	v_lshl_add_u64 v[52:53], v[24:25], 0, v[52:53]
	v_lshl_add_u64 v[50:51], v[24:25], 0, v[50:51]
	v_lshl_add_u64 v[56:57], v[24:25], 0, v[56:57]
	v_lshl_add_u64 v[54:55], v[24:25], 0, v[54:55]
	v_lshl_add_u64 v[60:61], v[24:25], 0, v[60:61]
	v_lshl_add_u64 v[58:59], v[24:25], 0, v[58:59]
	v_lshl_add_u64 v[64:65], v[24:25], 0, v[64:65]
	v_lshl_add_u64 v[62:63], v[24:25], 0, v[62:63]
	v_lshl_add_u64 v[68:69], v[24:25], 0, v[68:69]
	v_lshl_add_u64 v[66:67], v[24:25], 0, v[66:67]
	v_lshl_add_u64 v[72:73], v[24:25], 0, v[72:73]
	v_lshl_add_u64 v[70:71], v[24:25], 0, v[70:71]
	global_load_dword v188, v[44:45], off
	global_load_dword v189, v[42:43], off
	global_load_dword v190, v[48:49], off
	global_load_dword v191, v[46:47], off
	global_load_dword v192, v[52:53], off
	global_load_dword v193, v[50:51], off
	global_load_dword v194, v[56:57], off
	global_load_dword v195, v[54:55], off
	global_load_dword v196, v[60:61], off
	global_load_dword v197, v[58:59], off
	global_load_dword v198, v[64:65], off
	global_load_dword v199, v[62:63], off
	global_load_dword v200, v[68:69], off
	global_load_dword v201, v[66:67], off
	global_load_dword v202, v[72:73], off
	global_load_dword v203, v[70:71], off
	s_add_i32 s2, s2, 16
	s_add_i32 s0, s0, 16
	s_lshl_b32 s7, s2, 1
	s_lshl_b32 s9, s0, 1
	v_add_u32_e32 v44, s7, v26
	v_add_u32_e32 v42, s9, v17
	v_add_u32_e32 v46, s9, v19
	v_add_u32_e32 v48, s7, v28
	v_add_u32_e32 v50, s9, v27
	v_add_u32_e32 v52, s7, v30
	v_add_u32_e32 v54, s9, v29
	v_add_u32_e32 v56, s7, v32
	v_add_u32_e32 v58, s9, v31
	v_add_u32_e32 v60, s7, v34
	v_add_u32_e32 v62, s9, v33
	v_add_u32_e32 v64, s7, v36
	v_add_u32_e32 v66, s9, v35
	v_add_u32_e32 v68, s7, v38
	v_add_u32_e32 v70, s9, v37
	v_add_u32_e32 v72, s7, v40
	v_ashrrev_i32_e32 v45, 31, v44
	v_ashrrev_i32_e32 v43, 31, v42
	v_ashrrev_i32_e32 v49, 31, v48
	v_ashrrev_i32_e32 v47, 31, v46
	v_ashrrev_i32_e32 v53, 31, v52
	v_ashrrev_i32_e32 v51, 31, v50
	v_ashrrev_i32_e32 v57, 31, v56
	v_ashrrev_i32_e32 v55, 31, v54
	v_ashrrev_i32_e32 v61, 31, v60
	v_ashrrev_i32_e32 v59, 31, v58
	v_ashrrev_i32_e32 v65, 31, v64
	v_ashrrev_i32_e32 v63, 31, v62
	v_ashrrev_i32_e32 v69, 31, v68
	v_ashrrev_i32_e32 v67, 31, v66
	v_ashrrev_i32_e32 v73, 31, v72
	v_ashrrev_i32_e32 v71, 31, v70
	v_lshlrev_b64 v[44:45], 13, v[44:45]
	v_lshlrev_b64 v[42:43], 13, v[42:43]
	v_lshlrev_b64 v[46:47], 13, v[46:47]
	v_lshlrev_b64 v[48:49], 13, v[48:49]
	v_lshlrev_b64 v[50:51], 13, v[50:51]
	v_lshlrev_b64 v[52:53], 13, v[52:53]
	v_lshlrev_b64 v[54:55], 13, v[54:55]
	v_lshlrev_b64 v[56:57], 13, v[56:57]
	v_lshlrev_b64 v[58:59], 13, v[58:59]
	v_lshlrev_b64 v[60:61], 13, v[60:61]
	v_lshlrev_b64 v[62:63], 13, v[62:63]
	v_lshlrev_b64 v[64:65], 13, v[64:65]
	v_lshlrev_b64 v[66:67], 13, v[66:67]
	v_lshlrev_b64 v[68:69], 13, v[68:69]
	v_lshlrev_b64 v[70:71], 13, v[70:71]
	v_lshlrev_b64 v[72:73], 13, v[72:73]
	v_lshl_add_u64 v[44:45], v[24:25], 0, v[44:45]
	v_lshl_add_u64 v[42:43], v[24:25], 0, v[42:43]
	v_lshl_add_u64 v[48:49], v[24:25], 0, v[48:49]
	v_lshl_add_u64 v[46:47], v[24:25], 0, v[46:47]
	v_lshl_add_u64 v[52:53], v[24:25], 0, v[52:53]
	v_lshl_add_u64 v[50:51], v[24:25], 0, v[50:51]
	v_lshl_add_u64 v[56:57], v[24:25], 0, v[56:57]
	v_lshl_add_u64 v[54:55], v[24:25], 0, v[54:55]
	v_lshl_add_u64 v[60:61], v[24:25], 0, v[60:61]
	v_lshl_add_u64 v[58:59], v[24:25], 0, v[58:59]
	v_lshl_add_u64 v[64:65], v[24:25], 0, v[64:65]
	v_lshl_add_u64 v[62:63], v[24:25], 0, v[62:63]
	v_lshl_add_u64 v[68:69], v[24:25], 0, v[68:69]
	v_lshl_add_u64 v[66:67], v[24:25], 0, v[66:67]
	v_lshl_add_u64 v[72:73], v[24:25], 0, v[72:73]
	v_lshl_add_u64 v[70:71], v[24:25], 0, v[70:71]
	global_load_dword v204, v[44:45], off
	global_load_dword v205, v[42:43], off
	global_load_dword v206, v[48:49], off
	global_load_dword v207, v[46:47], off
	global_load_dword v208, v[52:53], off
	global_load_dword v209, v[50:51], off
	global_load_dword v210, v[56:57], off
	global_load_dword v211, v[54:55], off
	global_load_dword v212, v[60:61], off
	global_load_dword v213, v[58:59], off
	global_load_dword v214, v[64:65], off
	global_load_dword v215, v[62:63], off
	global_load_dword v216, v[68:69], off
	global_load_dword v217, v[66:67], off
	global_load_dword v218, v[72:73], off
	global_load_dword v219, v[70:71], off
	s_mov_b32 s7, s98
	s_mov_b32 s9, s99
	v_add_u32_e32 v42, s7, v2
	v_add_u32_e32 v44, s9, v1
	v_add_u32_e32 v48, s9, v3
	v_add_u32_e32 v46, s7, v4
	v_add_u32_e32 v52, s9, v5
	v_add_u32_e32 v50, s7, v6
	v_add_u32_e32 v56, s9, v7
	v_add_u32_e32 v54, s7, v8
	v_add_u32_e32 v60, s9, v9
	v_add_u32_e32 v58, s7, v10
	v_add_u32_e32 v64, s9, v11
	v_add_u32_e32 v62, s7, v12
	v_add_u32_e32 v68, s9, v13
	v_add_u32_e32 v66, s7, v14
	v_add_u32_e32 v72, s9, v15
	v_add_u32_e32 v70, s7, v16
	v_mad_u64_u32 v[42:43], s[16:17], v42, s95, v[18:19]
	v_mad_u64_u32 v[44:45], s[16:17], v44, s95, v[18:19]
	v_mad_u64_u32 v[46:47], s[16:17], v46, s95, v[18:19]
	v_mad_u64_u32 v[48:49], s[16:17], v48, s95, v[18:19]
	v_mad_u64_u32 v[50:51], s[16:17], v50, s95, v[18:19]
	v_mad_u64_u32 v[52:53], s[16:17], v52, s95, v[18:19]
	v_mad_u64_u32 v[54:55], s[16:17], v54, s95, v[18:19]
	v_mad_u64_u32 v[56:57], s[16:17], v56, s95, v[18:19]
	v_mad_u64_u32 v[58:59], s[16:17], v58, s95, v[18:19]
	v_mad_u64_u32 v[60:61], s[16:17], v60, s95, v[18:19]
	v_mad_u64_u32 v[62:63], s[16:17], v62, s95, v[18:19]
	v_mad_u64_u32 v[64:65], s[16:17], v64, s95, v[18:19]
	v_mad_u64_u32 v[66:67], s[16:17], v66, s95, v[18:19]
	v_mad_u64_u32 v[68:69], s[16:17], v68, s95, v[18:19]
	v_mad_u64_u32 v[70:71], s[16:17], v70, s95, v[18:19]
	v_mad_u64_u32 v[72:73], s[16:17], v72, s95, v[18:19]
	s_waitcnt vmcnt(31)
	ds_write_b32 v42, v188
	s_waitcnt vmcnt(30)
	ds_write_b32 v44, v189
	s_waitcnt vmcnt(29)
	ds_write_b32 v46, v190
	s_waitcnt vmcnt(28)
	ds_write_b32 v48, v191
	s_waitcnt vmcnt(27)
	ds_write_b32 v50, v192
	s_waitcnt vmcnt(26)
	ds_write_b32 v52, v193
	s_waitcnt vmcnt(25)
	ds_write_b32 v54, v194
	s_waitcnt vmcnt(24)
	ds_write_b32 v56, v195
	s_waitcnt vmcnt(23)
	ds_write_b32 v58, v196
	s_waitcnt vmcnt(22)
	ds_write_b32 v60, v197
	s_waitcnt vmcnt(21)
	ds_write_b32 v62, v198
	s_waitcnt vmcnt(20)
	ds_write_b32 v64, v199
	s_waitcnt vmcnt(19)
	ds_write_b32 v66, v200
	s_waitcnt vmcnt(18)
	ds_write_b32 v68, v201
	s_waitcnt vmcnt(17)
	ds_write_b32 v70, v202
	s_waitcnt vmcnt(16)
	ds_write_b32 v72, v203
	s_lshl_b32 s7, s2, 1
	s_lshl_b32 s9, s0, 1
	v_add_u32_e32 v42, s7, v2
	v_add_u32_e32 v44, s9, v1
	v_add_u32_e32 v48, s9, v3
	v_add_u32_e32 v46, s7, v4
	v_add_u32_e32 v52, s9, v5
	v_add_u32_e32 v50, s7, v6
	v_add_u32_e32 v56, s9, v7
	v_add_u32_e32 v54, s7, v8
	v_add_u32_e32 v60, s9, v9
	v_add_u32_e32 v58, s7, v10
	v_add_u32_e32 v64, s9, v11
	v_add_u32_e32 v62, s7, v12
	v_add_u32_e32 v68, s9, v13
	v_add_u32_e32 v66, s7, v14
	v_add_u32_e32 v72, s9, v15
	v_add_u32_e32 v70, s7, v16
	v_mad_u64_u32 v[42:43], s[16:17], v42, s95, v[18:19]
	v_mad_u64_u32 v[44:45], s[16:17], v44, s95, v[18:19]
	v_mad_u64_u32 v[46:47], s[16:17], v46, s95, v[18:19]
	v_mad_u64_u32 v[48:49], s[16:17], v48, s95, v[18:19]
	v_mad_u64_u32 v[50:51], s[16:17], v50, s95, v[18:19]
	v_mad_u64_u32 v[52:53], s[16:17], v52, s95, v[18:19]
	v_mad_u64_u32 v[54:55], s[16:17], v54, s95, v[18:19]
	v_mad_u64_u32 v[56:57], s[16:17], v56, s95, v[18:19]
	v_mad_u64_u32 v[58:59], s[16:17], v58, s95, v[18:19]
	v_mad_u64_u32 v[60:61], s[16:17], v60, s95, v[18:19]
	v_mad_u64_u32 v[62:63], s[16:17], v62, s95, v[18:19]
	v_mad_u64_u32 v[64:65], s[16:17], v64, s95, v[18:19]
	v_mad_u64_u32 v[66:67], s[16:17], v66, s95, v[18:19]
	v_mad_u64_u32 v[68:69], s[16:17], v68, s95, v[18:19]
	v_mad_u64_u32 v[70:71], s[16:17], v70, s95, v[18:19]
	v_mad_u64_u32 v[72:73], s[16:17], v72, s95, v[18:19]
	s_waitcnt vmcnt(15)
	ds_write_b32 v42, v204
	s_waitcnt vmcnt(14)
	ds_write_b32 v44, v205
	s_waitcnt vmcnt(13)
	ds_write_b32 v46, v206
	s_waitcnt vmcnt(12)
	ds_write_b32 v48, v207
	s_waitcnt vmcnt(11)
	ds_write_b32 v50, v208
	s_waitcnt vmcnt(10)
	ds_write_b32 v52, v209
	s_waitcnt vmcnt(9)
	ds_write_b32 v54, v210
	s_waitcnt vmcnt(8)
	ds_write_b32 v56, v211
	s_waitcnt vmcnt(7)
	ds_write_b32 v58, v212
	s_waitcnt vmcnt(6)
	ds_write_b32 v60, v213
	s_waitcnt vmcnt(5)
	ds_write_b32 v62, v214
	s_waitcnt vmcnt(4)
	ds_write_b32 v64, v215
	s_waitcnt vmcnt(3)
	ds_write_b32 v66, v216
	s_waitcnt vmcnt(2)
	ds_write_b32 v68, v217
	s_waitcnt vmcnt(1)
	ds_write_b32 v70, v218
	s_waitcnt vmcnt(0)
	ds_write_b32 v72, v219
	s_add_i32 s2, s2, 16
	s_add_i32 s0, s0, 16
	s_add_i32 s3, s3, -16
	s_add_i32 s3, s3, -16
	s_cmp_lg_u32 s3, 0
	s_waitcnt lgkmcnt(0)
	ds_read2_b32 v[28:29], v39 offset0:33 offset1:41
	ds_read2_b32 v[30:31], v39 offset1:8
	ds_read2_b32 v[32:33], v39 offset0:66 offset1:74
	ds_read2_b32 v[34:35], v39 offset0:99 offset1:107
	ds_read2_b32 v[36:37], v39 offset0:132 offset1:140
	ds_read2_b32 v[42:43], v39 offset0:165 offset1:173
	ds_read2_b32 v[44:45], v39 offset0:198 offset1:206
	ds_read2_b32 v[46:47], v39 offset0:231 offset1:239
	v_add_u32_e32 v50, s8, v41
	s_ashr_i32 s13, s12, 31
	v_ashrrev_i32_e32 v51, 31, v50
	v_lshl_add_u64 v[48:49], s[12:13], 1, v[22:23]
	v_lshlrev_b64 v[52:53], 12, v[50:51]
	s_waitcnt lgkmcnt(6)
	v_cvt_pk_bf16_f32 v24, v30, v28
	s_waitcnt lgkmcnt(4)
	v_cvt_pk_bf16_f32 v25, v32, v34
	s_waitcnt lgkmcnt(2)
	v_cvt_pk_bf16_f32 v26, v36, v42
	s_waitcnt lgkmcnt(0)
	v_cvt_pk_bf16_f32 v27, v44, v46
	v_lshl_add_u64 v[52:53], v[48:49], 0, v[52:53]
	v_add_u32_e32 v28, 8, v50
	global_store_dwordx4 v[52:53], v[24:27], off
	s_add_i32 s53, s53, s81
	s_cmpk_lt_i32 s53, 0x800
	v_cvt_pk_bf16_f32 v24, v31, v29
	v_ashrrev_i32_e32 v29, 31, v28
	v_cvt_pk_bf16_f32 v25, v33, v35
	v_cvt_pk_bf16_f32 v26, v37, v43
	v_cvt_pk_bf16_f32 v27, v45, v47
	v_lshlrev_b64 v[28:29], 12, v[28:29]
	ds_read2_b32 v[30:31], v39 offset0:49 offset1:57
	ds_read2_b32 v[32:33], v39 offset0:16 offset1:24
	ds_read2_b32 v[34:35], v39 offset0:82 offset1:90
	ds_read2_b32 v[36:37], v39 offset0:115 offset1:123
	ds_read2_b32 v[42:43], v39 offset0:148 offset1:156
	ds_read2_b32 v[44:45], v39 offset0:181 offset1:189
	ds_read2_b32 v[46:47], v39 offset0:214 offset1:222
	ds_read2_b32 v[52:53], v39 offset0:247 offset1:255
	v_lshl_add_u64 v[28:29], v[48:49], 0, v[28:29]
	global_store_dwordx4 v[28:29], v[24:27], off
	v_add_u32_e32 v28, 16, v50
	v_ashrrev_i32_e32 v29, 31, v28
	v_lshlrev_b64 v[28:29], 12, v[28:29]
	s_waitcnt lgkmcnt(6)
	v_cvt_pk_bf16_f32 v24, v32, v30
	s_waitcnt lgkmcnt(4)
	v_cvt_pk_bf16_f32 v25, v34, v36
	s_waitcnt lgkmcnt(2)
	v_cvt_pk_bf16_f32 v26, v42, v44
	s_waitcnt lgkmcnt(0)
	v_cvt_pk_bf16_f32 v27, v46, v52
	v_lshl_add_u64 v[28:29], v[48:49], 0, v[28:29]
	global_store_dwordx4 v[28:29], v[24:27], off
	v_add_u32_e32 v28, 24, v50
	v_ashrrev_i32_e32 v29, 31, v28
	v_lshlrev_b64 v[28:29], 12, v[28:29]
	v_cvt_pk_bf16_f32 v24, v33, v31
	v_cvt_pk_bf16_f32 v25, v35, v37
	v_cvt_pk_bf16_f32 v26, v43, v45
	v_cvt_pk_bf16_f32 v27, v47, v53
	v_lshl_add_u64 v[28:29], v[48:49], 0, v[28:29]
	global_store_dwordx4 v[28:29], v[24:27], off
	s_waitcnt lgkmcnt(0)
	s_cbranch_scc1 .LBB0_165
